# code placement: one s_nop in the preceding load segment where needed so that every 32-MFMA block of the K-loops starts on an 8-byte boundary
# baseline (speedup 1.0000x reference)
; #define PG8_STAGE(bufoff, gbase, voff) do { _Pragma("unroll") for (int _i = 0; _i < 2; ++_i) \
;         __builtin_amdgcn_global_load_lds((const unsigned*)((const char*)(gbase) + (voff)[_i]), (PG8_LAS unsigned*)(lds + (bufoff) + ldsw + _i * 8192), 16, 0, 0); } while (0)
; #define PG8_LDA(dst, b, h) do { _Pragma("unroll") for (int m = 0; m < 4; ++m) _Pragma("unroll") for (int k = 0; k < 2; ++k) dst[m][k] = *(const PG8_LAS bf16x8*)(lds + PG8_SA(b, h) + aoff + m * 2048 + k * 1024); } while (0)
; #define PG8_LDB(dst, b, h) do { _Pragma("unroll") for (int n = 0; n < 2; ++n) _Pragma("unroll") for (int k = 0; k < 2; ++k) dst[n][k] = *(const PG8_LAS bf16x8*)(lds + PG8_SB(b, h) + boff + n * 2048 + k * 1024); } while (0)
; #define PG8_WAIT_V(n) asm volatile("s_waitcnt vmcnt(" #n ")" ::: "memory")
; #define PG8_WAIT_L(n) asm volatile("s_waitcnt lgkmcnt(" #n ")" ::: "memory")
; #define PG8_BAR __builtin_amdgcn_s_barrier()
; #define PG8_SCHED __builtin_amdgcn_sched_barrier(0)
; template <class Epi, class Sched, bool ALIGN_EPI = false, bool SP2 = false>
; __device__ __forceinline__ void gemm_phase(PG8_LAS unsigned char* lds, const Gemm g, const Sched& S, const Epi& E) {
;     ...
;         const bool has_next = S.next(ui + 1, nxt);
;         const char* nA = has_next ? (const char*)g.A + (size_t)nxt.pm * tstep : cA; const char* nB = has_next ? (const char*)g.Bt + (size_t)nxt.pn * tstep : cB;
;         for (int t = 0; t < nt; t += 2) {
;             const bool last = (t == nt - 2);
;             const char* a1 = cA + (size_t)(t + 1) * kstep;
;             const char* a2 = last ? nA : cA + (size_t)(t + 2) * kstep; const char* b2 = last ? nB : cB + (size_t)(t + 2) * kstep;
;             const char* a3 = a2 + kstep; const char* b3 = b2 + kstep;
;             if (last && has_next) S.a_ready(nxt);
;             if constexpr (SP2) {
;             PG8_LDB(B0, 0, 0); PG8_LDB(B1, 0, 1); PG8_SCHED; PG8_LDA(At, 0, 0); PG8_STAGE(PG8_SA(1, 1), a1 + hstep, voffA);
;             PG8_WAIT_V(8); PG8_WAIT_L(0); PG8_BAR; PG8_MMA(0, 0, At, B0); PG8_MMA(0, 1, At, B1); PG8_BAR; PG8_SCHED;
;             PG8_LDA(At, 0, 1); PG8_STAGE(PG8_SB(0, 0), b2, voffB); PG8_STAGE(PG8_SB(0, 1), b2 + hstepB, voffB); PG8_STAGE(PG8_SA(0, 0), a2, voffA);
;             PG8_WAIT_V(8); PG8_WAIT_L(0); PG8_BAR; PG8_MMA(1, 0, At, B0); PG8_MMA(1, 1, At, B1); PG8_BAR; PG8_SCHED;
.LBB0_169:
	s_add_u32 s93, s46, 0x100
	s_addc_u32 s94, s47, 0
	s_ashr_i32 s69, s68, 31
	s_lshl_b64 s[4:5], s[68:69], 20
	s_add_u32 s76, s52, s4
	s_addc_u32 s77, s53, s5
	s_and_b64 s[4:5], s[38:39], exec
	s_cselect_b32 s4, s77, s71
	s_cselect_b32 s5, s76, s70
	s_ashr_i32 s63, s62, 31
	s_lshl_b64 s[6:7], s[62:63], 20
	v_readlane_b32 s8, v249, 19
	v_readlane_b32 s9, v249, 20
	s_add_u32 s72, s8, s6
	s_addc_u32 s73, s9, s7
	s_and_b64 s[6:7], s[38:39], exec
	s_cselect_b32 s6, s73, s47
	s_cselect_b32 s7, s72, s46
	s_add_u32 s8, s70, 0x80080
	s_addc_u32 s9, s71, 0
	v_lshl_add_u64 v[144:145], s[8:9], 0, v[140:141]
	v_lshl_add_u64 v[146:147], s[8:9], 0, v[142:143]
	s_mov_b32 s8, -2
	s_mov_b64 s[46:47], 0
	v_add_u32_e32 v186, 0x10000, v139
	v_add_u32_e32 v187, 0x14000, v139
	v_add_u32_e32 v198, 0x18000, v139
	v_add_u32_e32 v199, 0x1c000, v139
	s_add_u32 s9, s70, s46
	s_addc_u32 s10, s71, s47
	s_add_u32 s9, s9, 0x100
	s_addc_u32 s10, s10, 0
	s_add_u32 s100, s9, 0x7ff80
	s_addc_u32 s101, s10, 0
	s_add_u32 s11, s93, s46
	s_addc_u32 s12, s94, s47
	s_add_i32 s13, 0, 0x10000
	s_cmpk_eq_i32 s46, 0xf00
	s_cselect_b32 s85, s4, s10
	s_cselect_b32 s84, s5, s9
	s_cselect_b32 s81, s6, s12
	s_cselect_b32 s80, s7, s11
	s_add_i32 s9, 0, 0x14000
	ds_read_b128 v[148:151], v186
	ds_read_b128 v[152:155], v186 offset:1024
	ds_read_b128 v[156:159], v186 offset:2048
	ds_read_b128 v[160:163], v186 offset:3072
	ds_read_b128 v[166:169], v187
	ds_read_b128 v[170:173], v187 offset:1024
	ds_read_b128 v[174:177], v187 offset:2048
	ds_read_b128 v[178:181], v187 offset:3072
	s_add_i32 m0, s1, 0xc000
	ds_read_b128 v[182:185], v165
	ds_read_b128 v[206:209], v165 offset:1024
	ds_read_b128 v[210:213], v165 offset:2048
	ds_read_b128 v[214:217], v165 offset:3072
	ds_read_b128 v[218:221], v165 offset:4096
	ds_read_b128 v[236:239], v165 offset:5120
	ds_read_b128 v[240:243], v165 offset:6144
	ds_read_b128 v[244:247], v165 offset:7168
	global_load_lds_dwordx4 v140, s[100:101]
	s_add_i32 m0, s1, 0xe000
	s_nop 0
	global_load_lds_dwordx4 v142, s[100:101]
	s_waitcnt vmcnt(8)
	s_waitcnt lgkmcnt(0)
	s_barrier
	v_mfma_f32_16x16x32_bf16 v[126:129], v[148:151], v[182:185], 0
	v_mfma_f32_16x16x32_bf16 v[122:125], v[156:159], v[182:185], 0
	v_mfma_f32_16x16x32_bf16 v[118:121], v[148:151], v[210:213], 0
	v_mfma_f32_16x16x32_bf16 v[114:117], v[156:159], v[210:213], 0
	v_mfma_f32_16x16x32_bf16 v[110:113], v[148:151], v[218:221], 0
	v_mfma_f32_16x16x32_bf16 v[106:109], v[156:159], v[218:221], 0
	v_mfma_f32_16x16x32_bf16 v[102:105], v[148:151], v[240:243], 0
	v_mfma_f32_16x16x32_bf16 v[98:101], v[156:159], v[240:243], 0
	v_mfma_f32_16x16x32_bf16 v[126:129], v[152:155], v[206:209], v[126:129]
	v_mfma_f32_16x16x32_bf16 v[122:125], v[160:163], v[206:209], v[122:125]
	v_mfma_f32_16x16x32_bf16 v[118:121], v[152:155], v[214:217], v[118:121]
	v_mfma_f32_16x16x32_bf16 v[114:117], v[160:163], v[214:217], v[114:117]
	v_mfma_f32_16x16x32_bf16 v[110:113], v[152:155], v[236:239], v[110:113]
	v_mfma_f32_16x16x32_bf16 v[106:109], v[160:163], v[236:239], v[106:109]
	v_mfma_f32_16x16x32_bf16 v[102:105], v[152:155], v[244:247], v[102:105]
	v_mfma_f32_16x16x32_bf16 v[98:101], v[160:163], v[244:247], v[98:101]
	v_mfma_f32_16x16x32_bf16 v[94:97], v[166:169], v[182:185], 0
	v_mfma_f32_16x16x32_bf16 v[90:93], v[174:177], v[182:185], 0
	v_mfma_f32_16x16x32_bf16 v[86:89], v[166:169], v[210:213], 0
	v_mfma_f32_16x16x32_bf16 v[82:85], v[174:177], v[210:213], 0
	v_mfma_f32_16x16x32_bf16 v[78:81], v[166:169], v[218:221], 0
	v_mfma_f32_16x16x32_bf16 v[74:77], v[174:177], v[218:221], 0
	v_mfma_f32_16x16x32_bf16 v[70:73], v[166:169], v[240:243], 0
	v_mfma_f32_16x16x32_bf16 v[66:69], v[174:177], v[240:243], 0
	v_mfma_f32_16x16x32_bf16 v[94:97], v[170:173], v[206:209], v[94:97]
	v_mfma_f32_16x16x32_bf16 v[90:93], v[178:181], v[206:209], v[90:93]
	v_mfma_f32_16x16x32_bf16 v[86:89], v[170:173], v[214:217], v[86:89]
	v_mfma_f32_16x16x32_bf16 v[82:85], v[178:181], v[214:217], v[82:85]
	v_mfma_f32_16x16x32_bf16 v[78:81], v[170:173], v[236:239], v[78:81]
	v_mfma_f32_16x16x32_bf16 v[74:77], v[178:181], v[236:239], v[74:77]
	v_mfma_f32_16x16x32_bf16 v[70:73], v[170:173], v[244:247], v[70:73]
	v_mfma_f32_16x16x32_bf16 v[66:69], v[178:181], v[244:247], v[66:69]
	s_barrier
	s_add_i32 s10, s13, s0
	s_mov_b32 m0, s10
	ds_read_b128 v[182:185], v165 offset:16384
	ds_read_b128 v[206:209], v165 offset:17408
	ds_read_b128 v[210:213], v165 offset:18432
	ds_read_b128 v[214:217], v165 offset:19456
	ds_read_b128 v[218:221], v165 offset:20480
	ds_read_b128 v[236:239], v165 offset:21504
	ds_read_b128 v[240:243], v165 offset:22528
	ds_read_b128 v[244:247], v165 offset:23552
	global_load_lds_dwordx4 v132, s[80:81]
	s_add_i32 m0, s10, 0x2000
	s_add_u32 s10, s80, 0x20000
	s_addc_u32 s11, s81, 0
	s_add_i32 s9, s9, s0
	global_load_lds_dwordx4 v136, s[80:81]
	s_mov_b32 m0, s9
	s_nop 0
	global_load_lds_dwordx4 v132, s[10:11]
	s_add_i32 m0, s9, 0x2000
	s_nop 0
	global_load_lds_dwordx4 v136, s[10:11]
	s_mov_b32 m0, s1
	s_nop 0
	global_load_lds_dwordx4 v130, s[84:85]
	s_mov_b32 m0, s25
	s_nop 0
	global_load_lds_dwordx4 v134, s[84:85]
	s_nop 0
	s_waitcnt vmcnt(8)
	s_waitcnt lgkmcnt(0)
	s_barrier
; #define PG8_STAGE(bufoff, gbase, voff) do { _Pragma("unroll") for (int _i = 0; _i < 2; ++_i) \
;         __builtin_amdgcn_global_load_lds((const unsigned*)((const char*)(gbase) + (voff)[_i]), (PG8_LAS unsigned*)(lds + (bufoff) + ldsw + _i * 8192), 16, 0, 0); } while (0)
; #define PG8_LDA(dst, b, h) do { _Pragma("unroll") for (int m = 0; m < 4; ++m) _Pragma("unroll") for (int k = 0; k < 2; ++k) dst[m][k] = *(const PG8_LAS bf16x8*)(lds + PG8_SA(b, h) + aoff + m * 2048 + k * 1024); } while (0)
; #define PG8_LDB(dst, b, h) do { _Pragma("unroll") for (int n = 0; n < 2; ++n) _Pragma("unroll") for (int k = 0; k < 2; ++k) dst[n][k] = *(const PG8_LAS bf16x8*)(lds + PG8_SB(b, h) + boff + n * 2048 + k * 1024); } while (0)
; #define PG8_MMA(ai, bj, At, Bt) do { __builtin_amdgcn_s_setprio(1); _Pragma("unroll") for (int m = 0; m < 4; ++m) _Pragma("unroll") for (int n = 0; n < 2; ++n) _Pragma("unroll") for (int k = 0; k < 2; ++k) \
;         acc[ai][bj][m][n] = __builtin_amdgcn_mfma_f32_16x16x32_bf16(Bt[n][k], At[m][k], acc[ai][bj][m][n], 0, 0, 0); __builtin_amdgcn_s_setprio(0); } while (0)
; #define PG8_WAIT_V(n) asm volatile("s_waitcnt vmcnt(" #n ")" ::: "memory")
; #define PG8_WAIT_L(n) asm volatile("s_waitcnt lgkmcnt(" #n ")" ::: "memory")
; #define PG8_BAR __builtin_amdgcn_s_barrier()
; #define PG8_SCHED __builtin_amdgcn_sched_barrier(0)
; template <class Epi, class Sched, bool ALIGN_EPI = false, bool SP2 = false>
; __device__ __forceinline__ void gemm_phase(PG8_LAS unsigned char* lds, const Gemm g, const Sched& S, const Epi& E) {
;     ...
;             PG8_WAIT_V(8); PG8_WAIT_L(0); PG8_BAR; PG8_MMA(1, 0, At, B0); PG8_MMA(1, 1, At, B1); PG8_BAR; PG8_SCHED;
;             PG8_LDB(B0, 1, 0); PG8_LDB(B1, 1, 1); PG8_SCHED; PG8_LDA(At, 1, 0); PG8_STAGE(PG8_SA(0, 1), a2 + hstep, voffA);
;             PG8_WAIT_V(8); PG8_WAIT_L(0); PG8_BAR; PG8_MMA(0, 0, At, B0); PG8_MMA(0, 1, At, B1); PG8_BAR; PG8_SCHED;
	v_mfma_f32_16x16x32_bf16 v[62:65], v[148:151], v[182:185], 0
	v_mfma_f32_16x16x32_bf16 v[58:61], v[156:159], v[182:185], 0
	v_mfma_f32_16x16x32_bf16 v[54:57], v[148:151], v[210:213], 0
	v_mfma_f32_16x16x32_bf16 v[50:53], v[156:159], v[210:213], 0
	v_mfma_f32_16x16x32_bf16 v[46:49], v[148:151], v[218:221], 0
	v_mfma_f32_16x16x32_bf16 v[42:45], v[156:159], v[218:221], 0
	v_mfma_f32_16x16x32_bf16 v[38:41], v[148:151], v[240:243], 0
	v_mfma_f32_16x16x32_bf16 v[34:37], v[156:159], v[240:243], 0
	v_mfma_f32_16x16x32_bf16 v[62:65], v[152:155], v[206:209], v[62:65]
	v_mfma_f32_16x16x32_bf16 v[58:61], v[160:163], v[206:209], v[58:61]
	v_mfma_f32_16x16x32_bf16 v[54:57], v[152:155], v[214:217], v[54:57]
	v_mfma_f32_16x16x32_bf16 v[50:53], v[160:163], v[214:217], v[50:53]
	v_mfma_f32_16x16x32_bf16 v[46:49], v[152:155], v[236:239], v[46:49]
	v_mfma_f32_16x16x32_bf16 v[42:45], v[160:163], v[236:239], v[42:45]
	v_mfma_f32_16x16x32_bf16 v[38:41], v[152:155], v[244:247], v[38:41]
	v_mfma_f32_16x16x32_bf16 v[34:37], v[160:163], v[244:247], v[34:37]
	v_mfma_f32_16x16x32_bf16 v[30:33], v[166:169], v[182:185], 0
	v_mfma_f32_16x16x32_bf16 v[26:29], v[174:177], v[182:185], 0
	v_mfma_f32_16x16x32_bf16 v[22:25], v[166:169], v[210:213], 0
	v_mfma_f32_16x16x32_bf16 v[18:21], v[174:177], v[210:213], 0
	v_mfma_f32_16x16x32_bf16 v[14:17], v[166:169], v[218:221], 0
	v_mfma_f32_16x16x32_bf16 v[10:13], v[174:177], v[218:221], 0
	v_mfma_f32_16x16x32_bf16 v[6:9], v[166:169], v[240:243], 0
	v_mfma_f32_16x16x32_bf16 v[2:5], v[174:177], v[240:243], 0
	v_mfma_f32_16x16x32_bf16 v[30:33], v[170:173], v[206:209], v[30:33]
	v_mfma_f32_16x16x32_bf16 v[26:29], v[178:181], v[206:209], v[26:29]
	v_mfma_f32_16x16x32_bf16 v[22:25], v[170:173], v[214:217], v[22:25]
	v_mfma_f32_16x16x32_bf16 v[18:21], v[178:181], v[214:217], v[18:21]
	v_mfma_f32_16x16x32_bf16 v[14:17], v[170:173], v[236:239], v[14:17]
	v_mfma_f32_16x16x32_bf16 v[10:13], v[178:181], v[236:239], v[10:13]
	v_mfma_f32_16x16x32_bf16 v[6:9], v[170:173], v[244:247], v[6:9]
	v_mfma_f32_16x16x32_bf16 v[2:5], v[178:181], v[244:247], v[2:5]
	s_barrier
	s_add_i32 s9, 0, 0x18000
	s_add_i32 s12, 0, 0x1c000
	ds_read_b128 v[148:151], v198
	ds_read_b128 v[152:155], v198 offset:1024
	ds_read_b128 v[156:159], v198 offset:2048
	ds_read_b128 v[160:163], v198 offset:3072
	ds_read_b128 v[166:169], v199
	ds_read_b128 v[170:173], v199 offset:1024
	ds_read_b128 v[174:177], v199 offset:2048
	ds_read_b128 v[178:181], v199 offset:3072
	s_add_u32 s10, s84, 0x80000
	s_addc_u32 s11, s85, 0
	s_mov_b32 m0, s42
	ds_read_b128 v[182:185], v165 offset:32768
	ds_read_b128 v[206:209], v165 offset:33792
	ds_read_b128 v[210:213], v165 offset:34816
	ds_read_b128 v[214:217], v165 offset:35840
	ds_read_b128 v[218:221], v165 offset:36864
	ds_read_b128 v[236:239], v165 offset:37888
	ds_read_b128 v[240:243], v165 offset:38912
	ds_read_b128 v[244:247], v165 offset:39936
	global_load_lds_dwordx4 v130, s[10:11]
	s_mov_b32 m0, s51
	s_nop 0
	global_load_lds_dwordx4 v134, s[10:11]
	s_waitcnt vmcnt(8)
	s_waitcnt lgkmcnt(0)
	s_barrier
	v_mfma_f32_16x16x32_bf16 v[126:129], v[148:151], v[182:185], v[126:129]
	v_mfma_f32_16x16x32_bf16 v[122:125], v[156:159], v[182:185], v[122:125]
	v_mfma_f32_16x16x32_bf16 v[118:121], v[148:151], v[210:213], v[118:121]
	v_mfma_f32_16x16x32_bf16 v[114:117], v[156:159], v[210:213], v[114:117]
	v_mfma_f32_16x16x32_bf16 v[110:113], v[148:151], v[218:221], v[110:113]
	v_mfma_f32_16x16x32_bf16 v[106:109], v[156:159], v[218:221], v[106:109]
	v_mfma_f32_16x16x32_bf16 v[102:105], v[148:151], v[240:243], v[102:105]
	v_mfma_f32_16x16x32_bf16 v[98:101], v[156:159], v[240:243], v[98:101]
	v_mfma_f32_16x16x32_bf16 v[126:129], v[152:155], v[206:209], v[126:129]
	v_mfma_f32_16x16x32_bf16 v[122:125], v[160:163], v[206:209], v[122:125]
	v_mfma_f32_16x16x32_bf16 v[118:121], v[152:155], v[214:217], v[118:121]
	v_mfma_f32_16x16x32_bf16 v[114:117], v[160:163], v[214:217], v[114:117]
	v_mfma_f32_16x16x32_bf16 v[110:113], v[152:155], v[236:239], v[110:113]
	v_mfma_f32_16x16x32_bf16 v[106:109], v[160:163], v[236:239], v[106:109]
	v_mfma_f32_16x16x32_bf16 v[102:105], v[152:155], v[244:247], v[102:105]
	v_mfma_f32_16x16x32_bf16 v[98:101], v[160:163], v[244:247], v[98:101]
	v_mfma_f32_16x16x32_bf16 v[94:97], v[166:169], v[182:185], v[94:97]
	v_mfma_f32_16x16x32_bf16 v[90:93], v[174:177], v[182:185], v[90:93]
	v_mfma_f32_16x16x32_bf16 v[86:89], v[166:169], v[210:213], v[86:89]
	v_mfma_f32_16x16x32_bf16 v[82:85], v[174:177], v[210:213], v[82:85]
	v_mfma_f32_16x16x32_bf16 v[78:81], v[166:169], v[218:221], v[78:81]
	v_mfma_f32_16x16x32_bf16 v[74:77], v[174:177], v[218:221], v[74:77]
	v_mfma_f32_16x16x32_bf16 v[70:73], v[166:169], v[240:243], v[70:73]
	v_mfma_f32_16x16x32_bf16 v[66:69], v[174:177], v[240:243], v[66:69]
	v_mfma_f32_16x16x32_bf16 v[94:97], v[170:173], v[206:209], v[94:97]
	v_mfma_f32_16x16x32_bf16 v[90:93], v[178:181], v[206:209], v[90:93]
	v_mfma_f32_16x16x32_bf16 v[86:89], v[170:173], v[214:217], v[86:89]
	v_mfma_f32_16x16x32_bf16 v[82:85], v[178:181], v[214:217], v[82:85]
	v_mfma_f32_16x16x32_bf16 v[78:81], v[170:173], v[236:239], v[78:81]
	v_mfma_f32_16x16x32_bf16 v[74:77], v[178:181], v[236:239], v[74:77]
	v_mfma_f32_16x16x32_bf16 v[70:73], v[170:173], v[244:247], v[70:73]
	v_mfma_f32_16x16x32_bf16 v[66:69], v[178:181], v[244:247], v[66:69]
	s_barrier
; #define PG8_STAGE(bufoff, gbase, voff) do { _Pragma("unroll") for (int _i = 0; _i < 2; ++_i) \
;         __builtin_amdgcn_global_load_lds((const unsigned*)((const char*)(gbase) + (voff)[_i]), (PG8_LAS unsigned*)(lds + (bufoff) + ldsw + _i * 8192), 16, 0, 0); } while (0)
; #define PG8_LDA(dst, b, h) do { _Pragma("unroll") for (int m = 0; m < 4; ++m) _Pragma("unroll") for (int k = 0; k < 2; ++k) dst[m][k] = *(const PG8_LAS bf16x8*)(lds + PG8_SA(b, h) + aoff + m * 2048 + k * 1024); } while (0)
; #define PG8_LDB(dst, b, h) do { _Pragma("unroll") for (int n = 0; n < 2; ++n) _Pragma("unroll") for (int k = 0; k < 2; ++k) dst[n][k] = *(const PG8_LAS bf16x8*)(lds + PG8_SB(b, h) + boff + n * 2048 + k * 1024); } while (0)
; #define PG8_MMA(ai, bj, At, Bt) do { __builtin_amdgcn_s_setprio(1); _Pragma("unroll") for (int m = 0; m < 4; ++m) _Pragma("unroll") for (int n = 0; n < 2; ++n) _Pragma("unroll") for (int k = 0; k < 2; ++k) \
;         acc[ai][bj][m][n] = __builtin_amdgcn_mfma_f32_16x16x32_bf16(Bt[n][k], At[m][k], acc[ai][bj][m][n], 0, 0, 0); __builtin_amdgcn_s_setprio(0); } while (0)
; #define PG8_WAIT_V(n) asm volatile("s_waitcnt vmcnt(" #n ")" ::: "memory")
; #define PG8_WAIT_L(n) asm volatile("s_waitcnt lgkmcnt(" #n ")" ::: "memory")
; #define PG8_BAR __builtin_amdgcn_s_barrier()
; template <class Epi, class Sched, bool ALIGN_EPI = false, bool SP2 = false>
; __device__ __forceinline__ void gemm_phase(PG8_LAS unsigned char* lds, const Gemm g, const Sched& S, const Epi& E) {
;     ...
;             const char* a1 = cA + (size_t)(t + 1) * kstep;
;             const char* a2 = last ? nA : cA + (size_t)(t + 2) * kstep; const char* b2 = last ? nB : cB + (size_t)(t + 2) * kstep;
;             const char* a3 = a2 + kstep; const char* b3 = b2 + kstep;
;             if (last && has_next) S.a_ready(nxt);
;             if constexpr (SP2) {
;             PG8_LDB(B0, 0, 0); PG8_LDB(B1, 0, 1); PG8_SCHED; PG8_LDA(At, 0, 0); PG8_STAGE(PG8_SA(1, 1), a1 + hstep, voffA);
;             PG8_WAIT_V(8); PG8_WAIT_L(0); PG8_BAR; PG8_MMA(0, 0, At, B0); PG8_MMA(0, 1, At, B1); PG8_BAR; PG8_SCHED;
;     ...
;             PG8_LDA(At, 1, 1); PG8_STAGE(PG8_SB(1, 0), b3, voffB); PG8_STAGE(PG8_SB(1, 1), b3 + hstepB, voffB); PG8_STAGE(PG8_SA(1, 0), a3, voffA);
;             PG8_WAIT_V(8); PG8_WAIT_L(0); PG8_BAR; PG8_MMA(1, 0, At, B0); PG8_MMA(1, 1, At, B1); PG8_BAR; PG8_SCHED;
	s_add_i32 s9, s9, s0
	s_mov_b32 m0, s9
	ds_read_b128 v[182:185], v165 offset:49152
	ds_read_b128 v[206:209], v165 offset:50176
	ds_read_b128 v[210:213], v165 offset:51200
	ds_read_b128 v[214:217], v165 offset:52224
	ds_read_b128 v[218:221], v165 offset:53248
	ds_read_b128 v[236:239], v165 offset:54272
	ds_read_b128 v[240:243], v165 offset:55296
	ds_read_b128 v[244:247], v165 offset:56320
	s_add_u32 s100, s80, s60
	s_addc_u32 s101, s81, s61
	global_load_lds_dwordx4 v132, s[100:101]
	s_add_i32 m0, s9, 0x2000
	s_add_u32 s10, s80, 0x20080
	s_addc_u32 s11, s81, 0
	s_add_i32 s9, s12, s0
	global_load_lds_dwordx4 v136, s[100:101]
	s_mov_b32 m0, s9
	s_nop 0
	global_load_lds_dwordx4 v132, s[10:11]
	s_add_i32 m0, s9, 0x2000
	s_nop 0
	global_load_lds_dwordx4 v136, s[10:11]
	s_mov_b32 m0, s66
	s_add_u32 s100, s84, s60
	s_addc_u32 s101, s85, s61
	global_load_lds_dwordx4 v130, s[100:101]
	s_mov_b32 m0, s67
	s_nop 0
	global_load_lds_dwordx4 v134, s[100:101]
	s_waitcnt vmcnt(8)
	s_waitcnt lgkmcnt(0)
	s_barrier
	v_mfma_f32_16x16x32_bf16 v[62:65], v[148:151], v[182:185], v[62:65]
	v_mfma_f32_16x16x32_bf16 v[58:61], v[156:159], v[182:185], v[58:61]
	v_mfma_f32_16x16x32_bf16 v[54:57], v[148:151], v[210:213], v[54:57]
	v_mfma_f32_16x16x32_bf16 v[50:53], v[156:159], v[210:213], v[50:53]
	v_mfma_f32_16x16x32_bf16 v[46:49], v[148:151], v[218:221], v[46:49]
	v_mfma_f32_16x16x32_bf16 v[42:45], v[156:159], v[218:221], v[42:45]
	v_mfma_f32_16x16x32_bf16 v[38:41], v[148:151], v[240:243], v[38:41]
	v_mfma_f32_16x16x32_bf16 v[34:37], v[156:159], v[240:243], v[34:37]
	v_mfma_f32_16x16x32_bf16 v[62:65], v[152:155], v[206:209], v[62:65]
	v_mfma_f32_16x16x32_bf16 v[58:61], v[160:163], v[206:209], v[58:61]
	v_mfma_f32_16x16x32_bf16 v[54:57], v[152:155], v[214:217], v[54:57]
	v_mfma_f32_16x16x32_bf16 v[50:53], v[160:163], v[214:217], v[50:53]
	v_mfma_f32_16x16x32_bf16 v[46:49], v[152:155], v[236:239], v[46:49]
	v_mfma_f32_16x16x32_bf16 v[42:45], v[160:163], v[236:239], v[42:45]
	v_mfma_f32_16x16x32_bf16 v[38:41], v[152:155], v[244:247], v[38:41]
	v_mfma_f32_16x16x32_bf16 v[34:37], v[160:163], v[244:247], v[34:37]
	v_mfma_f32_16x16x32_bf16 v[30:33], v[166:169], v[182:185], v[30:33]
	v_mfma_f32_16x16x32_bf16 v[26:29], v[174:177], v[182:185], v[26:29]
	v_mfma_f32_16x16x32_bf16 v[22:25], v[166:169], v[210:213], v[22:25]
	v_mfma_f32_16x16x32_bf16 v[18:21], v[174:177], v[210:213], v[18:21]
	v_mfma_f32_16x16x32_bf16 v[14:17], v[166:169], v[218:221], v[14:17]
	v_mfma_f32_16x16x32_bf16 v[10:13], v[174:177], v[218:221], v[10:13]
	v_mfma_f32_16x16x32_bf16 v[6:9], v[166:169], v[240:243], v[6:9]
	v_mfma_f32_16x16x32_bf16 v[2:5], v[174:177], v[240:243], v[2:5]
	v_mfma_f32_16x16x32_bf16 v[30:33], v[170:173], v[206:209], v[30:33]
	v_mfma_f32_16x16x32_bf16 v[26:29], v[178:181], v[206:209], v[26:29]
	v_mfma_f32_16x16x32_bf16 v[22:25], v[170:173], v[214:217], v[22:25]
	v_mfma_f32_16x16x32_bf16 v[18:21], v[178:181], v[214:217], v[18:21]
	v_mfma_f32_16x16x32_bf16 v[14:17], v[170:173], v[236:239], v[14:17]
	v_mfma_f32_16x16x32_bf16 v[10:13], v[178:181], v[236:239], v[10:13]
	v_mfma_f32_16x16x32_bf16 v[6:9], v[170:173], v[244:247], v[6:9]
	v_mfma_f32_16x16x32_bf16 v[2:5], v[178:181], v[244:247], v[2:5]
	s_barrier
	s_add_i32 s8, s8, 2
	s_add_u32 s46, s46, 0x100
	s_addc_u32 s47, s47, 0
	s_cmp_gt_u32 s8, 29
.LBB0_170:
	s_add_u32 s9, s70, s46
	s_addc_u32 s10, s71, s47
	s_add_u32 s9, s9, 0x100
	s_addc_u32 s10, s10, 0
	s_add_u32 s100, s9, 0x7ff80
	s_addc_u32 s101, s10, 0
	s_add_u32 s11, s93, s46
	s_addc_u32 s12, s94, s47
	s_add_i32 s13, 0, 0x10000
	s_cmpk_eq_i32 s46, 0xf00
	s_cselect_b32 s85, s4, s10
	s_cselect_b32 s84, s5, s9
	s_cselect_b32 s81, s6, s12
	s_cselect_b32 s80, s7, s11
	s_add_i32 s9, 0, 0x14000
	ds_read_b128 v[148:151], v186
	ds_read_b128 v[152:155], v186 offset:1024
	ds_read_b128 v[156:159], v186 offset:2048
	ds_read_b128 v[160:163], v186 offset:3072
	ds_read_b128 v[166:169], v187
	ds_read_b128 v[170:173], v187 offset:1024
	ds_read_b128 v[174:177], v187 offset:2048
	ds_read_b128 v[178:181], v187 offset:3072
	s_add_i32 m0, s1, 0xc000
	ds_read_b128 v[182:185], v165
	ds_read_b128 v[206:209], v165 offset:1024
	ds_read_b128 v[210:213], v165 offset:2048
	ds_read_b128 v[214:217], v165 offset:3072
	ds_read_b128 v[218:221], v165 offset:4096
	ds_read_b128 v[236:239], v165 offset:5120
	ds_read_b128 v[240:243], v165 offset:6144
	ds_read_b128 v[244:247], v165 offset:7168
	global_load_lds_dwordx4 v140, s[100:101]
	s_add_i32 m0, s1, 0xe000
	s_nop 0
	global_load_lds_dwordx4 v142, s[100:101]
	s_nop 0
	s_waitcnt vmcnt(8)
	s_waitcnt lgkmcnt(0)
	s_barrier
; #define PG8_STAGE(bufoff, gbase, voff) do { _Pragma("unroll") for (int _i = 0; _i < 2; ++_i) \
;         __builtin_amdgcn_global_load_lds((const unsigned*)((const char*)(gbase) + (voff)[_i]), (PG8_LAS unsigned*)(lds + (bufoff) + ldsw + _i * 8192), 16, 0, 0); } while (0)
; #define PG8_LDA(dst, b, h) do { _Pragma("unroll") for (int m = 0; m < 4; ++m) _Pragma("unroll") for (int k = 0; k < 2; ++k) dst[m][k] = *(const PG8_LAS bf16x8*)(lds + PG8_SA(b, h) + aoff + m * 2048 + k * 1024); } while (0)
; #define PG8_MMA(ai, bj, At, Bt) do { __builtin_amdgcn_s_setprio(1); _Pragma("unroll") for (int m = 0; m < 4; ++m) _Pragma("unroll") for (int n = 0; n < 2; ++n) _Pragma("unroll") for (int k = 0; k < 2; ++k) \
;         acc[ai][bj][m][n] = __builtin_amdgcn_mfma_f32_16x16x32_bf16(Bt[n][k], At[m][k], acc[ai][bj][m][n], 0, 0, 0); __builtin_amdgcn_s_setprio(0); } while (0)
; #define PG8_WAIT_V(n) asm volatile("s_waitcnt vmcnt(" #n ")" ::: "memory")
; #define PG8_WAIT_L(n) asm volatile("s_waitcnt lgkmcnt(" #n ")" ::: "memory")
; #define PG8_BAR __builtin_amdgcn_s_barrier()
; #define PG8_SCHED __builtin_amdgcn_sched_barrier(0)
; template <class Epi, class Sched, bool ALIGN_EPI = false, bool SP2 = false>
; __device__ __forceinline__ void gemm_phase(PG8_LAS unsigned char* lds, const Gemm g, const Sched& S, const Epi& E) {
;     ...
;             PG8_WAIT_V(8); PG8_WAIT_L(0); PG8_BAR; PG8_MMA(0, 0, At, B0); PG8_MMA(0, 1, At, B1); PG8_BAR; PG8_SCHED;
;             PG8_LDA(At, 0, 1); PG8_STAGE(PG8_SB(0, 0), b2, voffB); PG8_STAGE(PG8_SB(0, 1), b2 + hstepB, voffB); PG8_STAGE(PG8_SA(0, 0), a2, voffA);
;             PG8_WAIT_V(8); PG8_WAIT_L(0); PG8_BAR; PG8_MMA(1, 0, At, B0); PG8_MMA(1, 1, At, B1); PG8_BAR; PG8_SCHED;
	v_mfma_f32_16x16x32_bf16 v[126:129], v[148:151], v[182:185], v[126:129]
	v_mfma_f32_16x16x32_bf16 v[122:125], v[156:159], v[182:185], v[122:125]
	v_mfma_f32_16x16x32_bf16 v[118:121], v[148:151], v[210:213], v[118:121]
	v_mfma_f32_16x16x32_bf16 v[114:117], v[156:159], v[210:213], v[114:117]
	v_mfma_f32_16x16x32_bf16 v[110:113], v[148:151], v[218:221], v[110:113]
	v_mfma_f32_16x16x32_bf16 v[106:109], v[156:159], v[218:221], v[106:109]
	v_mfma_f32_16x16x32_bf16 v[102:105], v[148:151], v[240:243], v[102:105]
	v_mfma_f32_16x16x32_bf16 v[98:101], v[156:159], v[240:243], v[98:101]
	v_mfma_f32_16x16x32_bf16 v[126:129], v[152:155], v[206:209], v[126:129]
	v_mfma_f32_16x16x32_bf16 v[122:125], v[160:163], v[206:209], v[122:125]
	v_mfma_f32_16x16x32_bf16 v[118:121], v[152:155], v[214:217], v[118:121]
	v_mfma_f32_16x16x32_bf16 v[114:117], v[160:163], v[214:217], v[114:117]
	v_mfma_f32_16x16x32_bf16 v[110:113], v[152:155], v[236:239], v[110:113]
	v_mfma_f32_16x16x32_bf16 v[106:109], v[160:163], v[236:239], v[106:109]
	v_mfma_f32_16x16x32_bf16 v[102:105], v[152:155], v[244:247], v[102:105]
	v_mfma_f32_16x16x32_bf16 v[98:101], v[160:163], v[244:247], v[98:101]
	v_mfma_f32_16x16x32_bf16 v[94:97], v[166:169], v[182:185], v[94:97]
	v_mfma_f32_16x16x32_bf16 v[90:93], v[174:177], v[182:185], v[90:93]
	v_mfma_f32_16x16x32_bf16 v[86:89], v[166:169], v[210:213], v[86:89]
	v_mfma_f32_16x16x32_bf16 v[82:85], v[174:177], v[210:213], v[82:85]
	v_mfma_f32_16x16x32_bf16 v[78:81], v[166:169], v[218:221], v[78:81]
	v_mfma_f32_16x16x32_bf16 v[74:77], v[174:177], v[218:221], v[74:77]
	v_mfma_f32_16x16x32_bf16 v[70:73], v[166:169], v[240:243], v[70:73]
	v_mfma_f32_16x16x32_bf16 v[66:69], v[174:177], v[240:243], v[66:69]
	v_mfma_f32_16x16x32_bf16 v[94:97], v[170:173], v[206:209], v[94:97]
	v_mfma_f32_16x16x32_bf16 v[90:93], v[178:181], v[206:209], v[90:93]
	v_mfma_f32_16x16x32_bf16 v[86:89], v[170:173], v[214:217], v[86:89]
	v_mfma_f32_16x16x32_bf16 v[82:85], v[178:181], v[214:217], v[82:85]
	v_mfma_f32_16x16x32_bf16 v[78:81], v[170:173], v[236:239], v[78:81]
	v_mfma_f32_16x16x32_bf16 v[74:77], v[178:181], v[236:239], v[74:77]
	v_mfma_f32_16x16x32_bf16 v[70:73], v[170:173], v[244:247], v[70:73]
	v_mfma_f32_16x16x32_bf16 v[66:69], v[178:181], v[244:247], v[66:69]
	s_barrier
	s_add_i32 s10, s13, s0
	s_mov_b32 m0, s10
	ds_read_b128 v[182:185], v165 offset:16384
	ds_read_b128 v[206:209], v165 offset:17408
	ds_read_b128 v[210:213], v165 offset:18432
	ds_read_b128 v[214:217], v165 offset:19456
	ds_read_b128 v[218:221], v165 offset:20480
	ds_read_b128 v[236:239], v165 offset:21504
	ds_read_b128 v[240:243], v165 offset:22528
	ds_read_b128 v[244:247], v165 offset:23552
	global_load_lds_dwordx4 v132, s[80:81]
	s_add_i32 m0, s10, 0x2000
	s_add_u32 s10, s80, 0x20000
	s_addc_u32 s11, s81, 0
	s_add_i32 s9, s9, s0
	global_load_lds_dwordx4 v136, s[80:81]
	s_mov_b32 m0, s9
	s_nop 0
	global_load_lds_dwordx4 v132, s[10:11]
	s_add_i32 m0, s9, 0x2000
	s_nop 0
	global_load_lds_dwordx4 v136, s[10:11]
	s_mov_b32 m0, s1
	s_nop 0
	global_load_lds_dwordx4 v130, s[84:85]
	s_mov_b32 m0, s25
	s_nop 0
	global_load_lds_dwordx4 v134, s[84:85]
	s_nop 0
	s_waitcnt vmcnt(8)
	s_waitcnt lgkmcnt(0)
	s_barrier
	v_mfma_f32_16x16x32_bf16 v[62:65], v[148:151], v[182:185], v[62:65]
	v_mfma_f32_16x16x32_bf16 v[58:61], v[156:159], v[182:185], v[58:61]
	v_mfma_f32_16x16x32_bf16 v[54:57], v[148:151], v[210:213], v[54:57]
	v_mfma_f32_16x16x32_bf16 v[50:53], v[156:159], v[210:213], v[50:53]
	v_mfma_f32_16x16x32_bf16 v[46:49], v[148:151], v[218:221], v[46:49]
	v_mfma_f32_16x16x32_bf16 v[42:45], v[156:159], v[218:221], v[42:45]
	v_mfma_f32_16x16x32_bf16 v[38:41], v[148:151], v[240:243], v[38:41]
	v_mfma_f32_16x16x32_bf16 v[34:37], v[156:159], v[240:243], v[34:37]
	v_mfma_f32_16x16x32_bf16 v[62:65], v[152:155], v[206:209], v[62:65]
	v_mfma_f32_16x16x32_bf16 v[58:61], v[160:163], v[206:209], v[58:61]
	v_mfma_f32_16x16x32_bf16 v[54:57], v[152:155], v[214:217], v[54:57]
	v_mfma_f32_16x16x32_bf16 v[50:53], v[160:163], v[214:217], v[50:53]
	v_mfma_f32_16x16x32_bf16 v[46:49], v[152:155], v[236:239], v[46:49]
	v_mfma_f32_16x16x32_bf16 v[42:45], v[160:163], v[236:239], v[42:45]
	v_mfma_f32_16x16x32_bf16 v[38:41], v[152:155], v[244:247], v[38:41]
	v_mfma_f32_16x16x32_bf16 v[34:37], v[160:163], v[244:247], v[34:37]
	v_mfma_f32_16x16x32_bf16 v[30:33], v[166:169], v[182:185], v[30:33]
	v_mfma_f32_16x16x32_bf16 v[26:29], v[174:177], v[182:185], v[26:29]
	v_mfma_f32_16x16x32_bf16 v[22:25], v[166:169], v[210:213], v[22:25]
	v_mfma_f32_16x16x32_bf16 v[18:21], v[174:177], v[210:213], v[18:21]
	v_mfma_f32_16x16x32_bf16 v[14:17], v[166:169], v[218:221], v[14:17]
	v_mfma_f32_16x16x32_bf16 v[10:13], v[174:177], v[218:221], v[10:13]
	v_mfma_f32_16x16x32_bf16 v[6:9], v[166:169], v[240:243], v[6:9]
	v_mfma_f32_16x16x32_bf16 v[2:5], v[174:177], v[240:243], v[2:5]
	v_mfma_f32_16x16x32_bf16 v[30:33], v[170:173], v[206:209], v[30:33]
	v_mfma_f32_16x16x32_bf16 v[26:29], v[178:181], v[206:209], v[26:29]
	v_mfma_f32_16x16x32_bf16 v[22:25], v[170:173], v[214:217], v[22:25]
	v_mfma_f32_16x16x32_bf16 v[18:21], v[178:181], v[214:217], v[18:21]
	v_mfma_f32_16x16x32_bf16 v[14:17], v[170:173], v[236:239], v[14:17]
	v_mfma_f32_16x16x32_bf16 v[10:13], v[178:181], v[236:239], v[10:13]
	v_mfma_f32_16x16x32_bf16 v[6:9], v[170:173], v[244:247], v[6:9]
	v_mfma_f32_16x16x32_bf16 v[2:5], v[178:181], v[244:247], v[2:5]
	s_barrier
; #define PG8_STAGE(bufoff, gbase, voff) do { _Pragma("unroll") for (int _i = 0; _i < 2; ++_i) \
;         __builtin_amdgcn_global_load_lds((const unsigned*)((const char*)(gbase) + (voff)[_i]), (PG8_LAS unsigned*)(lds + (bufoff) + ldsw + _i * 8192), 16, 0, 0); } while (0)
; #define PG8_LDA(dst, b, h) do { _Pragma("unroll") for (int m = 0; m < 4; ++m) _Pragma("unroll") for (int k = 0; k < 2; ++k) dst[m][k] = *(const PG8_LAS bf16x8*)(lds + PG8_SA(b, h) + aoff + m * 2048 + k * 1024); } while (0)
; #define PG8_LDB(dst, b, h) do { _Pragma("unroll") for (int n = 0; n < 2; ++n) _Pragma("unroll") for (int k = 0; k < 2; ++k) dst[n][k] = *(const PG8_LAS bf16x8*)(lds + PG8_SB(b, h) + boff + n * 2048 + k * 1024); } while (0)
; #define PG8_MMA(ai, bj, At, Bt) do { __builtin_amdgcn_s_setprio(1); _Pragma("unroll") for (int m = 0; m < 4; ++m) _Pragma("unroll") for (int n = 0; n < 2; ++n) _Pragma("unroll") for (int k = 0; k < 2; ++k) \
;         acc[ai][bj][m][n] = __builtin_amdgcn_mfma_f32_16x16x32_bf16(Bt[n][k], At[m][k], acc[ai][bj][m][n], 0, 0, 0); __builtin_amdgcn_s_setprio(0); } while (0)
; #define PG8_WAIT_V(n) asm volatile("s_waitcnt vmcnt(" #n ")" ::: "memory")
; #define PG8_WAIT_L(n) asm volatile("s_waitcnt lgkmcnt(" #n ")" ::: "memory")
; #define PG8_BAR __builtin_amdgcn_s_barrier()
; #define PG8_SCHED __builtin_amdgcn_sched_barrier(0)
; template <class Epi, class Sched, bool ALIGN_EPI = false, bool SP2 = false>
; __device__ __forceinline__ void gemm_phase(PG8_LAS unsigned char* lds, const Gemm g, const Sched& S, const Epi& E) {
;     ...
;             PG8_LDB(B0, 1, 0); PG8_LDB(B1, 1, 1); PG8_SCHED; PG8_LDA(At, 1, 0); PG8_STAGE(PG8_SA(0, 1), a2 + hstep, voffA);
;             PG8_WAIT_V(8); PG8_WAIT_L(0); PG8_BAR; PG8_MMA(0, 0, At, B0); PG8_MMA(0, 1, At, B1); PG8_BAR; PG8_SCHED;
;             PG8_LDA(At, 1, 1); PG8_STAGE(PG8_SB(1, 0), b3, voffB); PG8_STAGE(PG8_SB(1, 1), b3 + hstepB, voffB); PG8_STAGE(PG8_SA(1, 0), a3, voffA);
;             PG8_WAIT_V(8); PG8_WAIT_L(0); PG8_BAR; PG8_MMA(1, 0, At, B0); PG8_MMA(1, 1, At, B1); PG8_BAR; PG8_SCHED;
	s_add_i32 s9, 0, 0x18000
	s_add_i32 s12, 0, 0x1c000
	ds_read_b128 v[148:151], v198
	ds_read_b128 v[152:155], v198 offset:1024
	ds_read_b128 v[156:159], v198 offset:2048
	ds_read_b128 v[160:163], v198 offset:3072
	ds_read_b128 v[166:169], v199
	ds_read_b128 v[170:173], v199 offset:1024
	ds_read_b128 v[174:177], v199 offset:2048
	ds_read_b128 v[178:181], v199 offset:3072
	s_add_u32 s10, s84, 0x80000
	s_addc_u32 s11, s85, 0
	s_mov_b32 m0, s42
	ds_read_b128 v[182:185], v165 offset:32768
	ds_read_b128 v[206:209], v165 offset:33792
	ds_read_b128 v[210:213], v165 offset:34816
	ds_read_b128 v[214:217], v165 offset:35840
	ds_read_b128 v[218:221], v165 offset:36864
	ds_read_b128 v[236:239], v165 offset:37888
	ds_read_b128 v[240:243], v165 offset:38912
	ds_read_b128 v[244:247], v165 offset:39936
	global_load_lds_dwordx4 v130, s[10:11]
	s_mov_b32 m0, s51
	s_nop 0
	global_load_lds_dwordx4 v134, s[10:11]
	s_waitcnt vmcnt(8)
	s_waitcnt lgkmcnt(0)
	s_barrier
	v_mfma_f32_16x16x32_bf16 v[126:129], v[148:151], v[182:185], v[126:129]
	v_mfma_f32_16x16x32_bf16 v[122:125], v[156:159], v[182:185], v[122:125]
	v_mfma_f32_16x16x32_bf16 v[118:121], v[148:151], v[210:213], v[118:121]
	v_mfma_f32_16x16x32_bf16 v[114:117], v[156:159], v[210:213], v[114:117]
	v_mfma_f32_16x16x32_bf16 v[110:113], v[148:151], v[218:221], v[110:113]
	v_mfma_f32_16x16x32_bf16 v[106:109], v[156:159], v[218:221], v[106:109]
	v_mfma_f32_16x16x32_bf16 v[102:105], v[148:151], v[240:243], v[102:105]
	v_mfma_f32_16x16x32_bf16 v[98:101], v[156:159], v[240:243], v[98:101]
	v_mfma_f32_16x16x32_bf16 v[126:129], v[152:155], v[206:209], v[126:129]
	v_mfma_f32_16x16x32_bf16 v[122:125], v[160:163], v[206:209], v[122:125]
	v_mfma_f32_16x16x32_bf16 v[118:121], v[152:155], v[214:217], v[118:121]
	v_mfma_f32_16x16x32_bf16 v[114:117], v[160:163], v[214:217], v[114:117]
	v_mfma_f32_16x16x32_bf16 v[110:113], v[152:155], v[236:239], v[110:113]
	v_mfma_f32_16x16x32_bf16 v[106:109], v[160:163], v[236:239], v[106:109]
	v_mfma_f32_16x16x32_bf16 v[102:105], v[152:155], v[244:247], v[102:105]
	v_mfma_f32_16x16x32_bf16 v[98:101], v[160:163], v[244:247], v[98:101]
	v_mfma_f32_16x16x32_bf16 v[94:97], v[166:169], v[182:185], v[94:97]
	v_mfma_f32_16x16x32_bf16 v[90:93], v[174:177], v[182:185], v[90:93]
	v_mfma_f32_16x16x32_bf16 v[86:89], v[166:169], v[210:213], v[86:89]
	v_mfma_f32_16x16x32_bf16 v[82:85], v[174:177], v[210:213], v[82:85]
	v_mfma_f32_16x16x32_bf16 v[78:81], v[166:169], v[218:221], v[78:81]
	v_mfma_f32_16x16x32_bf16 v[74:77], v[174:177], v[218:221], v[74:77]
	v_mfma_f32_16x16x32_bf16 v[70:73], v[166:169], v[240:243], v[70:73]
	v_mfma_f32_16x16x32_bf16 v[66:69], v[174:177], v[240:243], v[66:69]
	v_mfma_f32_16x16x32_bf16 v[94:97], v[170:173], v[206:209], v[94:97]
	v_mfma_f32_16x16x32_bf16 v[90:93], v[178:181], v[206:209], v[90:93]
	v_mfma_f32_16x16x32_bf16 v[86:89], v[170:173], v[214:217], v[86:89]
	v_mfma_f32_16x16x32_bf16 v[82:85], v[178:181], v[214:217], v[82:85]
	v_mfma_f32_16x16x32_bf16 v[78:81], v[170:173], v[236:239], v[78:81]
	v_mfma_f32_16x16x32_bf16 v[74:77], v[178:181], v[236:239], v[74:77]
	v_mfma_f32_16x16x32_bf16 v[70:73], v[170:173], v[244:247], v[70:73]
	v_mfma_f32_16x16x32_bf16 v[66:69], v[178:181], v[244:247], v[66:69]
	s_barrier
	s_add_i32 s9, s9, s0
	s_mov_b32 m0, s9
	ds_read_b128 v[182:185], v165 offset:49152
	ds_read_b128 v[206:209], v165 offset:50176
	ds_read_b128 v[210:213], v165 offset:51200
	ds_read_b128 v[214:217], v165 offset:52224
	ds_read_b128 v[218:221], v165 offset:53248
	ds_read_b128 v[236:239], v165 offset:54272
	ds_read_b128 v[240:243], v165 offset:55296
	ds_read_b128 v[244:247], v165 offset:56320
	s_add_u32 s100, s80, s60
	s_addc_u32 s101, s81, s61
	global_load_lds_dwordx4 v132, s[100:101]
	s_add_i32 m0, s9, 0x2000
	s_add_u32 s10, s80, 0x20080
	s_addc_u32 s11, s81, 0
	s_add_i32 s9, s12, s0
	global_load_lds_dwordx4 v136, s[100:101]
	s_mov_b32 m0, s9
	s_nop 0
	global_load_lds_dwordx4 v132, s[10:11]
	s_add_i32 m0, s9, 0x2000
	s_nop 0
	global_load_lds_dwordx4 v136, s[10:11]
	s_mov_b32 m0, s66
	s_add_u32 s100, s84, s60
	s_addc_u32 s101, s85, s61
	global_load_lds_dwordx4 v130, s[100:101]
	s_mov_b32 m0, s67
	s_nop 0
	global_load_lds_dwordx4 v134, s[100:101]
	s_waitcnt vmcnt(8)
	s_waitcnt lgkmcnt(0)
	s_barrier
	v_mfma_f32_16x16x32_bf16 v[62:65], v[148:151], v[182:185], v[62:65]
	v_mfma_f32_16x16x32_bf16 v[58:61], v[156:159], v[182:185], v[58:61]
	v_mfma_f32_16x16x32_bf16 v[54:57], v[148:151], v[210:213], v[54:57]
	v_mfma_f32_16x16x32_bf16 v[50:53], v[156:159], v[210:213], v[50:53]
	v_mfma_f32_16x16x32_bf16 v[46:49], v[148:151], v[218:221], v[46:49]
	v_mfma_f32_16x16x32_bf16 v[42:45], v[156:159], v[218:221], v[42:45]
	v_mfma_f32_16x16x32_bf16 v[38:41], v[148:151], v[240:243], v[38:41]
	v_mfma_f32_16x16x32_bf16 v[34:37], v[156:159], v[240:243], v[34:37]
	v_mfma_f32_16x16x32_bf16 v[62:65], v[152:155], v[206:209], v[62:65]
	v_mfma_f32_16x16x32_bf16 v[58:61], v[160:163], v[206:209], v[58:61]
	v_mfma_f32_16x16x32_bf16 v[54:57], v[152:155], v[214:217], v[54:57]
	v_mfma_f32_16x16x32_bf16 v[50:53], v[160:163], v[214:217], v[50:53]
	v_mfma_f32_16x16x32_bf16 v[46:49], v[152:155], v[236:239], v[46:49]
	v_mfma_f32_16x16x32_bf16 v[42:45], v[160:163], v[236:239], v[42:45]
	v_mfma_f32_16x16x32_bf16 v[38:41], v[152:155], v[244:247], v[38:41]
	v_mfma_f32_16x16x32_bf16 v[34:37], v[160:163], v[244:247], v[34:37]
	v_mfma_f32_16x16x32_bf16 v[30:33], v[166:169], v[182:185], v[30:33]
	v_mfma_f32_16x16x32_bf16 v[26:29], v[174:177], v[182:185], v[26:29]
	v_mfma_f32_16x16x32_bf16 v[22:25], v[166:169], v[210:213], v[22:25]
	v_mfma_f32_16x16x32_bf16 v[18:21], v[174:177], v[210:213], v[18:21]
	v_mfma_f32_16x16x32_bf16 v[14:17], v[166:169], v[218:221], v[14:17]
	v_mfma_f32_16x16x32_bf16 v[10:13], v[174:177], v[218:221], v[10:13]
	v_mfma_f32_16x16x32_bf16 v[6:9], v[166:169], v[240:243], v[6:9]
	v_mfma_f32_16x16x32_bf16 v[2:5], v[174:177], v[240:243], v[2:5]
	v_mfma_f32_16x16x32_bf16 v[30:33], v[170:173], v[206:209], v[30:33]
	v_mfma_f32_16x16x32_bf16 v[26:29], v[178:181], v[206:209], v[26:29]
	v_mfma_f32_16x16x32_bf16 v[22:25], v[170:173], v[214:217], v[22:25]
	v_mfma_f32_16x16x32_bf16 v[18:21], v[178:181], v[214:217], v[18:21]
	v_mfma_f32_16x16x32_bf16 v[14:17], v[170:173], v[236:239], v[14:17]
	v_mfma_f32_16x16x32_bf16 v[10:13], v[178:181], v[236:239], v[10:13]
	v_mfma_f32_16x16x32_bf16 v[6:9], v[170:173], v[244:247], v[6:9]
	v_mfma_f32_16x16x32_bf16 v[2:5], v[178:181], v[244:247], v[2:5]
	s_barrier
	s_add_i32 s8, s8, 2
	s_add_u32 s46, s46, 0x100
	s_addc_u32 s47, s47, 0
	s_cmp_gt_u32 s8, 29
	s_cbranch_scc0 .LBB0_170
	s_and_b64 vcc, exec, s[54:55]
	s_cbranch_vccz .LBB0_173
	s_barrier

; #define PG8_STAGE(bufoff, gbase, voff) do { _Pragma("unroll") for (int _i = 0; _i < 2; ++_i) \
;         __builtin_amdgcn_global_load_lds((const unsigned*)((const char*)(gbase) + (voff)[_i]), (PG8_LAS unsigned*)(lds + (bufoff) + ldsw + _i * 8192), 16, 0, 0); } while (0)
; #define PG8_LDA(dst, b, h) do { _Pragma("unroll") for (int m = 0; m < 4; ++m) _Pragma("unroll") for (int k = 0; k < 2; ++k) dst[m][k] = *(const PG8_LAS bf16x8*)(lds + PG8_SA(b, h) + aoff + m * 2048 + k * 1024); } while (0)
; #define PG8_LDB(dst, b, h) do { _Pragma("unroll") for (int n = 0; n < 2; ++n) _Pragma("unroll") for (int k = 0; k < 2; ++k) dst[n][k] = *(const PG8_LAS bf16x8*)(lds + PG8_SB(b, h) + boff + n * 2048 + k * 1024); } while (0)
; #define PG8_MMA(ai, bj, At, Bt) do { __builtin_amdgcn_s_setprio(1); _Pragma("unroll") for (int m = 0; m < 4; ++m) _Pragma("unroll") for (int n = 0; n < 2; ++n) _Pragma("unroll") for (int k = 0; k < 2; ++k) \
;         acc[ai][bj][m][n] = __builtin_amdgcn_mfma_f32_16x16x32_bf16(Bt[n][k], At[m][k], acc[ai][bj][m][n], 0, 0, 0); __builtin_amdgcn_s_setprio(0); } while (0)
; #define PG8_WAIT_V(n) asm volatile("s_waitcnt vmcnt(" #n ")" ::: "memory")
; #define PG8_WAIT_L(n) asm volatile("s_waitcnt lgkmcnt(" #n ")" ::: "memory")
; #define PG8_BAR __builtin_amdgcn_s_barrier()
; template <class Epi, class Sched, bool ALIGN_EPI = false, bool SP2 = false>
; __device__ __forceinline__ void gemm_phase(PG8_LAS unsigned char* lds, const Gemm g, const Sched& S, const Epi& E) {
;     ...
;             const char* a1 = cA + (size_t)(t + 1) * kstep;
;             const char* a2 = last ? nA : cA + (size_t)(t + 2) * kstep; const char* b2 = last ? nB : cB + (size_t)(t + 2) * kstep;
;             const char* a3 = a2 + kstep; const char* b3 = b2 + kstep;
;             if (last && has_next) S.a_ready(nxt);
;             if constexpr (SP2) {
;             PG8_LDB(B0, 0, 0); PG8_LDB(B1, 0, 1); PG8_SCHED; PG8_LDA(At, 0, 0); PG8_STAGE(PG8_SA(1, 1), a1 + hstep, voffA);
;             PG8_WAIT_V(8); PG8_WAIT_L(0); PG8_BAR; PG8_MMA(0, 0, At, B0); PG8_MMA(0, 1, At, B1); PG8_BAR; PG8_SCHED;
;             PG8_LDA(At, 0, 1); PG8_STAGE(PG8_SB(0, 0), b2, voffB); PG8_STAGE(PG8_SB(0, 1), b2 + hstepB, voffB); PG8_STAGE(PG8_SA(0, 0), a2, voffA);
;             PG8_WAIT_V(8); PG8_WAIT_L(0); PG8_BAR; PG8_MMA(1, 0, At, B0); PG8_MMA(1, 1, At, B1); PG8_BAR; PG8_SCHED;
.LBB0_788:
	s_add_u32 s9, s68, 0xfffe0080
	s_addc_u32 s10, s69, -1
	s_add_i32 s11, 0, 0x10000
	s_cmp_eq_u32 s8, 4
	s_cselect_b32 s77, s36, s10
	s_cselect_b32 s76, s37, s9
	s_cselect_b32 s73, s4, s7
	s_cselect_b32 s72, s5, s6
	s_add_i32 s9, 0, 0x14000
	ds_read_b128 v[34:37], v186
	ds_read_b128 v[38:41], v186 offset:1024
	ds_read_b128 v[50:53], v186 offset:2048
	ds_read_b128 v[54:57], v186 offset:3072
	ds_read_b128 v[114:117], v187
	ds_read_b128 v[126:129], v187 offset:1024
	ds_read_b128 v[138:141], v187 offset:2048
	ds_read_b128 v[150:153], v187 offset:3072
	s_add_i32 m0, s66, 0xc000
	ds_read_b128 v[154:157], v217
	ds_read_b128 v[158:161], v217 offset:1024
	ds_read_b128 v[170:173], v217 offset:2048
	ds_read_b128 v[206:209], v217 offset:3072
	ds_read_b128 v[210:213], v217 offset:4096
	ds_read_b128 v[218:221], v217 offset:5120
	ds_read_b128 v[236:239], v217 offset:6144
	ds_read_b128 v[240:243], v217 offset:7168
	global_load_lds_dwordx4 v180, s[68:69]
	s_add_i32 m0, s66, 0xe000
	s_nop 0
	global_load_lds_dwordx4 v182, s[68:69]
	s_waitcnt vmcnt(8)
	s_waitcnt lgkmcnt(0)
	s_barrier
	v_mfma_f32_16x16x32_bf16 v[166:169], v[34:37], v[154:157], v[166:169]
	v_mfma_f32_16x16x32_bf16 v[162:165], v[50:53], v[154:157], v[162:165]
	v_mfma_f32_16x16x32_bf16 v[134:137], v[34:37], v[170:173], v[134:137]
	v_mfma_f32_16x16x32_bf16 v[130:133], v[50:53], v[170:173], v[130:133]
	v_mfma_f32_16x16x32_bf16 v[110:113], v[34:37], v[210:213], v[110:113]
	v_mfma_f32_16x16x32_bf16 v[106:109], v[50:53], v[210:213], v[106:109]
	v_mfma_f32_16x16x32_bf16 v[94:97], v[34:37], v[236:239], v[94:97]
	v_mfma_f32_16x16x32_bf16 v[90:93], v[50:53], v[236:239], v[90:93]
	v_mfma_f32_16x16x32_bf16 v[166:169], v[38:41], v[158:161], v[166:169]
	v_mfma_f32_16x16x32_bf16 v[162:165], v[54:57], v[158:161], v[162:165]
	v_mfma_f32_16x16x32_bf16 v[134:137], v[38:41], v[206:209], v[134:137]
	v_mfma_f32_16x16x32_bf16 v[130:133], v[54:57], v[206:209], v[130:133]
	v_mfma_f32_16x16x32_bf16 v[110:113], v[38:41], v[218:221], v[110:113]
	v_mfma_f32_16x16x32_bf16 v[106:109], v[54:57], v[218:221], v[106:109]
	v_mfma_f32_16x16x32_bf16 v[94:97], v[38:41], v[240:243], v[94:97]
	v_mfma_f32_16x16x32_bf16 v[90:93], v[54:57], v[240:243], v[90:93]
	v_mfma_f32_16x16x32_bf16 v[146:149], v[114:117], v[154:157], v[146:149]
	v_mfma_f32_16x16x32_bf16 v[142:145], v[138:141], v[154:157], v[142:145]
	v_mfma_f32_16x16x32_bf16 v[122:125], v[114:117], v[170:173], v[122:125]
	v_mfma_f32_16x16x32_bf16 v[118:121], v[138:141], v[170:173], v[118:121]
	v_mfma_f32_16x16x32_bf16 v[102:105], v[114:117], v[210:213], v[102:105]
	v_mfma_f32_16x16x32_bf16 v[98:101], v[138:141], v[210:213], v[98:101]
	v_mfma_f32_16x16x32_bf16 v[86:89], v[114:117], v[236:239], v[86:89]
	v_mfma_f32_16x16x32_bf16 v[82:85], v[138:141], v[236:239], v[82:85]
	v_mfma_f32_16x16x32_bf16 v[146:149], v[126:129], v[158:161], v[146:149]
	v_mfma_f32_16x16x32_bf16 v[142:145], v[150:153], v[158:161], v[142:145]
	v_mfma_f32_16x16x32_bf16 v[122:125], v[126:129], v[206:209], v[122:125]
	v_mfma_f32_16x16x32_bf16 v[118:121], v[150:153], v[206:209], v[118:121]
	v_mfma_f32_16x16x32_bf16 v[102:105], v[126:129], v[218:221], v[102:105]
	v_mfma_f32_16x16x32_bf16 v[98:101], v[150:153], v[218:221], v[98:101]
	v_mfma_f32_16x16x32_bf16 v[86:89], v[126:129], v[240:243], v[86:89]
	v_mfma_f32_16x16x32_bf16 v[82:85], v[150:153], v[240:243], v[82:85]
	s_barrier
	s_add_i32 s10, s11, s25
	s_mov_b32 m0, s10
	ds_read_b128 v[154:157], v217 offset:16384
	ds_read_b128 v[158:161], v217 offset:17408
	ds_read_b128 v[170:173], v217 offset:18432
	ds_read_b128 v[206:209], v217 offset:19456
	ds_read_b128 v[210:213], v217 offset:20480
	ds_read_b128 v[218:221], v217 offset:21504
	ds_read_b128 v[236:239], v217 offset:22528
	ds_read_b128 v[240:243], v217 offset:23552
	global_load_lds_dwordx4 v190, s[72:73]
	s_add_i32 m0, s10, 0x2000
	s_add_u32 s10, s72, 0x8000
	s_addc_u32 s11, s73, 0
	s_add_i32 s9, s9, s25
	global_load_lds_dwordx4 v174, s[72:73]
	s_mov_b32 m0, s9
	s_nop 0
	global_load_lds_dwordx4 v190, s[10:11]
	s_add_i32 m0, s9, 0x2000
	s_nop 0
	global_load_lds_dwordx4 v174, s[10:11]
	s_mov_b32 m0, s66
	s_nop 0
	global_load_lds_dwordx4 v178, s[76:77]
	s_mov_b32 m0, s67
	s_nop 0
	global_load_lds_dwordx4 v176, s[76:77]
	s_nop 0
	s_waitcnt vmcnt(8)
	s_waitcnt lgkmcnt(0)
	s_barrier
	v_mfma_f32_16x16x32_bf16 v[78:81], v[34:37], v[154:157], v[78:81]
	v_mfma_f32_16x16x32_bf16 v[74:77], v[50:53], v[154:157], v[74:77]
	v_mfma_f32_16x16x32_bf16 v[62:65], v[34:37], v[170:173], v[62:65]
	v_mfma_f32_16x16x32_bf16 v[58:61], v[50:53], v[170:173], v[58:61]
	v_mfma_f32_16x16x32_bf16 v[30:33], v[34:37], v[210:213], v[30:33]
	v_mfma_f32_16x16x32_bf16 v[26:29], v[50:53], v[210:213], v[26:29]
	v_mfma_f32_16x16x32_bf16 v[14:17], v[34:37], v[236:239], v[14:17]
	v_mfma_f32_16x16x32_bf16 v[10:13], v[50:53], v[236:239], v[10:13]
	v_mfma_f32_16x16x32_bf16 v[78:81], v[38:41], v[158:161], v[78:81]
	v_mfma_f32_16x16x32_bf16 v[74:77], v[54:57], v[158:161], v[74:77]
	v_mfma_f32_16x16x32_bf16 v[62:65], v[38:41], v[206:209], v[62:65]
	v_mfma_f32_16x16x32_bf16 v[58:61], v[54:57], v[206:209], v[58:61]
	v_mfma_f32_16x16x32_bf16 v[30:33], v[38:41], v[218:221], v[30:33]
	v_mfma_f32_16x16x32_bf16 v[26:29], v[54:57], v[218:221], v[26:29]
	v_mfma_f32_16x16x32_bf16 v[14:17], v[38:41], v[240:243], v[14:17]
	v_mfma_f32_16x16x32_bf16 v[10:13], v[54:57], v[240:243], v[10:13]
	v_mfma_f32_16x16x32_bf16 v[46:49], v[114:117], v[170:173], v[46:49]
	v_mfma_f32_16x16x32_bf16 v[42:45], v[138:141], v[170:173], v[42:45]
	v_mfma_f32_16x16x32_bf16 v[22:25], v[114:117], v[210:213], v[22:25]
	v_mfma_f32_16x16x32_bf16 v[18:21], v[138:141], v[210:213], v[18:21]
	v_mfma_f32_16x16x32_bf16 v[6:9], v[114:117], v[236:239], v[6:9]
	v_mfma_f32_16x16x32_bf16 v[2:5], v[138:141], v[236:239], v[2:5]
	v_mfma_f32_16x16x32_bf16 v[34:37], v[114:117], v[154:157], v[70:73]
	v_mfma_f32_16x16x32_bf16 v[38:41], v[138:141], v[154:157], v[66:69]
	v_mfma_f32_16x16x32_bf16 v[46:49], v[126:129], v[206:209], v[46:49]
	v_mfma_f32_16x16x32_bf16 v[42:45], v[150:153], v[206:209], v[42:45]
	v_mfma_f32_16x16x32_bf16 v[22:25], v[126:129], v[218:221], v[22:25]
	v_mfma_f32_16x16x32_bf16 v[18:21], v[150:153], v[218:221], v[18:21]
	v_mfma_f32_16x16x32_bf16 v[6:9], v[126:129], v[240:243], v[6:9]
	v_mfma_f32_16x16x32_bf16 v[2:5], v[150:153], v[240:243], v[2:5]
	v_mfma_f32_16x16x32_bf16 v[34:37], v[126:129], v[158:161], v[34:37]
	v_mfma_f32_16x16x32_bf16 v[38:41], v[150:153], v[158:161], v[38:41]
	s_barrier
; #define PG8_STAGE(bufoff, gbase, voff) do { _Pragma("unroll") for (int _i = 0; _i < 2; ++_i) \
;         __builtin_amdgcn_global_load_lds((const unsigned*)((const char*)(gbase) + (voff)[_i]), (PG8_LAS unsigned*)(lds + (bufoff) + ldsw + _i * 8192), 16, 0, 0); } while (0)
; #define PG8_LDA(dst, b, h) do { _Pragma("unroll") for (int m = 0; m < 4; ++m) _Pragma("unroll") for (int k = 0; k < 2; ++k) dst[m][k] = *(const PG8_LAS bf16x8*)(lds + PG8_SA(b, h) + aoff + m * 2048 + k * 1024); } while (0)
; #define PG8_LDB(dst, b, h) do { _Pragma("unroll") for (int n = 0; n < 2; ++n) _Pragma("unroll") for (int k = 0; k < 2; ++k) dst[n][k] = *(const PG8_LAS bf16x8*)(lds + PG8_SB(b, h) + boff + n * 2048 + k * 1024); } while (0)
; #define PG8_MMA(ai, bj, At, Bt) do { __builtin_amdgcn_s_setprio(1); _Pragma("unroll") for (int m = 0; m < 4; ++m) _Pragma("unroll") for (int n = 0; n < 2; ++n) _Pragma("unroll") for (int k = 0; k < 2; ++k) \
;         acc[ai][bj][m][n] = __builtin_amdgcn_mfma_f32_16x16x32_bf16(Bt[n][k], At[m][k], acc[ai][bj][m][n], 0, 0, 0); __builtin_amdgcn_s_setprio(0); } while (0)
; #define PG8_WAIT_V(n) asm volatile("s_waitcnt vmcnt(" #n ")" ::: "memory")
; #define PG8_WAIT_L(n) asm volatile("s_waitcnt lgkmcnt(" #n ")" ::: "memory")
; #define PG8_BAR __builtin_amdgcn_s_barrier()
; #define PG8_SCHED __builtin_amdgcn_sched_barrier(0)
; template <class Epi, class Sched, bool ALIGN_EPI = false, bool SP2 = false>
; __device__ __forceinline__ void gemm_phase(PG8_LAS unsigned char* lds, const Gemm g, const Sched& S, const Epi& E) {
;     ...
;             PG8_LDB(B0, 1, 0); PG8_LDB(B1, 1, 1); PG8_SCHED; PG8_LDA(At, 1, 0); PG8_STAGE(PG8_SA(0, 1), a2 + hstep, voffA);
;             PG8_WAIT_V(8); PG8_WAIT_L(0); PG8_BAR; PG8_MMA(0, 0, At, B0); PG8_MMA(0, 1, At, B1); PG8_BAR; PG8_SCHED;
;             PG8_LDA(At, 1, 1); PG8_STAGE(PG8_SB(1, 0), b3, voffB); PG8_STAGE(PG8_SB(1, 1), b3 + hstepB, voffB); PG8_STAGE(PG8_SA(1, 0), a3, voffA);
;             PG8_WAIT_V(8); PG8_WAIT_L(0); PG8_BAR; PG8_MMA(1, 0, At, B0); PG8_MMA(1, 1, At, B1); PG8_BAR; PG8_SCHED;
	s_add_i32 s9, 0, 0x18000
	s_add_i32 s12, 0, 0x1c000
	ds_read_b128 v[50:53], v198
	ds_read_b128 v[54:57], v198 offset:1024
	ds_read_b128 v[66:69], v198 offset:2048
	ds_read_b128 v[70:73], v198 offset:3072
	ds_read_b128 v[114:117], v199
	ds_read_b128 v[126:129], v199 offset:1024
	ds_read_b128 v[138:141], v199 offset:2048
	ds_read_b128 v[150:153], v199 offset:3072
	s_add_u32 s10, s76, 0x20000
	s_addc_u32 s11, s77, 0
	s_mov_b32 m0, s80
	ds_read_b128 v[154:157], v217 offset:32768
	ds_read_b128 v[158:161], v217 offset:33792
	ds_read_b128 v[170:173], v217 offset:34816
	ds_read_b128 v[206:209], v217 offset:35840
	ds_read_b128 v[210:213], v217 offset:36864
	ds_read_b128 v[218:221], v217 offset:37888
	ds_read_b128 v[236:239], v217 offset:38912
	ds_read_b128 v[240:243], v217 offset:39936
	global_load_lds_dwordx4 v178, s[10:11]
	s_mov_b32 m0, s81
	s_nop 0
	global_load_lds_dwordx4 v176, s[10:11]
	s_waitcnt vmcnt(8)
	s_waitcnt lgkmcnt(0)
	s_barrier
	v_mfma_f32_16x16x32_bf16 v[166:169], v[50:53], v[154:157], v[166:169]
	v_mfma_f32_16x16x32_bf16 v[162:165], v[66:69], v[154:157], v[162:165]
	v_mfma_f32_16x16x32_bf16 v[134:137], v[50:53], v[170:173], v[134:137]
	v_mfma_f32_16x16x32_bf16 v[130:133], v[66:69], v[170:173], v[130:133]
	v_mfma_f32_16x16x32_bf16 v[110:113], v[50:53], v[210:213], v[110:113]
	v_mfma_f32_16x16x32_bf16 v[106:109], v[66:69], v[210:213], v[106:109]
	v_mfma_f32_16x16x32_bf16 v[94:97], v[50:53], v[236:239], v[94:97]
	v_mfma_f32_16x16x32_bf16 v[90:93], v[66:69], v[236:239], v[90:93]
	v_mfma_f32_16x16x32_bf16 v[166:169], v[54:57], v[158:161], v[166:169]
	v_mfma_f32_16x16x32_bf16 v[162:165], v[70:73], v[158:161], v[162:165]
	v_mfma_f32_16x16x32_bf16 v[134:137], v[54:57], v[206:209], v[134:137]
	v_mfma_f32_16x16x32_bf16 v[130:133], v[70:73], v[206:209], v[130:133]
	v_mfma_f32_16x16x32_bf16 v[110:113], v[54:57], v[218:221], v[110:113]
	v_mfma_f32_16x16x32_bf16 v[106:109], v[70:73], v[218:221], v[106:109]
	v_mfma_f32_16x16x32_bf16 v[94:97], v[54:57], v[240:243], v[94:97]
	v_mfma_f32_16x16x32_bf16 v[90:93], v[70:73], v[240:243], v[90:93]
	v_mfma_f32_16x16x32_bf16 v[146:149], v[114:117], v[154:157], v[146:149]
	v_mfma_f32_16x16x32_bf16 v[142:145], v[138:141], v[154:157], v[142:145]
	v_mfma_f32_16x16x32_bf16 v[122:125], v[114:117], v[170:173], v[122:125]
	v_mfma_f32_16x16x32_bf16 v[118:121], v[138:141], v[170:173], v[118:121]
	v_mfma_f32_16x16x32_bf16 v[102:105], v[114:117], v[210:213], v[102:105]
	v_mfma_f32_16x16x32_bf16 v[98:101], v[138:141], v[210:213], v[98:101]
	v_mfma_f32_16x16x32_bf16 v[86:89], v[114:117], v[236:239], v[86:89]
	v_mfma_f32_16x16x32_bf16 v[82:85], v[138:141], v[236:239], v[82:85]
	v_mfma_f32_16x16x32_bf16 v[146:149], v[126:129], v[158:161], v[146:149]
	v_mfma_f32_16x16x32_bf16 v[142:145], v[150:153], v[158:161], v[142:145]
	v_mfma_f32_16x16x32_bf16 v[122:125], v[126:129], v[206:209], v[122:125]
	v_mfma_f32_16x16x32_bf16 v[118:121], v[150:153], v[206:209], v[118:121]
	v_mfma_f32_16x16x32_bf16 v[102:105], v[126:129], v[218:221], v[102:105]
	v_mfma_f32_16x16x32_bf16 v[98:101], v[150:153], v[218:221], v[98:101]
	v_mfma_f32_16x16x32_bf16 v[86:89], v[126:129], v[240:243], v[86:89]
	v_mfma_f32_16x16x32_bf16 v[82:85], v[150:153], v[240:243], v[82:85]
	s_barrier
	s_add_i32 s9, s9, s25
	s_mov_b32 m0, s9
	ds_read_b128 v[154:157], v217 offset:49152
	ds_read_b128 v[158:161], v217 offset:50176
	ds_read_b128 v[170:173], v217 offset:51200
	ds_read_b128 v[206:209], v217 offset:52224
	ds_read_b128 v[210:213], v217 offset:53248
	ds_read_b128 v[218:221], v217 offset:54272
	ds_read_b128 v[236:239], v217 offset:55296
	ds_read_b128 v[240:243], v217 offset:56320
	s_add_u32 s100, s72, s60
	s_addc_u32 s101, s73, s61
	global_load_lds_dwordx4 v190, s[100:101]
	s_add_i32 m0, s9, 0x2000
	s_add_u32 s10, s72, 0x8080
	s_addc_u32 s11, s73, 0
	s_add_i32 s9, s12, s25
	global_load_lds_dwordx4 v174, s[100:101]
	s_mov_b32 m0, s9
	s_nop 0
	global_load_lds_dwordx4 v190, s[10:11]
	s_add_i32 m0, s9, 0x2000
	s_nop 0
	global_load_lds_dwordx4 v174, s[10:11]
	s_mov_b32 m0, s82
	s_add_u32 s100, s76, s60
	s_addc_u32 s101, s77, s61
	global_load_lds_dwordx4 v178, s[100:101]
	s_mov_b32 m0, s92
	s_nop 0
	global_load_lds_dwordx4 v176, s[100:101]
	s_waitcnt vmcnt(8)
	s_waitcnt lgkmcnt(0)
	s_barrier
	v_mfma_f32_16x16x32_bf16 v[78:81], v[50:53], v[154:157], v[78:81]
	v_mfma_f32_16x16x32_bf16 v[74:77], v[66:69], v[154:157], v[74:77]
	v_mfma_f32_16x16x32_bf16 v[62:65], v[50:53], v[170:173], v[62:65]
	v_mfma_f32_16x16x32_bf16 v[58:61], v[66:69], v[170:173], v[58:61]
	v_mfma_f32_16x16x32_bf16 v[30:33], v[50:53], v[210:213], v[30:33]
	v_mfma_f32_16x16x32_bf16 v[26:29], v[66:69], v[210:213], v[26:29]
	v_mfma_f32_16x16x32_bf16 v[14:17], v[50:53], v[236:239], v[14:17]
	v_mfma_f32_16x16x32_bf16 v[10:13], v[66:69], v[236:239], v[10:13]
	v_mfma_f32_16x16x32_bf16 v[78:81], v[54:57], v[158:161], v[78:81]
	v_mfma_f32_16x16x32_bf16 v[74:77], v[70:73], v[158:161], v[74:77]
	v_mfma_f32_16x16x32_bf16 v[62:65], v[54:57], v[206:209], v[62:65]
	v_mfma_f32_16x16x32_bf16 v[58:61], v[70:73], v[206:209], v[58:61]
	v_mfma_f32_16x16x32_bf16 v[30:33], v[54:57], v[218:221], v[30:33]
	v_mfma_f32_16x16x32_bf16 v[26:29], v[70:73], v[218:221], v[26:29]
	v_mfma_f32_16x16x32_bf16 v[14:17], v[54:57], v[240:243], v[14:17]
	v_mfma_f32_16x16x32_bf16 v[10:13], v[70:73], v[240:243], v[10:13]
	v_mfma_f32_16x16x32_bf16 v[34:37], v[114:117], v[154:157], v[34:37]
	v_mfma_f32_16x16x32_bf16 v[70:73], v[126:129], v[158:161], v[34:37]
	v_mfma_f32_16x16x32_bf16 v[34:37], v[138:141], v[154:157], v[38:41]
	v_mfma_f32_16x16x32_bf16 v[66:69], v[150:153], v[158:161], v[34:37]
	v_mfma_f32_16x16x32_bf16 v[34:37], v[114:117], v[170:173], v[46:49]
	v_mfma_f32_16x16x32_bf16 v[46:49], v[126:129], v[206:209], v[34:37]
	v_mfma_f32_16x16x32_bf16 v[34:37], v[138:141], v[170:173], v[42:45]
	v_mfma_f32_16x16x32_bf16 v[22:25], v[114:117], v[210:213], v[22:25]
	v_mfma_f32_16x16x32_bf16 v[18:21], v[138:141], v[210:213], v[18:21]
	v_mfma_f32_16x16x32_bf16 v[6:9], v[114:117], v[236:239], v[6:9]
	v_mfma_f32_16x16x32_bf16 v[2:5], v[138:141], v[236:239], v[2:5]
	v_mfma_f32_16x16x32_bf16 v[42:45], v[150:153], v[206:209], v[34:37]
	v_mfma_f32_16x16x32_bf16 v[22:25], v[126:129], v[218:221], v[22:25]
	v_mfma_f32_16x16x32_bf16 v[18:21], v[150:153], v[218:221], v[18:21]
	v_mfma_f32_16x16x32_bf16 v[6:9], v[126:129], v[240:243], v[6:9]
	v_mfma_f32_16x16x32_bf16 v[2:5], v[150:153], v[240:243], v[2:5]
	s_barrier
	s_add_i32 s8, s8, 2
	s_add_u32 s68, s68, 0x100
	s_addc_u32 s69, s69, 0
	s_add_u32 s6, s6, 0x100
	s_addc_u32 s7, s7, 0
	s_cmp_gt_u32 s8, 5
	s_cbranch_scc0 .LBB0_788
	s_and_b64 vcc, exec, s[46:47]
	s_cbranch_vccz .LBB0_791
	s_barrier

; #define PG8_STAGE(bufoff, gbase, voff) do { _Pragma("unroll") for (int _i = 0; _i < 2; ++_i) \
;         __builtin_amdgcn_global_load_lds((const unsigned*)((const char*)(gbase) + (voff)[_i]), (PG8_LAS unsigned*)(lds + (bufoff) + ldsw + _i * 8192), 16, 0, 0); } while (0)
; #define PG8_LDA(dst, b, h) do { _Pragma("unroll") for (int m = 0; m < 4; ++m) _Pragma("unroll") for (int k = 0; k < 2; ++k) dst[m][k] = *(const PG8_LAS bf16x8*)(lds + PG8_SA(b, h) + aoff + m * 2048 + k * 1024); } while (0)
; #define PG8_LDB(dst, b, h) do { _Pragma("unroll") for (int n = 0; n < 2; ++n) _Pragma("unroll") for (int k = 0; k < 2; ++k) dst[n][k] = *(const PG8_LAS bf16x8*)(lds + PG8_SB(b, h) + boff + n * 2048 + k * 1024); } while (0)
; #define PG8_WAIT_V(n) asm volatile("s_waitcnt vmcnt(" #n ")" ::: "memory")
; #define PG8_WAIT_L(n) asm volatile("s_waitcnt lgkmcnt(" #n ")" ::: "memory")
; #define PG8_BAR __builtin_amdgcn_s_barrier()
; #define PG8_SCHED __builtin_amdgcn_sched_barrier(0)
; template <class Epi, class Sched, bool ALIGN_EPI = false, bool SP2 = false>
; __device__ __forceinline__ void gemm_phase(PG8_LAS unsigned char* lds, const Gemm g, const Sched& S, const Epi& E) {
;     ...
;         const bool has_next = S.next(ui + 1, nxt);
;         const char* nA = has_next ? (const char*)g.A + (size_t)nxt.pm * tstep : cA; const char* nB = has_next ? (const char*)g.Bt + (size_t)nxt.pn * tstep : cB;
;         for (int t = 0; t < nt; t += 2) {
;             const bool last = (t == nt - 2);
;             const char* a1 = cA + (size_t)(t + 1) * kstep;
;             const char* a2 = last ? nA : cA + (size_t)(t + 2) * kstep; const char* b2 = last ? nB : cB + (size_t)(t + 2) * kstep;
;             const char* a3 = a2 + kstep; const char* b3 = b2 + kstep;
;             if (last && has_next) S.a_ready(nxt);
;             if constexpr (SP2) {
;             PG8_LDB(B0, 0, 0); PG8_LDB(B1, 0, 1); PG8_SCHED; PG8_LDA(At, 0, 0); PG8_STAGE(PG8_SA(1, 1), a1 + hstep, voffA);
;             PG8_WAIT_V(8); PG8_WAIT_L(0); PG8_BAR; PG8_MMA(0, 0, At, B0); PG8_MMA(0, 1, At, B1); PG8_BAR; PG8_SCHED;
;             PG8_LDA(At, 0, 1); PG8_STAGE(PG8_SB(0, 0), b2, voffB); PG8_STAGE(PG8_SB(0, 1), b2 + hstepB, voffB); PG8_STAGE(PG8_SA(0, 0), a2, voffA);
;             PG8_WAIT_V(8); PG8_WAIT_L(0); PG8_BAR; PG8_MMA(1, 0, At, B0); PG8_MMA(1, 1, At, B1); PG8_BAR; PG8_SCHED;
.LBB0_926:
	s_ashr_i32 s73, s72, 31
	s_lshl_b64 s[4:5], s[72:73], 20
	v_readlane_b32 s6, v249, 9
	v_readlane_b32 s7, v249, 10
	s_add_u32 s76, s6, s4
	s_addc_u32 s77, s7, s5
	s_and_b64 s[4:5], s[92:93], exec
	s_cselect_b32 s36, s77, s39
	s_cselect_b32 s37, s76, s38
	s_ashr_i32 s69, s68, 31
	s_lshl_b64 s[4:5], s[68:69], 20
	v_readlane_b32 s6, v249, 17
	v_readlane_b32 s7, v249, 18
	s_add_u32 s80, s6, s4
	s_addc_u32 s81, s7, s5
	s_and_b64 s[4:5], s[92:93], exec
	s_cselect_b32 s4, s81, s47
	s_cselect_b32 s5, s80, s46
	s_add_u32 s38, s38, 0x80080
	s_addc_u32 s39, s39, 0
	s_add_u32 s6, s46, 0x100
	v_mov_b32_e32 v2, 0
	s_addc_u32 s7, s47, 0
	s_mov_b32 s8, -2
	v_mov_b32_e32 v3, v2
	v_mov_b32_e32 v4, v2
	v_mov_b32_e32 v5, v2
	v_mov_b32_e32 v6, v2
	v_mov_b32_e32 v7, v2
	v_mov_b32_e32 v8, v2
	v_mov_b32_e32 v9, v2
	v_mov_b32_e32 v18, v2
	v_mov_b32_e32 v19, v2
	v_mov_b32_e32 v20, v2
	v_mov_b32_e32 v21, v2
	v_mov_b32_e32 v22, v2
	v_mov_b32_e32 v23, v2
	v_mov_b32_e32 v24, v2
	v_mov_b32_e32 v25, v2
	v_mov_b32_e32 v34, v2
	s_waitcnt lgkmcnt(0)
	v_add_u32_e32 v186, 0x10000, v193
	v_add_u32_e32 v187, 0x14000, v193
	v_add_u32_e32 v198, 0x18000, v193
	v_add_u32_e32 v199, 0x1c000, v193
	s_add_u32 s9, s38, 0xfff80080
	s_addc_u32 s10, s39, -1
	s_add_i32 s11, 0, 0x10000
	s_cmp_eq_u32 s8, 28
	s_cselect_b32 s95, s36, s10
	s_cselect_b32 s94, s37, s9
	s_cselect_b32 s47, s4, s7
	s_cselect_b32 s46, s5, s6
	s_add_i32 s9, 0, 0x14000
	ds_read_b128 v[66:69], v186
	ds_read_b128 v[70:73], v186 offset:1024
	ds_read_b128 v[78:81], v186 offset:2048
	ds_read_b128 v[86:89], v186 offset:3072
	ds_read_b128 v[146:149], v187
	ds_read_b128 v[150:153], v187 offset:1024
	ds_read_b128 v[154:157], v187 offset:2048
	ds_read_b128 v[158:161], v187 offset:3072
	s_add_i32 m0, s66, 0xc000
	ds_read_b128 v[162:165], v236
	ds_read_b128 v[166:169], v236 offset:1024
	ds_read_b128 v[170:173], v236 offset:2048
	ds_read_b128 v[174:177], v236 offset:3072
	ds_read_b128 v[178:181], v236 offset:4096
	ds_read_b128 v[182:185], v236 offset:5120
	ds_read_b128 v[216:219], v236 offset:6144
	ds_read_b128 v[220:223], v236 offset:7168
	global_load_lds_dwordx4 v212, s[38:39]
	s_add_i32 m0, s66, 0xe000
	s_nop 0
	global_load_lds_dwordx4 v214, s[38:39]
	s_nop 0
	s_waitcnt vmcnt(8)
	s_waitcnt lgkmcnt(0)
	s_barrier
	v_mfma_f32_16x16x32_bf16 v[142:145], v[66:69], v[162:165], 0
	v_mfma_f32_16x16x32_bf16 v[138:141], v[78:81], v[162:165], 0
	v_mfma_f32_16x16x32_bf16 v[126:129], v[66:69], v[170:173], 0
	v_mfma_f32_16x16x32_bf16 v[122:125], v[78:81], v[170:173], 0
	v_mfma_f32_16x16x32_bf16 v[110:113], v[66:69], v[178:181], 0
	v_mfma_f32_16x16x32_bf16 v[106:109], v[78:81], v[178:181], 0
	v_mfma_f32_16x16x32_bf16 v[94:97], v[66:69], v[216:219], 0
	v_mfma_f32_16x16x32_bf16 v[90:93], v[78:81], v[216:219], 0
	v_mfma_f32_16x16x32_bf16 v[142:145], v[70:73], v[166:169], v[142:145]
	v_mfma_f32_16x16x32_bf16 v[138:141], v[86:89], v[166:169], v[138:141]
	v_mfma_f32_16x16x32_bf16 v[126:129], v[70:73], v[174:177], v[126:129]
	v_mfma_f32_16x16x32_bf16 v[122:125], v[86:89], v[174:177], v[122:125]
	v_mfma_f32_16x16x32_bf16 v[110:113], v[70:73], v[182:185], v[110:113]
	v_mfma_f32_16x16x32_bf16 v[106:109], v[86:89], v[182:185], v[106:109]
	v_mfma_f32_16x16x32_bf16 v[94:97], v[70:73], v[220:223], v[94:97]
	v_mfma_f32_16x16x32_bf16 v[90:93], v[86:89], v[220:223], v[90:93]
	v_mfma_f32_16x16x32_bf16 v[134:137], v[146:149], v[162:165], 0
	v_mfma_f32_16x16x32_bf16 v[130:133], v[154:157], v[162:165], 0
	v_mfma_f32_16x16x32_bf16 v[118:121], v[146:149], v[170:173], 0
	v_mfma_f32_16x16x32_bf16 v[114:117], v[154:157], v[170:173], 0
	v_mfma_f32_16x16x32_bf16 v[102:105], v[146:149], v[178:181], 0
	v_mfma_f32_16x16x32_bf16 v[98:101], v[154:157], v[178:181], 0
	v_mfma_f32_16x16x32_bf16 v[82:85], v[146:149], v[216:219], 0
	v_mfma_f32_16x16x32_bf16 v[74:77], v[154:157], v[216:219], 0
	v_mfma_f32_16x16x32_bf16 v[134:137], v[150:153], v[166:169], v[134:137]
	v_mfma_f32_16x16x32_bf16 v[130:133], v[158:161], v[166:169], v[130:133]
	v_mfma_f32_16x16x32_bf16 v[118:121], v[150:153], v[174:177], v[118:121]
	v_mfma_f32_16x16x32_bf16 v[114:117], v[158:161], v[174:177], v[114:117]
	v_mfma_f32_16x16x32_bf16 v[102:105], v[150:153], v[182:185], v[102:105]
	v_mfma_f32_16x16x32_bf16 v[98:101], v[158:161], v[182:185], v[98:101]
	v_mfma_f32_16x16x32_bf16 v[82:85], v[150:153], v[220:223], v[82:85]
	v_mfma_f32_16x16x32_bf16 v[74:77], v[158:161], v[220:223], v[74:77]
	s_barrier
	s_add_i32 s10, s11, s25
	s_mov_b32 m0, s10
	ds_read_b128 v[162:165], v236 offset:16384
	ds_read_b128 v[166:169], v236 offset:17408
	ds_read_b128 v[170:173], v236 offset:18432
	ds_read_b128 v[174:177], v236 offset:19456
	ds_read_b128 v[178:181], v236 offset:20480
	ds_read_b128 v[182:185], v236 offset:21504
	ds_read_b128 v[216:219], v236 offset:22528
	ds_read_b128 v[220:223], v236 offset:23552
	global_load_lds_dwordx4 v190, s[46:47]
	s_add_i32 m0, s10, 0x2000
	s_add_u32 s10, s46, 0x20000
	s_addc_u32 s11, s47, 0
	s_add_i32 s9, s9, s25
	global_load_lds_dwordx4 v206, s[46:47]
	s_mov_b32 m0, s9
	s_nop 0
	global_load_lds_dwordx4 v190, s[10:11]
	s_add_i32 m0, s9, 0x2000
	s_nop 0
	global_load_lds_dwordx4 v206, s[10:11]
	s_mov_b32 m0, s66
	s_nop 0
	global_load_lds_dwordx4 v210, s[94:95]
	s_mov_b32 m0, s67
	s_nop 0
	global_load_lds_dwordx4 v208, s[94:95]
	s_nop 0
	s_waitcnt vmcnt(8)
	s_waitcnt lgkmcnt(0)
	s_barrier
; #define PG8_STAGE(bufoff, gbase, voff) do { _Pragma("unroll") for (int _i = 0; _i < 2; ++_i) \
;         __builtin_amdgcn_global_load_lds((const unsigned*)((const char*)(gbase) + (voff)[_i]), (PG8_LAS unsigned*)(lds + (bufoff) + ldsw + _i * 8192), 16, 0, 0); } while (0)
; #define PG8_LDA(dst, b, h) do { _Pragma("unroll") for (int m = 0; m < 4; ++m) _Pragma("unroll") for (int k = 0; k < 2; ++k) dst[m][k] = *(const PG8_LAS bf16x8*)(lds + PG8_SA(b, h) + aoff + m * 2048 + k * 1024); } while (0)
; #define PG8_LDB(dst, b, h) do { _Pragma("unroll") for (int n = 0; n < 2; ++n) _Pragma("unroll") for (int k = 0; k < 2; ++k) dst[n][k] = *(const PG8_LAS bf16x8*)(lds + PG8_SB(b, h) + boff + n * 2048 + k * 1024); } while (0)
; #define PG8_MMA(ai, bj, At, Bt) do { __builtin_amdgcn_s_setprio(1); _Pragma("unroll") for (int m = 0; m < 4; ++m) _Pragma("unroll") for (int n = 0; n < 2; ++n) _Pragma("unroll") for (int k = 0; k < 2; ++k) \
;         acc[ai][bj][m][n] = __builtin_amdgcn_mfma_f32_16x16x32_bf16(Bt[n][k], At[m][k], acc[ai][bj][m][n], 0, 0, 0); __builtin_amdgcn_s_setprio(0); } while (0)
; #define PG8_WAIT_V(n) asm volatile("s_waitcnt vmcnt(" #n ")" ::: "memory")
; #define PG8_WAIT_L(n) asm volatile("s_waitcnt lgkmcnt(" #n ")" ::: "memory")
; #define PG8_BAR __builtin_amdgcn_s_barrier()
; #define PG8_SCHED __builtin_amdgcn_sched_barrier(0)
; template <class Epi, class Sched, bool ALIGN_EPI = false, bool SP2 = false>
; __device__ __forceinline__ void gemm_phase(PG8_LAS unsigned char* lds, const Gemm g, const Sched& S, const Epi& E) {
;     ...
;             PG8_WAIT_V(8); PG8_WAIT_L(0); PG8_BAR; PG8_MMA(1, 0, At, B0); PG8_MMA(1, 1, At, B1); PG8_BAR; PG8_SCHED;
;             PG8_LDB(B0, 1, 0); PG8_LDB(B1, 1, 1); PG8_SCHED; PG8_LDA(At, 1, 0); PG8_STAGE(PG8_SA(0, 1), a2 + hstep, voffA);
;             PG8_WAIT_V(8); PG8_WAIT_L(0); PG8_BAR; PG8_MMA(0, 0, At, B0); PG8_MMA(0, 1, At, B1); PG8_BAR; PG8_SCHED;
	v_mfma_f32_16x16x32_bf16 v[62:65], v[66:69], v[162:165], 0
	v_mfma_f32_16x16x32_bf16 v[58:61], v[78:81], v[162:165], 0
	v_mfma_f32_16x16x32_bf16 v[46:49], v[66:69], v[170:173], 0
	v_mfma_f32_16x16x32_bf16 v[42:45], v[78:81], v[170:173], 0
	v_mfma_f32_16x16x32_bf16 v[30:33], v[66:69], v[178:181], 0
	v_mfma_f32_16x16x32_bf16 v[26:29], v[78:81], v[178:181], 0
	v_mfma_f32_16x16x32_bf16 v[14:17], v[66:69], v[216:219], 0
	v_mfma_f32_16x16x32_bf16 v[10:13], v[78:81], v[216:219], 0
	v_mfma_f32_16x16x32_bf16 v[62:65], v[70:73], v[166:169], v[62:65]
	v_mfma_f32_16x16x32_bf16 v[58:61], v[86:89], v[166:169], v[58:61]
	v_mfma_f32_16x16x32_bf16 v[46:49], v[70:73], v[174:177], v[46:49]
	v_mfma_f32_16x16x32_bf16 v[42:45], v[86:89], v[174:177], v[42:45]
	v_mfma_f32_16x16x32_bf16 v[30:33], v[70:73], v[182:185], v[30:33]
	v_mfma_f32_16x16x32_bf16 v[26:29], v[86:89], v[182:185], v[26:29]
	v_mfma_f32_16x16x32_bf16 v[14:17], v[70:73], v[220:223], v[14:17]
	v_mfma_f32_16x16x32_bf16 v[10:13], v[86:89], v[220:223], v[10:13]
	v_mfma_f32_16x16x32_bf16 v[54:57], v[146:149], v[162:165], 0
	v_mfma_f32_16x16x32_bf16 v[50:53], v[154:157], v[162:165], 0
	v_mfma_f32_16x16x32_bf16 v[38:41], v[146:149], v[170:173], 0
	v_mfma_f32_16x16x32_bf16 v[34:37], v[154:157], v[170:173], 0
	v_mfma_f32_16x16x32_bf16 v[22:25], v[146:149], v[178:181], 0
	v_mfma_f32_16x16x32_bf16 v[18:21], v[154:157], v[178:181], 0
	v_mfma_f32_16x16x32_bf16 v[6:9], v[146:149], v[216:219], 0
	v_mfma_f32_16x16x32_bf16 v[2:5], v[154:157], v[216:219], 0
	v_mfma_f32_16x16x32_bf16 v[54:57], v[150:153], v[166:169], v[54:57]
	v_mfma_f32_16x16x32_bf16 v[50:53], v[158:161], v[166:169], v[50:53]
	v_mfma_f32_16x16x32_bf16 v[38:41], v[150:153], v[174:177], v[38:41]
	v_mfma_f32_16x16x32_bf16 v[34:37], v[158:161], v[174:177], v[34:37]
	v_mfma_f32_16x16x32_bf16 v[22:25], v[150:153], v[182:185], v[22:25]
	v_mfma_f32_16x16x32_bf16 v[18:21], v[158:161], v[182:185], v[18:21]
	v_mfma_f32_16x16x32_bf16 v[6:9], v[150:153], v[220:223], v[6:9]
	v_mfma_f32_16x16x32_bf16 v[2:5], v[158:161], v[220:223], v[2:5]
	s_barrier
	s_add_i32 s9, 0, 0x18000
	s_add_i32 s12, 0, 0x1c000
	ds_read_b128 v[66:69], v198
	ds_read_b128 v[70:73], v198 offset:1024
	ds_read_b128 v[78:81], v198 offset:2048
	ds_read_b128 v[86:89], v198 offset:3072
	ds_read_b128 v[146:149], v199
	ds_read_b128 v[150:153], v199 offset:1024
	ds_read_b128 v[154:157], v199 offset:2048
	ds_read_b128 v[158:161], v199 offset:3072
	s_add_u32 s10, s94, 0x80000
	s_addc_u32 s11, s95, 0
	s_mov_b32 m0, s59
	ds_read_b128 v[162:165], v236 offset:32768
	ds_read_b128 v[166:169], v236 offset:33792
	ds_read_b128 v[170:173], v236 offset:34816
	ds_read_b128 v[174:177], v236 offset:35840
	ds_read_b128 v[178:181], v236 offset:36864
	ds_read_b128 v[182:185], v236 offset:37888
	ds_read_b128 v[216:219], v236 offset:38912
	ds_read_b128 v[220:223], v236 offset:39936
	global_load_lds_dwordx4 v210, s[10:11]
	s_mov_b32 m0, s74
	s_nop 0
	global_load_lds_dwordx4 v208, s[10:11]
	s_waitcnt vmcnt(8)
	s_waitcnt lgkmcnt(0)
	s_barrier
	v_mfma_f32_16x16x32_bf16 v[142:145], v[66:69], v[162:165], v[142:145]
	v_mfma_f32_16x16x32_bf16 v[138:141], v[78:81], v[162:165], v[138:141]
	v_mfma_f32_16x16x32_bf16 v[126:129], v[66:69], v[170:173], v[126:129]
	v_mfma_f32_16x16x32_bf16 v[122:125], v[78:81], v[170:173], v[122:125]
	v_mfma_f32_16x16x32_bf16 v[110:113], v[66:69], v[178:181], v[110:113]
	v_mfma_f32_16x16x32_bf16 v[106:109], v[78:81], v[178:181], v[106:109]
	v_mfma_f32_16x16x32_bf16 v[94:97], v[66:69], v[216:219], v[94:97]
	v_mfma_f32_16x16x32_bf16 v[90:93], v[78:81], v[216:219], v[90:93]
	v_mfma_f32_16x16x32_bf16 v[142:145], v[70:73], v[166:169], v[142:145]
	v_mfma_f32_16x16x32_bf16 v[138:141], v[86:89], v[166:169], v[138:141]
	v_mfma_f32_16x16x32_bf16 v[126:129], v[70:73], v[174:177], v[126:129]
	v_mfma_f32_16x16x32_bf16 v[122:125], v[86:89], v[174:177], v[122:125]
	v_mfma_f32_16x16x32_bf16 v[110:113], v[70:73], v[182:185], v[110:113]
	v_mfma_f32_16x16x32_bf16 v[106:109], v[86:89], v[182:185], v[106:109]
	v_mfma_f32_16x16x32_bf16 v[94:97], v[70:73], v[220:223], v[94:97]
	v_mfma_f32_16x16x32_bf16 v[90:93], v[86:89], v[220:223], v[90:93]
	v_mfma_f32_16x16x32_bf16 v[134:137], v[146:149], v[162:165], v[134:137]
	v_mfma_f32_16x16x32_bf16 v[130:133], v[154:157], v[162:165], v[130:133]
	v_mfma_f32_16x16x32_bf16 v[118:121], v[146:149], v[170:173], v[118:121]
	v_mfma_f32_16x16x32_bf16 v[114:117], v[154:157], v[170:173], v[114:117]
	v_mfma_f32_16x16x32_bf16 v[102:105], v[146:149], v[178:181], v[102:105]
	v_mfma_f32_16x16x32_bf16 v[98:101], v[154:157], v[178:181], v[98:101]
	v_mfma_f32_16x16x32_bf16 v[82:85], v[146:149], v[216:219], v[82:85]
	v_mfma_f32_16x16x32_bf16 v[74:77], v[154:157], v[216:219], v[74:77]
	v_mfma_f32_16x16x32_bf16 v[134:137], v[150:153], v[166:169], v[134:137]
	v_mfma_f32_16x16x32_bf16 v[130:133], v[158:161], v[166:169], v[130:133]
	v_mfma_f32_16x16x32_bf16 v[118:121], v[150:153], v[174:177], v[118:121]
	v_mfma_f32_16x16x32_bf16 v[114:117], v[158:161], v[174:177], v[114:117]
	v_mfma_f32_16x16x32_bf16 v[102:105], v[150:153], v[182:185], v[102:105]
	v_mfma_f32_16x16x32_bf16 v[98:101], v[158:161], v[182:185], v[98:101]
	v_mfma_f32_16x16x32_bf16 v[82:85], v[150:153], v[220:223], v[82:85]
	v_mfma_f32_16x16x32_bf16 v[74:77], v[158:161], v[220:223], v[74:77]
	s_barrier
; #define PG8_STAGE(bufoff, gbase, voff) do { _Pragma("unroll") for (int _i = 0; _i < 2; ++_i) \
;         __builtin_amdgcn_global_load_lds((const unsigned*)((const char*)(gbase) + (voff)[_i]), (PG8_LAS unsigned*)(lds + (bufoff) + ldsw + _i * 8192), 16, 0, 0); } while (0)
; #define PG8_LDA(dst, b, h) do { _Pragma("unroll") for (int m = 0; m < 4; ++m) _Pragma("unroll") for (int k = 0; k < 2; ++k) dst[m][k] = *(const PG8_LAS bf16x8*)(lds + PG8_SA(b, h) + aoff + m * 2048 + k * 1024); } while (0)
; #define PG8_LDB(dst, b, h) do { _Pragma("unroll") for (int n = 0; n < 2; ++n) _Pragma("unroll") for (int k = 0; k < 2; ++k) dst[n][k] = *(const PG8_LAS bf16x8*)(lds + PG8_SB(b, h) + boff + n * 2048 + k * 1024); } while (0)
; #define PG8_WAIT_V(n) asm volatile("s_waitcnt vmcnt(" #n ")" ::: "memory")
; template <class Epi, class Sched, bool ALIGN_EPI = false, bool SP2 = false>
; __device__ __forceinline__ void gemm_phase(PG8_LAS unsigned char* lds, const Gemm g, const Sched& S, const Epi& E) {
;     ...
;             const char* a1 = cA + (size_t)(t + 1) * kstep;
;             const char* a2 = last ? nA : cA + (size_t)(t + 2) * kstep; const char* b2 = last ? nB : cB + (size_t)(t + 2) * kstep;
;             const char* a3 = a2 + kstep; const char* b3 = b2 + kstep;
;             if (last && has_next) S.a_ready(nxt);
;             if constexpr (SP2) {
;             PG8_LDB(B0, 0, 0); PG8_LDB(B1, 0, 1); PG8_SCHED; PG8_LDA(At, 0, 0); PG8_STAGE(PG8_SA(1, 1), a1 + hstep, voffA);
;             PG8_WAIT_V(8); PG8_WAIT_L(0); PG8_BAR; PG8_MMA(0, 0, At, B0); PG8_MMA(0, 1, At, B1); PG8_BAR; PG8_SCHED;
;             PG8_LDA(At, 0, 1); PG8_STAGE(PG8_SB(0, 0), b2, voffB); PG8_STAGE(PG8_SB(0, 1), b2 + hstepB, voffB); PG8_STAGE(PG8_SA(0, 0), a2, voffA);
;             PG8_WAIT_V(8); PG8_WAIT_L(0); PG8_BAR; PG8_MMA(1, 0, At, B0); PG8_MMA(1, 1, At, B1); PG8_BAR; PG8_SCHED;
;             PG8_LDB(B0, 1, 0); PG8_LDB(B1, 1, 1); PG8_SCHED; PG8_LDA(At, 1, 0); PG8_STAGE(PG8_SA(0, 1), a2 + hstep, voffA);
;             PG8_WAIT_V(8); PG8_WAIT_L(0); PG8_BAR; PG8_MMA(0, 0, At, B0); PG8_MMA(0, 1, At, B1); PG8_BAR; PG8_SCHED;
;             PG8_LDA(At, 1, 1); PG8_STAGE(PG8_SB(1, 0), b3, voffB); PG8_STAGE(PG8_SB(1, 1), b3 + hstepB, voffB); PG8_STAGE(PG8_SA(1, 0), a3, voffA);
;             PG8_WAIT_V(8); PG8_WAIT_L(0); PG8_BAR; PG8_MMA(1, 0, At, B0); PG8_MMA(1, 1, At, B1); PG8_BAR; PG8_SCHED;
	s_add_i32 s9, s9, s25
	s_mov_b32 m0, s9
	ds_read_b128 v[162:165], v236 offset:49152
	ds_read_b128 v[166:169], v236 offset:50176
	ds_read_b128 v[170:173], v236 offset:51200
	ds_read_b128 v[174:177], v236 offset:52224
	ds_read_b128 v[178:181], v236 offset:53248
	ds_read_b128 v[182:185], v236 offset:54272
	ds_read_b128 v[216:219], v236 offset:55296
	ds_read_b128 v[220:223], v236 offset:56320
	s_add_u32 s100, s46, s60
	s_addc_u32 s101, s47, s61
	global_load_lds_dwordx4 v190, s[100:101]
	s_add_i32 m0, s9, 0x2000
	s_add_u32 s10, s46, 0x20080
	s_addc_u32 s11, s47, 0
	s_add_i32 s9, s12, s25
	global_load_lds_dwordx4 v206, s[100:101]
	s_mov_b32 m0, s9
	s_nop 0
	global_load_lds_dwordx4 v190, s[10:11]
	s_add_i32 m0, s9, 0x2000
	s_nop 0
	global_load_lds_dwordx4 v206, s[10:11]
	s_mov_b32 m0, s75
	s_add_u32 s100, s94, s60
	s_addc_u32 s101, s95, s61
	global_load_lds_dwordx4 v210, s[100:101]
	s_mov_b32 m0, s0
	s_nop 0
	global_load_lds_dwordx4 v208, s[100:101]
	s_waitcnt vmcnt(8)
	s_waitcnt lgkmcnt(0)
	s_barrier
	v_mfma_f32_16x16x32_bf16 v[62:65], v[66:69], v[162:165], v[62:65]
	v_mfma_f32_16x16x32_bf16 v[58:61], v[78:81], v[162:165], v[58:61]
	v_mfma_f32_16x16x32_bf16 v[46:49], v[66:69], v[170:173], v[46:49]
	v_mfma_f32_16x16x32_bf16 v[42:45], v[78:81], v[170:173], v[42:45]
	v_mfma_f32_16x16x32_bf16 v[30:33], v[66:69], v[178:181], v[30:33]
	v_mfma_f32_16x16x32_bf16 v[26:29], v[78:81], v[178:181], v[26:29]
	v_mfma_f32_16x16x32_bf16 v[14:17], v[66:69], v[216:219], v[14:17]
	v_mfma_f32_16x16x32_bf16 v[10:13], v[78:81], v[216:219], v[10:13]
	v_mfma_f32_16x16x32_bf16 v[62:65], v[70:73], v[166:169], v[62:65]
	v_mfma_f32_16x16x32_bf16 v[58:61], v[86:89], v[166:169], v[58:61]
	v_mfma_f32_16x16x32_bf16 v[46:49], v[70:73], v[174:177], v[46:49]
	v_mfma_f32_16x16x32_bf16 v[42:45], v[86:89], v[174:177], v[42:45]
	v_mfma_f32_16x16x32_bf16 v[30:33], v[70:73], v[182:185], v[30:33]
	v_mfma_f32_16x16x32_bf16 v[26:29], v[86:89], v[182:185], v[26:29]
	v_mfma_f32_16x16x32_bf16 v[14:17], v[70:73], v[220:223], v[14:17]
	v_mfma_f32_16x16x32_bf16 v[10:13], v[86:89], v[220:223], v[10:13]
	v_mfma_f32_16x16x32_bf16 v[54:57], v[146:149], v[162:165], v[54:57]
	v_mfma_f32_16x16x32_bf16 v[50:53], v[154:157], v[162:165], v[50:53]
	v_mfma_f32_16x16x32_bf16 v[38:41], v[146:149], v[170:173], v[38:41]
	v_mfma_f32_16x16x32_bf16 v[34:37], v[154:157], v[170:173], v[34:37]
	v_mfma_f32_16x16x32_bf16 v[22:25], v[146:149], v[178:181], v[22:25]
	v_mfma_f32_16x16x32_bf16 v[18:21], v[154:157], v[178:181], v[18:21]
	v_mfma_f32_16x16x32_bf16 v[6:9], v[146:149], v[216:219], v[6:9]
	v_mfma_f32_16x16x32_bf16 v[2:5], v[154:157], v[216:219], v[2:5]
	v_mfma_f32_16x16x32_bf16 v[54:57], v[150:153], v[166:169], v[54:57]
	v_mfma_f32_16x16x32_bf16 v[50:53], v[158:161], v[166:169], v[50:53]
	v_mfma_f32_16x16x32_bf16 v[38:41], v[150:153], v[174:177], v[38:41]
	v_mfma_f32_16x16x32_bf16 v[34:37], v[158:161], v[174:177], v[34:37]
	v_mfma_f32_16x16x32_bf16 v[22:25], v[150:153], v[182:185], v[22:25]
	v_mfma_f32_16x16x32_bf16 v[18:21], v[158:161], v[182:185], v[18:21]
	v_mfma_f32_16x16x32_bf16 v[6:9], v[150:153], v[220:223], v[6:9]
	v_mfma_f32_16x16x32_bf16 v[2:5], v[158:161], v[220:223], v[2:5]
	s_barrier
	s_add_i32 s8, s8, 2
	s_add_u32 s38, s38, 0x100
	s_addc_u32 s39, s39, 0
	s_add_u32 s6, s6, 0x100
	s_addc_u32 s7, s7, 0
	s_cmp_gt_u32 s8, 29
.LBB0_927:
	s_add_u32 s9, s38, 0xfff80080
	s_addc_u32 s10, s39, -1
	s_add_i32 s11, 0, 0x10000
	s_cmp_eq_u32 s8, 28
	s_cselect_b32 s95, s36, s10
	s_cselect_b32 s94, s37, s9
	s_cselect_b32 s47, s4, s7
	s_cselect_b32 s46, s5, s6
	s_add_i32 s9, 0, 0x14000
	ds_read_b128 v[66:69], v186
	ds_read_b128 v[70:73], v186 offset:1024
	ds_read_b128 v[78:81], v186 offset:2048
	ds_read_b128 v[86:89], v186 offset:3072
	ds_read_b128 v[146:149], v187
	ds_read_b128 v[150:153], v187 offset:1024
	ds_read_b128 v[154:157], v187 offset:2048
	ds_read_b128 v[158:161], v187 offset:3072
	s_add_i32 m0, s66, 0xc000
	ds_read_b128 v[162:165], v236
	ds_read_b128 v[166:169], v236 offset:1024
	ds_read_b128 v[170:173], v236 offset:2048
	ds_read_b128 v[174:177], v236 offset:3072
	ds_read_b128 v[178:181], v236 offset:4096
	ds_read_b128 v[182:185], v236 offset:5120
	ds_read_b128 v[216:219], v236 offset:6144
	ds_read_b128 v[220:223], v236 offset:7168
	global_load_lds_dwordx4 v212, s[38:39]
	s_add_i32 m0, s66, 0xe000
	s_nop 0
	global_load_lds_dwordx4 v214, s[38:39]
	s_nop 0
	s_waitcnt vmcnt(8)
	s_waitcnt lgkmcnt(0)
	s_barrier
	v_mfma_f32_16x16x32_bf16 v[142:145], v[66:69], v[162:165], v[142:145]
	v_mfma_f32_16x16x32_bf16 v[138:141], v[78:81], v[162:165], v[138:141]
	v_mfma_f32_16x16x32_bf16 v[126:129], v[66:69], v[170:173], v[126:129]
	v_mfma_f32_16x16x32_bf16 v[122:125], v[78:81], v[170:173], v[122:125]
	v_mfma_f32_16x16x32_bf16 v[110:113], v[66:69], v[178:181], v[110:113]
	v_mfma_f32_16x16x32_bf16 v[106:109], v[78:81], v[178:181], v[106:109]
	v_mfma_f32_16x16x32_bf16 v[94:97], v[66:69], v[216:219], v[94:97]
	v_mfma_f32_16x16x32_bf16 v[90:93], v[78:81], v[216:219], v[90:93]
	v_mfma_f32_16x16x32_bf16 v[142:145], v[70:73], v[166:169], v[142:145]
	v_mfma_f32_16x16x32_bf16 v[138:141], v[86:89], v[166:169], v[138:141]
	v_mfma_f32_16x16x32_bf16 v[126:129], v[70:73], v[174:177], v[126:129]
	v_mfma_f32_16x16x32_bf16 v[122:125], v[86:89], v[174:177], v[122:125]
	v_mfma_f32_16x16x32_bf16 v[110:113], v[70:73], v[182:185], v[110:113]
	v_mfma_f32_16x16x32_bf16 v[106:109], v[86:89], v[182:185], v[106:109]
	v_mfma_f32_16x16x32_bf16 v[94:97], v[70:73], v[220:223], v[94:97]
	v_mfma_f32_16x16x32_bf16 v[90:93], v[86:89], v[220:223], v[90:93]
	v_mfma_f32_16x16x32_bf16 v[134:137], v[146:149], v[162:165], v[134:137]
	v_mfma_f32_16x16x32_bf16 v[130:133], v[154:157], v[162:165], v[130:133]
	v_mfma_f32_16x16x32_bf16 v[118:121], v[146:149], v[170:173], v[118:121]
	v_mfma_f32_16x16x32_bf16 v[114:117], v[154:157], v[170:173], v[114:117]
	v_mfma_f32_16x16x32_bf16 v[102:105], v[146:149], v[178:181], v[102:105]
	v_mfma_f32_16x16x32_bf16 v[98:101], v[154:157], v[178:181], v[98:101]
	v_mfma_f32_16x16x32_bf16 v[82:85], v[146:149], v[216:219], v[82:85]
	v_mfma_f32_16x16x32_bf16 v[74:77], v[154:157], v[216:219], v[74:77]
	v_mfma_f32_16x16x32_bf16 v[134:137], v[150:153], v[166:169], v[134:137]
	v_mfma_f32_16x16x32_bf16 v[130:133], v[158:161], v[166:169], v[130:133]
	v_mfma_f32_16x16x32_bf16 v[118:121], v[150:153], v[174:177], v[118:121]
	v_mfma_f32_16x16x32_bf16 v[114:117], v[158:161], v[174:177], v[114:117]
	v_mfma_f32_16x16x32_bf16 v[102:105], v[150:153], v[182:185], v[102:105]
	v_mfma_f32_16x16x32_bf16 v[98:101], v[158:161], v[182:185], v[98:101]
	v_mfma_f32_16x16x32_bf16 v[82:85], v[150:153], v[220:223], v[82:85]
	v_mfma_f32_16x16x32_bf16 v[74:77], v[158:161], v[220:223], v[74:77]
	s_barrier
; #define PG8_STAGE(bufoff, gbase, voff) do { _Pragma("unroll") for (int _i = 0; _i < 2; ++_i) \
;         __builtin_amdgcn_global_load_lds((const unsigned*)((const char*)(gbase) + (voff)[_i]), (PG8_LAS unsigned*)(lds + (bufoff) + ldsw + _i * 8192), 16, 0, 0); } while (0)
; #define PG8_LDA(dst, b, h) do { _Pragma("unroll") for (int m = 0; m < 4; ++m) _Pragma("unroll") for (int k = 0; k < 2; ++k) dst[m][k] = *(const PG8_LAS bf16x8*)(lds + PG8_SA(b, h) + aoff + m * 2048 + k * 1024); } while (0)
; #define PG8_LDB(dst, b, h) do { _Pragma("unroll") for (int n = 0; n < 2; ++n) _Pragma("unroll") for (int k = 0; k < 2; ++k) dst[n][k] = *(const PG8_LAS bf16x8*)(lds + PG8_SB(b, h) + boff + n * 2048 + k * 1024); } while (0)
; #define PG8_MMA(ai, bj, At, Bt) do { __builtin_amdgcn_s_setprio(1); _Pragma("unroll") for (int m = 0; m < 4; ++m) _Pragma("unroll") for (int n = 0; n < 2; ++n) _Pragma("unroll") for (int k = 0; k < 2; ++k) \
;         acc[ai][bj][m][n] = __builtin_amdgcn_mfma_f32_16x16x32_bf16(Bt[n][k], At[m][k], acc[ai][bj][m][n], 0, 0, 0); __builtin_amdgcn_s_setprio(0); } while (0)
; #define PG8_WAIT_V(n) asm volatile("s_waitcnt vmcnt(" #n ")" ::: "memory")
; #define PG8_WAIT_L(n) asm volatile("s_waitcnt lgkmcnt(" #n ")" ::: "memory")
; #define PG8_BAR __builtin_amdgcn_s_barrier()
; #define PG8_SCHED __builtin_amdgcn_sched_barrier(0)
; template <class Epi, class Sched, bool ALIGN_EPI = false, bool SP2 = false>
; __device__ __forceinline__ void gemm_phase(PG8_LAS unsigned char* lds, const Gemm g, const Sched& S, const Epi& E) {
;     ...
;             PG8_LDA(At, 0, 1); PG8_STAGE(PG8_SB(0, 0), b2, voffB); PG8_STAGE(PG8_SB(0, 1), b2 + hstepB, voffB); PG8_STAGE(PG8_SA(0, 0), a2, voffA);
;             PG8_WAIT_V(8); PG8_WAIT_L(0); PG8_BAR; PG8_MMA(1, 0, At, B0); PG8_MMA(1, 1, At, B1); PG8_BAR; PG8_SCHED;
;             PG8_LDB(B0, 1, 0); PG8_LDB(B1, 1, 1); PG8_SCHED; PG8_LDA(At, 1, 0); PG8_STAGE(PG8_SA(0, 1), a2 + hstep, voffA);
;             PG8_WAIT_V(8); PG8_WAIT_L(0); PG8_BAR; PG8_MMA(0, 0, At, B0); PG8_MMA(0, 1, At, B1); PG8_BAR; PG8_SCHED;
	s_add_i32 s10, s11, s25
	s_mov_b32 m0, s10
	ds_read_b128 v[162:165], v236 offset:16384
	ds_read_b128 v[166:169], v236 offset:17408
	ds_read_b128 v[170:173], v236 offset:18432
	ds_read_b128 v[174:177], v236 offset:19456
	ds_read_b128 v[178:181], v236 offset:20480
	ds_read_b128 v[182:185], v236 offset:21504
	ds_read_b128 v[216:219], v236 offset:22528
	ds_read_b128 v[220:223], v236 offset:23552
	global_load_lds_dwordx4 v190, s[46:47]
	s_add_i32 m0, s10, 0x2000
	s_add_u32 s10, s46, 0x20000
	s_addc_u32 s11, s47, 0
	s_add_i32 s9, s9, s25
	global_load_lds_dwordx4 v206, s[46:47]
	s_mov_b32 m0, s9
	s_nop 0
	global_load_lds_dwordx4 v190, s[10:11]
	s_add_i32 m0, s9, 0x2000
	s_nop 0
	global_load_lds_dwordx4 v206, s[10:11]
	s_mov_b32 m0, s66
	s_nop 0
	global_load_lds_dwordx4 v210, s[94:95]
	s_mov_b32 m0, s67
	s_nop 0
	global_load_lds_dwordx4 v208, s[94:95]
	s_nop 0
	s_waitcnt vmcnt(8)
	s_waitcnt lgkmcnt(0)
	s_barrier
	v_mfma_f32_16x16x32_bf16 v[62:65], v[66:69], v[162:165], v[62:65]
	v_mfma_f32_16x16x32_bf16 v[58:61], v[78:81], v[162:165], v[58:61]
	v_mfma_f32_16x16x32_bf16 v[46:49], v[66:69], v[170:173], v[46:49]
	v_mfma_f32_16x16x32_bf16 v[42:45], v[78:81], v[170:173], v[42:45]
	v_mfma_f32_16x16x32_bf16 v[30:33], v[66:69], v[178:181], v[30:33]
	v_mfma_f32_16x16x32_bf16 v[26:29], v[78:81], v[178:181], v[26:29]
	v_mfma_f32_16x16x32_bf16 v[14:17], v[66:69], v[216:219], v[14:17]
	v_mfma_f32_16x16x32_bf16 v[10:13], v[78:81], v[216:219], v[10:13]
	v_mfma_f32_16x16x32_bf16 v[62:65], v[70:73], v[166:169], v[62:65]
	v_mfma_f32_16x16x32_bf16 v[58:61], v[86:89], v[166:169], v[58:61]
	v_mfma_f32_16x16x32_bf16 v[46:49], v[70:73], v[174:177], v[46:49]
	v_mfma_f32_16x16x32_bf16 v[42:45], v[86:89], v[174:177], v[42:45]
	v_mfma_f32_16x16x32_bf16 v[30:33], v[70:73], v[182:185], v[30:33]
	v_mfma_f32_16x16x32_bf16 v[26:29], v[86:89], v[182:185], v[26:29]
	v_mfma_f32_16x16x32_bf16 v[14:17], v[70:73], v[220:223], v[14:17]
	v_mfma_f32_16x16x32_bf16 v[10:13], v[86:89], v[220:223], v[10:13]
	v_mfma_f32_16x16x32_bf16 v[54:57], v[146:149], v[162:165], v[54:57]
	v_mfma_f32_16x16x32_bf16 v[50:53], v[154:157], v[162:165], v[50:53]
	v_mfma_f32_16x16x32_bf16 v[38:41], v[146:149], v[170:173], v[38:41]
	v_mfma_f32_16x16x32_bf16 v[34:37], v[154:157], v[170:173], v[34:37]
	v_mfma_f32_16x16x32_bf16 v[22:25], v[146:149], v[178:181], v[22:25]
	v_mfma_f32_16x16x32_bf16 v[18:21], v[154:157], v[178:181], v[18:21]
	v_mfma_f32_16x16x32_bf16 v[6:9], v[146:149], v[216:219], v[6:9]
	v_mfma_f32_16x16x32_bf16 v[2:5], v[154:157], v[216:219], v[2:5]
	v_mfma_f32_16x16x32_bf16 v[54:57], v[150:153], v[166:169], v[54:57]
	v_mfma_f32_16x16x32_bf16 v[50:53], v[158:161], v[166:169], v[50:53]
	v_mfma_f32_16x16x32_bf16 v[38:41], v[150:153], v[174:177], v[38:41]
	v_mfma_f32_16x16x32_bf16 v[34:37], v[158:161], v[174:177], v[34:37]
	v_mfma_f32_16x16x32_bf16 v[22:25], v[150:153], v[182:185], v[22:25]
	v_mfma_f32_16x16x32_bf16 v[18:21], v[158:161], v[182:185], v[18:21]
	v_mfma_f32_16x16x32_bf16 v[6:9], v[150:153], v[220:223], v[6:9]
	v_mfma_f32_16x16x32_bf16 v[2:5], v[158:161], v[220:223], v[2:5]
	s_barrier
	s_add_i32 s9, 0, 0x18000
	s_add_i32 s12, 0, 0x1c000
	ds_read_b128 v[66:69], v198
	ds_read_b128 v[70:73], v198 offset:1024
	ds_read_b128 v[78:81], v198 offset:2048
	ds_read_b128 v[86:89], v198 offset:3072
	ds_read_b128 v[146:149], v199
	ds_read_b128 v[150:153], v199 offset:1024
	ds_read_b128 v[154:157], v199 offset:2048
	ds_read_b128 v[158:161], v199 offset:3072
	s_add_u32 s10, s94, 0x80000
	s_addc_u32 s11, s95, 0
	s_mov_b32 m0, s59
	ds_read_b128 v[162:165], v236 offset:32768
	ds_read_b128 v[166:169], v236 offset:33792
	ds_read_b128 v[170:173], v236 offset:34816
	ds_read_b128 v[174:177], v236 offset:35840
	ds_read_b128 v[178:181], v236 offset:36864
	ds_read_b128 v[182:185], v236 offset:37888
	ds_read_b128 v[216:219], v236 offset:38912
	ds_read_b128 v[220:223], v236 offset:39936
	global_load_lds_dwordx4 v210, s[10:11]
	s_mov_b32 m0, s74
	s_nop 0
	global_load_lds_dwordx4 v208, s[10:11]
	s_waitcnt vmcnt(8)
	s_waitcnt lgkmcnt(0)
	s_barrier
; #define PG8_STAGE(bufoff, gbase, voff) do { _Pragma("unroll") for (int _i = 0; _i < 2; ++_i) \
;         __builtin_amdgcn_global_load_lds((const unsigned*)((const char*)(gbase) + (voff)[_i]), (PG8_LAS unsigned*)(lds + (bufoff) + ldsw + _i * 8192), 16, 0, 0); } while (0)
; #define PG8_LDA(dst, b, h) do { _Pragma("unroll") for (int m = 0; m < 4; ++m) _Pragma("unroll") for (int k = 0; k < 2; ++k) dst[m][k] = *(const PG8_LAS bf16x8*)(lds + PG8_SA(b, h) + aoff + m * 2048 + k * 1024); } while (0)
; #define PG8_MMA(ai, bj, At, Bt) do { __builtin_amdgcn_s_setprio(1); _Pragma("unroll") for (int m = 0; m < 4; ++m) _Pragma("unroll") for (int n = 0; n < 2; ++n) _Pragma("unroll") for (int k = 0; k < 2; ++k) \
;         acc[ai][bj][m][n] = __builtin_amdgcn_mfma_f32_16x16x32_bf16(Bt[n][k], At[m][k], acc[ai][bj][m][n], 0, 0, 0); __builtin_amdgcn_s_setprio(0); } while (0)
; #define PG8_WAIT_V(n) asm volatile("s_waitcnt vmcnt(" #n ")" ::: "memory")
; #define PG8_WAIT_L(n) asm volatile("s_waitcnt lgkmcnt(" #n ")" ::: "memory")
; #define PG8_BAR __builtin_amdgcn_s_barrier()
; #define PG8_SCHED __builtin_amdgcn_sched_barrier(0)
; template <class Epi, class Sched, bool ALIGN_EPI = false, bool SP2 = false>
; __device__ __forceinline__ void gemm_phase(PG8_LAS unsigned char* lds, const Gemm g, const Sched& S, const Epi& E) {
;     ...
;             PG8_WAIT_V(8); PG8_WAIT_L(0); PG8_BAR; PG8_MMA(0, 0, At, B0); PG8_MMA(0, 1, At, B1); PG8_BAR; PG8_SCHED;
;             PG8_LDA(At, 1, 1); PG8_STAGE(PG8_SB(1, 0), b3, voffB); PG8_STAGE(PG8_SB(1, 1), b3 + hstepB, voffB); PG8_STAGE(PG8_SA(1, 0), a3, voffA);
;             PG8_WAIT_V(8); PG8_WAIT_L(0); PG8_BAR; PG8_MMA(1, 0, At, B0); PG8_MMA(1, 1, At, B1); PG8_BAR; PG8_SCHED;
	v_mfma_f32_16x16x32_bf16 v[142:145], v[66:69], v[162:165], v[142:145]
	v_mfma_f32_16x16x32_bf16 v[138:141], v[78:81], v[162:165], v[138:141]
	v_mfma_f32_16x16x32_bf16 v[126:129], v[66:69], v[170:173], v[126:129]
	v_mfma_f32_16x16x32_bf16 v[122:125], v[78:81], v[170:173], v[122:125]
	v_mfma_f32_16x16x32_bf16 v[110:113], v[66:69], v[178:181], v[110:113]
	v_mfma_f32_16x16x32_bf16 v[106:109], v[78:81], v[178:181], v[106:109]
	v_mfma_f32_16x16x32_bf16 v[94:97], v[66:69], v[216:219], v[94:97]
	v_mfma_f32_16x16x32_bf16 v[90:93], v[78:81], v[216:219], v[90:93]
	v_mfma_f32_16x16x32_bf16 v[142:145], v[70:73], v[166:169], v[142:145]
	v_mfma_f32_16x16x32_bf16 v[138:141], v[86:89], v[166:169], v[138:141]
	v_mfma_f32_16x16x32_bf16 v[126:129], v[70:73], v[174:177], v[126:129]
	v_mfma_f32_16x16x32_bf16 v[122:125], v[86:89], v[174:177], v[122:125]
	v_mfma_f32_16x16x32_bf16 v[110:113], v[70:73], v[182:185], v[110:113]
	v_mfma_f32_16x16x32_bf16 v[106:109], v[86:89], v[182:185], v[106:109]
	v_mfma_f32_16x16x32_bf16 v[94:97], v[70:73], v[220:223], v[94:97]
	v_mfma_f32_16x16x32_bf16 v[90:93], v[86:89], v[220:223], v[90:93]
	v_mfma_f32_16x16x32_bf16 v[134:137], v[146:149], v[162:165], v[134:137]
	v_mfma_f32_16x16x32_bf16 v[130:133], v[154:157], v[162:165], v[130:133]
	v_mfma_f32_16x16x32_bf16 v[118:121], v[146:149], v[170:173], v[118:121]
	v_mfma_f32_16x16x32_bf16 v[114:117], v[154:157], v[170:173], v[114:117]
	v_mfma_f32_16x16x32_bf16 v[102:105], v[146:149], v[178:181], v[102:105]
	v_mfma_f32_16x16x32_bf16 v[98:101], v[154:157], v[178:181], v[98:101]
	v_mfma_f32_16x16x32_bf16 v[82:85], v[146:149], v[216:219], v[82:85]
	v_mfma_f32_16x16x32_bf16 v[74:77], v[154:157], v[216:219], v[74:77]
	v_mfma_f32_16x16x32_bf16 v[134:137], v[150:153], v[166:169], v[134:137]
	v_mfma_f32_16x16x32_bf16 v[130:133], v[158:161], v[166:169], v[130:133]
	v_mfma_f32_16x16x32_bf16 v[118:121], v[150:153], v[174:177], v[118:121]
	v_mfma_f32_16x16x32_bf16 v[114:117], v[158:161], v[174:177], v[114:117]
	v_mfma_f32_16x16x32_bf16 v[102:105], v[150:153], v[182:185], v[102:105]
	v_mfma_f32_16x16x32_bf16 v[98:101], v[158:161], v[182:185], v[98:101]
	v_mfma_f32_16x16x32_bf16 v[82:85], v[150:153], v[220:223], v[82:85]
	v_mfma_f32_16x16x32_bf16 v[74:77], v[158:161], v[220:223], v[74:77]
	s_barrier
	s_add_i32 s9, s9, s25
	s_mov_b32 m0, s9
	ds_read_b128 v[162:165], v236 offset:49152
	ds_read_b128 v[166:169], v236 offset:50176
	ds_read_b128 v[170:173], v236 offset:51200
	ds_read_b128 v[174:177], v236 offset:52224
	ds_read_b128 v[178:181], v236 offset:53248
	ds_read_b128 v[182:185], v236 offset:54272
	ds_read_b128 v[216:219], v236 offset:55296
	ds_read_b128 v[220:223], v236 offset:56320
	s_add_u32 s100, s46, s60
	s_addc_u32 s101, s47, s61
	global_load_lds_dwordx4 v190, s[100:101]
	s_add_i32 m0, s9, 0x2000
	s_add_u32 s10, s46, 0x20080
	s_addc_u32 s11, s47, 0
	s_add_i32 s9, s12, s25
	global_load_lds_dwordx4 v206, s[100:101]
	s_mov_b32 m0, s9
	s_nop 0
	global_load_lds_dwordx4 v190, s[10:11]
	s_add_i32 m0, s9, 0x2000
	s_nop 0
	global_load_lds_dwordx4 v206, s[10:11]
	s_mov_b32 m0, s75
	s_add_u32 s100, s94, s60
	s_addc_u32 s101, s95, s61
	global_load_lds_dwordx4 v210, s[100:101]
	s_mov_b32 m0, s0
	s_nop 0
	global_load_lds_dwordx4 v208, s[100:101]
	s_waitcnt vmcnt(8)
	s_waitcnt lgkmcnt(0)
	s_barrier
	v_mfma_f32_16x16x32_bf16 v[62:65], v[66:69], v[162:165], v[62:65]
	v_mfma_f32_16x16x32_bf16 v[58:61], v[78:81], v[162:165], v[58:61]
	v_mfma_f32_16x16x32_bf16 v[46:49], v[66:69], v[170:173], v[46:49]
	v_mfma_f32_16x16x32_bf16 v[42:45], v[78:81], v[170:173], v[42:45]
	v_mfma_f32_16x16x32_bf16 v[30:33], v[66:69], v[178:181], v[30:33]
	v_mfma_f32_16x16x32_bf16 v[26:29], v[78:81], v[178:181], v[26:29]
	v_mfma_f32_16x16x32_bf16 v[14:17], v[66:69], v[216:219], v[14:17]
	v_mfma_f32_16x16x32_bf16 v[10:13], v[78:81], v[216:219], v[10:13]
	v_mfma_f32_16x16x32_bf16 v[62:65], v[70:73], v[166:169], v[62:65]
	v_mfma_f32_16x16x32_bf16 v[58:61], v[86:89], v[166:169], v[58:61]
	v_mfma_f32_16x16x32_bf16 v[46:49], v[70:73], v[174:177], v[46:49]
	v_mfma_f32_16x16x32_bf16 v[42:45], v[86:89], v[174:177], v[42:45]
	v_mfma_f32_16x16x32_bf16 v[30:33], v[70:73], v[182:185], v[30:33]
	v_mfma_f32_16x16x32_bf16 v[26:29], v[86:89], v[182:185], v[26:29]
	v_mfma_f32_16x16x32_bf16 v[14:17], v[70:73], v[220:223], v[14:17]
	v_mfma_f32_16x16x32_bf16 v[10:13], v[86:89], v[220:223], v[10:13]
	v_mfma_f32_16x16x32_bf16 v[54:57], v[146:149], v[162:165], v[54:57]
	v_mfma_f32_16x16x32_bf16 v[50:53], v[154:157], v[162:165], v[50:53]
	v_mfma_f32_16x16x32_bf16 v[38:41], v[146:149], v[170:173], v[38:41]
	v_mfma_f32_16x16x32_bf16 v[34:37], v[154:157], v[170:173], v[34:37]
	v_mfma_f32_16x16x32_bf16 v[22:25], v[146:149], v[178:181], v[22:25]
	v_mfma_f32_16x16x32_bf16 v[18:21], v[154:157], v[178:181], v[18:21]
	v_mfma_f32_16x16x32_bf16 v[6:9], v[146:149], v[216:219], v[6:9]
	v_mfma_f32_16x16x32_bf16 v[2:5], v[154:157], v[216:219], v[2:5]
	v_mfma_f32_16x16x32_bf16 v[54:57], v[150:153], v[166:169], v[54:57]
	v_mfma_f32_16x16x32_bf16 v[50:53], v[158:161], v[166:169], v[50:53]
	v_mfma_f32_16x16x32_bf16 v[38:41], v[150:153], v[174:177], v[38:41]
	v_mfma_f32_16x16x32_bf16 v[34:37], v[158:161], v[174:177], v[34:37]
	v_mfma_f32_16x16x32_bf16 v[22:25], v[150:153], v[182:185], v[22:25]
	v_mfma_f32_16x16x32_bf16 v[18:21], v[158:161], v[182:185], v[18:21]
	v_mfma_f32_16x16x32_bf16 v[6:9], v[150:153], v[220:223], v[6:9]
	v_mfma_f32_16x16x32_bf16 v[2:5], v[158:161], v[220:223], v[2:5]
	s_barrier
	s_add_i32 s8, s8, 2
	s_add_u32 s38, s38, 0x100
	s_addc_u32 s39, s39, 0
	s_add_u32 s6, s6, 0x100
	s_addc_u32 s7, s7, 0
	s_cmp_gt_u32 s8, 29
	s_cbranch_scc0 .LBB0_927
	s_and_b64 vcc, exec, s[70:71]
	s_cbranch_vccz .LBB0_930
	s_barrier

; #define PG8_STAGE(bufoff, gbase, voff) do { _Pragma("unroll") for (int _i = 0; _i < 2; ++_i) \
;         __builtin_amdgcn_global_load_lds((const unsigned*)((const char*)(gbase) + (voff)[_i]), (PG8_LAS unsigned*)(lds + (bufoff) + ldsw + _i * 8192), 16, 0, 0); } while (0)
; #define PG8_LDA(dst, b, h) do { _Pragma("unroll") for (int m = 0; m < 4; ++m) _Pragma("unroll") for (int k = 0; k < 2; ++k) dst[m][k] = *(const PG8_LAS bf16x8*)(lds + PG8_SA(b, h) + aoff + m * 2048 + k * 1024); } while (0)
; #define PG8_LDB(dst, b, h) do { _Pragma("unroll") for (int n = 0; n < 2; ++n) _Pragma("unroll") for (int k = 0; k < 2; ++k) dst[n][k] = *(const PG8_LAS bf16x8*)(lds + PG8_SB(b, h) + boff + n * 2048 + k * 1024); } while (0)
; #define PG8_WAIT_V(n) asm volatile("s_waitcnt vmcnt(" #n ")" ::: "memory")
; #define PG8_WAIT_L(n) asm volatile("s_waitcnt lgkmcnt(" #n ")" ::: "memory")
; #define PG8_BAR __builtin_amdgcn_s_barrier()
; #define PG8_SCHED __builtin_amdgcn_sched_barrier(0)
; template <class Epi, class Sched, bool ALIGN_EPI = false, bool SP2 = false>
; __device__ __forceinline__ void gemm_phase(PG8_LAS unsigned char* lds, const Gemm g, const Sched& S, const Epi& E) {
;     ...
;         const bool has_next = S.next(ui + 1, nxt);
;         const char* nA = has_next ? (const char*)g.A + (size_t)nxt.pm * tstep : cA; const char* nB = has_next ? (const char*)g.Bt + (size_t)nxt.pn * tstep : cB;
;         for (int t = 0; t < nt; t += 2) {
;             const bool last = (t == nt - 2);
;             const char* a1 = cA + (size_t)(t + 1) * kstep;
;             const char* a2 = last ? nA : cA + (size_t)(t + 2) * kstep; const char* b2 = last ? nB : cB + (size_t)(t + 2) * kstep;
;             const char* a3 = a2 + kstep; const char* b3 = b2 + kstep;
;             if (last && has_next) S.a_ready(nxt);
;             if constexpr (SP2) {
;             PG8_LDB(B0, 0, 0); PG8_LDB(B1, 0, 1); PG8_SCHED; PG8_LDA(At, 0, 0); PG8_STAGE(PG8_SA(1, 1), a1 + hstep, voffA);
;             PG8_WAIT_V(8); PG8_WAIT_L(0); PG8_BAR; PG8_MMA(0, 0, At, B0); PG8_MMA(0, 1, At, B1); PG8_BAR; PG8_SCHED;
;             PG8_LDA(At, 0, 1); PG8_STAGE(PG8_SB(0, 0), b2, voffB); PG8_STAGE(PG8_SB(0, 1), b2 + hstepB, voffB); PG8_STAGE(PG8_SA(0, 0), a2, voffA);
;             PG8_WAIT_V(8); PG8_WAIT_L(0); PG8_BAR; PG8_MMA(1, 0, At, B0); PG8_MMA(1, 1, At, B1); PG8_BAR; PG8_SCHED;
.LBB0_1070:
	s_ashr_i32 s97, s96, 31
	s_lshl_b64 s[4:5], s[96:97], 22
	s_add_u32 s26, s0, s4
	s_addc_u32 s27, s1, s5
	s_and_b64 s[4:5], s[92:93], exec
	s_cselect_b32 s97, s27, s39
	s_cselect_b32 s4, s26, s38
	s_ashr_i32 s85, s84, 31
	s_lshl_b64 s[6:7], s[84:85], 22
	s_add_u32 s94, s56, s6
	s_addc_u32 s95, s57, s7
	s_and_b64 s[6:7], s[92:93], exec
	s_cselect_b32 s5, s95, s47
	s_cselect_b32 s6, s94, s46
	s_add_u32 s38, s38, 0x200080
	s_addc_u32 s39, s39, 0
	s_add_u32 s7, s46, 0x100
	s_addc_u32 s8, s47, 0
	s_mov_b32 s9, -2
	s_waitcnt lgkmcnt(0)
	v_add_u32_e32 v186, 0x10000, v164
	v_add_u32_e32 v187, 0x14000, v164
	v_add_u32_e32 v198, 0x18000, v164
	v_add_u32_e32 v199, 0x1c000, v164
	s_add_u32 s10, s38, 0xffe00080
	s_addc_u32 s11, s39, -1
	s_add_i32 s12, 0, 0x10000
	s_cmpk_eq_i32 s9, 0x7c
	s_cselect_b32 vcc_hi, s97, s11
	s_cselect_b32 vcc_lo, s4, s10
	s_cselect_b32 s47, s5, s8
	s_cselect_b32 s46, s6, s7
	s_add_i32 s13, 0, 0x14000
	ds_read_b128 v[130:133], v186
	ds_read_b128 v[134:137], v186 offset:1024
	ds_read_b128 v[138:141], v186 offset:2048
	ds_read_b128 v[152:155], v186 offset:3072
	ds_read_b128 v[156:159], v187
	ds_read_b128 v[160:163], v187 offset:1024
	ds_read_b128 v[168:171], v187 offset:2048
	ds_read_b128 v[172:175], v187 offset:3072
	s_add_i32 m0, s74, 0xc000
	ds_read_b128 v[176:179], v166
	ds_read_b128 v[180:183], v166 offset:1024
	ds_read_b128 v[206:209], v166 offset:2048
	ds_read_b128 v[210:213], v166 offset:3072
	ds_read_b128 v[214:217], v166 offset:4096
	ds_read_b128 v[218:221], v166 offset:5120
	ds_read_b128 v[236:239], v166 offset:6144
	ds_read_b128 v[240:243], v166 offset:7168
	global_load_lds_dwordx4 v148, s[38:39]
	s_add_i32 m0, s74, 0xe000
	s_nop 0
	global_load_lds_dwordx4 v150, s[38:39]
	s_nop 0
	s_waitcnt vmcnt(8)
	s_waitcnt lgkmcnt(0)
	s_barrier
	v_mfma_f32_16x16x32_bf16 v[126:129], v[130:133], v[176:179], 0
	v_mfma_f32_16x16x32_bf16 v[122:125], v[138:141], v[176:179], 0
	v_mfma_f32_16x16x32_bf16 v[110:113], v[130:133], v[206:209], 0
	v_mfma_f32_16x16x32_bf16 v[106:109], v[138:141], v[206:209], 0
	v_mfma_f32_16x16x32_bf16 v[94:97], v[130:133], v[214:217], 0
	v_mfma_f32_16x16x32_bf16 v[90:93], v[138:141], v[214:217], 0
	v_mfma_f32_16x16x32_bf16 v[78:81], v[130:133], v[236:239], 0
	v_mfma_f32_16x16x32_bf16 v[74:77], v[138:141], v[236:239], 0
	v_mfma_f32_16x16x32_bf16 v[126:129], v[134:137], v[180:183], v[126:129]
	v_mfma_f32_16x16x32_bf16 v[122:125], v[152:155], v[180:183], v[122:125]
	v_mfma_f32_16x16x32_bf16 v[110:113], v[134:137], v[210:213], v[110:113]
	v_mfma_f32_16x16x32_bf16 v[106:109], v[152:155], v[210:213], v[106:109]
	v_mfma_f32_16x16x32_bf16 v[94:97], v[134:137], v[218:221], v[94:97]
	v_mfma_f32_16x16x32_bf16 v[90:93], v[152:155], v[218:221], v[90:93]
	v_mfma_f32_16x16x32_bf16 v[78:81], v[134:137], v[240:243], v[78:81]
	v_mfma_f32_16x16x32_bf16 v[74:77], v[152:155], v[240:243], v[74:77]
	v_mfma_f32_16x16x32_bf16 v[118:121], v[156:159], v[176:179], 0
	v_mfma_f32_16x16x32_bf16 v[114:117], v[168:171], v[176:179], 0
	v_mfma_f32_16x16x32_bf16 v[102:105], v[156:159], v[206:209], 0
	v_mfma_f32_16x16x32_bf16 v[98:101], v[168:171], v[206:209], 0
	v_mfma_f32_16x16x32_bf16 v[86:89], v[156:159], v[214:217], 0
	v_mfma_f32_16x16x32_bf16 v[82:85], v[168:171], v[214:217], 0
	v_mfma_f32_16x16x32_bf16 v[70:73], v[156:159], v[236:239], 0
	v_mfma_f32_16x16x32_bf16 v[66:69], v[168:171], v[236:239], 0
	v_mfma_f32_16x16x32_bf16 v[118:121], v[160:163], v[180:183], v[118:121]
	v_mfma_f32_16x16x32_bf16 v[114:117], v[172:175], v[180:183], v[114:117]
	v_mfma_f32_16x16x32_bf16 v[102:105], v[160:163], v[210:213], v[102:105]
	v_mfma_f32_16x16x32_bf16 v[98:101], v[172:175], v[210:213], v[98:101]
	v_mfma_f32_16x16x32_bf16 v[86:89], v[160:163], v[218:221], v[86:89]
	v_mfma_f32_16x16x32_bf16 v[82:85], v[172:175], v[218:221], v[82:85]
	v_mfma_f32_16x16x32_bf16 v[70:73], v[160:163], v[240:243], v[70:73]
	v_mfma_f32_16x16x32_bf16 v[66:69], v[172:175], v[240:243], v[66:69]
	s_barrier
	s_add_i32 s10, s12, s67
	s_mov_b32 m0, s10
	ds_read_b128 v[176:179], v166 offset:16384
	ds_read_b128 v[180:183], v166 offset:17408
	ds_read_b128 v[206:209], v166 offset:18432
	ds_read_b128 v[210:213], v166 offset:19456
	ds_read_b128 v[214:217], v166 offset:20480
	ds_read_b128 v[218:221], v166 offset:21504
	ds_read_b128 v[236:239], v166 offset:22528
	ds_read_b128 v[240:243], v166 offset:23552
	global_load_lds_dwordx4 v146, s[46:47]
	s_add_i32 m0, s10, 0x2000
	s_add_u32 s10, s46, 0x80000
	s_addc_u32 s11, s47, 0
	s_add_i32 s12, s13, s67
	global_load_lds_dwordx4 v142, s[46:47]
	s_mov_b32 m0, s12
	s_nop 0
	global_load_lds_dwordx4 v146, s[10:11]
	s_add_i32 m0, s12, 0x2000
	s_nop 0
	global_load_lds_dwordx4 v142, s[10:11]
	s_mov_b32 m0, s74
	s_nop 0
	global_load_lds_dwordx4 v190, vcc
	s_mov_b32 m0, s75
	s_nop 0
	global_load_lds_dwordx4 v144, vcc
	s_nop 0
	s_waitcnt vmcnt(8)
	s_waitcnt lgkmcnt(0)
	s_barrier
; #define PG8_STAGE(bufoff, gbase, voff) do { _Pragma("unroll") for (int _i = 0; _i < 2; ++_i) \
;         __builtin_amdgcn_global_load_lds((const unsigned*)((const char*)(gbase) + (voff)[_i]), (PG8_LAS unsigned*)(lds + (bufoff) + ldsw + _i * 8192), 16, 0, 0); } while (0)
; #define PG8_LDA(dst, b, h) do { _Pragma("unroll") for (int m = 0; m < 4; ++m) _Pragma("unroll") for (int k = 0; k < 2; ++k) dst[m][k] = *(const PG8_LAS bf16x8*)(lds + PG8_SA(b, h) + aoff + m * 2048 + k * 1024); } while (0)
; #define PG8_LDB(dst, b, h) do { _Pragma("unroll") for (int n = 0; n < 2; ++n) _Pragma("unroll") for (int k = 0; k < 2; ++k) dst[n][k] = *(const PG8_LAS bf16x8*)(lds + PG8_SB(b, h) + boff + n * 2048 + k * 1024); } while (0)
; #define PG8_MMA(ai, bj, At, Bt) do { __builtin_amdgcn_s_setprio(1); _Pragma("unroll") for (int m = 0; m < 4; ++m) _Pragma("unroll") for (int n = 0; n < 2; ++n) _Pragma("unroll") for (int k = 0; k < 2; ++k) \
;         acc[ai][bj][m][n] = __builtin_amdgcn_mfma_f32_16x16x32_bf16(Bt[n][k], At[m][k], acc[ai][bj][m][n], 0, 0, 0); __builtin_amdgcn_s_setprio(0); } while (0)
; #define PG8_WAIT_V(n) asm volatile("s_waitcnt vmcnt(" #n ")" ::: "memory")
; #define PG8_WAIT_L(n) asm volatile("s_waitcnt lgkmcnt(" #n ")" ::: "memory")
; #define PG8_BAR __builtin_amdgcn_s_barrier()
; #define PG8_SCHED __builtin_amdgcn_sched_barrier(0)
; template <class Epi, class Sched, bool ALIGN_EPI = false, bool SP2 = false>
; __device__ __forceinline__ void gemm_phase(PG8_LAS unsigned char* lds, const Gemm g, const Sched& S, const Epi& E) {
;     ...
;             PG8_WAIT_V(8); PG8_WAIT_L(0); PG8_BAR; PG8_MMA(1, 0, At, B0); PG8_MMA(1, 1, At, B1); PG8_BAR; PG8_SCHED;
;             PG8_LDB(B0, 1, 0); PG8_LDB(B1, 1, 1); PG8_SCHED; PG8_LDA(At, 1, 0); PG8_STAGE(PG8_SA(0, 1), a2 + hstep, voffA);
;             PG8_WAIT_V(8); PG8_WAIT_L(0); PG8_BAR; PG8_MMA(0, 0, At, B0); PG8_MMA(0, 1, At, B1); PG8_BAR; PG8_SCHED;
	v_mfma_f32_16x16x32_bf16 v[62:65], v[130:133], v[176:179], 0
	v_mfma_f32_16x16x32_bf16 v[58:61], v[138:141], v[176:179], 0
	v_mfma_f32_16x16x32_bf16 v[46:49], v[130:133], v[206:209], 0
	v_mfma_f32_16x16x32_bf16 v[42:45], v[138:141], v[206:209], 0
	v_mfma_f32_16x16x32_bf16 v[30:33], v[130:133], v[214:217], 0
	v_mfma_f32_16x16x32_bf16 v[26:29], v[138:141], v[214:217], 0
	v_mfma_f32_16x16x32_bf16 v[14:17], v[130:133], v[236:239], 0
	v_mfma_f32_16x16x32_bf16 v[10:13], v[138:141], v[236:239], 0
	v_mfma_f32_16x16x32_bf16 v[62:65], v[134:137], v[180:183], v[62:65]
	v_mfma_f32_16x16x32_bf16 v[58:61], v[152:155], v[180:183], v[58:61]
	v_mfma_f32_16x16x32_bf16 v[46:49], v[134:137], v[210:213], v[46:49]
	v_mfma_f32_16x16x32_bf16 v[42:45], v[152:155], v[210:213], v[42:45]
	v_mfma_f32_16x16x32_bf16 v[30:33], v[134:137], v[218:221], v[30:33]
	v_mfma_f32_16x16x32_bf16 v[26:29], v[152:155], v[218:221], v[26:29]
	v_mfma_f32_16x16x32_bf16 v[14:17], v[134:137], v[240:243], v[14:17]
	v_mfma_f32_16x16x32_bf16 v[10:13], v[152:155], v[240:243], v[10:13]
	v_mfma_f32_16x16x32_bf16 v[54:57], v[156:159], v[176:179], 0
	v_mfma_f32_16x16x32_bf16 v[50:53], v[168:171], v[176:179], 0
	v_mfma_f32_16x16x32_bf16 v[38:41], v[156:159], v[206:209], 0
	v_mfma_f32_16x16x32_bf16 v[34:37], v[168:171], v[206:209], 0
	v_mfma_f32_16x16x32_bf16 v[22:25], v[156:159], v[214:217], 0
	v_mfma_f32_16x16x32_bf16 v[18:21], v[168:171], v[214:217], 0
	v_mfma_f32_16x16x32_bf16 v[6:9], v[156:159], v[236:239], 0
	v_mfma_f32_16x16x32_bf16 v[2:5], v[168:171], v[236:239], 0
	v_mfma_f32_16x16x32_bf16 v[54:57], v[160:163], v[180:183], v[54:57]
	v_mfma_f32_16x16x32_bf16 v[50:53], v[172:175], v[180:183], v[50:53]
	v_mfma_f32_16x16x32_bf16 v[38:41], v[160:163], v[210:213], v[38:41]
	v_mfma_f32_16x16x32_bf16 v[34:37], v[172:175], v[210:213], v[34:37]
	v_mfma_f32_16x16x32_bf16 v[22:25], v[160:163], v[218:221], v[22:25]
	v_mfma_f32_16x16x32_bf16 v[18:21], v[172:175], v[218:221], v[18:21]
	v_mfma_f32_16x16x32_bf16 v[6:9], v[160:163], v[240:243], v[6:9]
	v_mfma_f32_16x16x32_bf16 v[2:5], v[172:175], v[240:243], v[2:5]
	s_barrier
	s_add_i32 s12, 0, 0x18000
	s_add_i32 s13, 0, 0x1c000
	ds_read_b128 v[130:133], v198
	ds_read_b128 v[134:137], v198 offset:1024
	ds_read_b128 v[138:141], v198 offset:2048
	ds_read_b128 v[152:155], v198 offset:3072
	ds_read_b128 v[156:159], v199
	ds_read_b128 v[160:163], v199 offset:1024
	ds_read_b128 v[168:171], v199 offset:2048
	ds_read_b128 v[172:175], v199 offset:3072
	s_add_u32 s10, vcc_lo, 0x200000
	s_addc_u32 s11, vcc_hi, 0
	s_mov_b32 m0, s86
	ds_read_b128 v[176:179], v166 offset:32768
	ds_read_b128 v[180:183], v166 offset:33792
	ds_read_b128 v[206:209], v166 offset:34816
	ds_read_b128 v[210:213], v166 offset:35840
	ds_read_b128 v[214:217], v166 offset:36864
	ds_read_b128 v[218:221], v166 offset:37888
	ds_read_b128 v[236:239], v166 offset:38912
	ds_read_b128 v[240:243], v166 offset:39936
	global_load_lds_dwordx4 v190, s[10:11]
	s_mov_b32 m0, s87
	s_nop 0
	global_load_lds_dwordx4 v144, s[10:11]
	s_waitcnt vmcnt(8)
	s_waitcnt lgkmcnt(0)
	s_barrier
	v_mfma_f32_16x16x32_bf16 v[126:129], v[130:133], v[176:179], v[126:129]
	v_mfma_f32_16x16x32_bf16 v[122:125], v[138:141], v[176:179], v[122:125]
	v_mfma_f32_16x16x32_bf16 v[110:113], v[130:133], v[206:209], v[110:113]
	v_mfma_f32_16x16x32_bf16 v[106:109], v[138:141], v[206:209], v[106:109]
	v_mfma_f32_16x16x32_bf16 v[94:97], v[130:133], v[214:217], v[94:97]
	v_mfma_f32_16x16x32_bf16 v[90:93], v[138:141], v[214:217], v[90:93]
	v_mfma_f32_16x16x32_bf16 v[78:81], v[130:133], v[236:239], v[78:81]
	v_mfma_f32_16x16x32_bf16 v[74:77], v[138:141], v[236:239], v[74:77]
	v_mfma_f32_16x16x32_bf16 v[126:129], v[134:137], v[180:183], v[126:129]
	v_mfma_f32_16x16x32_bf16 v[122:125], v[152:155], v[180:183], v[122:125]
	v_mfma_f32_16x16x32_bf16 v[110:113], v[134:137], v[210:213], v[110:113]
	v_mfma_f32_16x16x32_bf16 v[106:109], v[152:155], v[210:213], v[106:109]
	v_mfma_f32_16x16x32_bf16 v[94:97], v[134:137], v[218:221], v[94:97]
	v_mfma_f32_16x16x32_bf16 v[90:93], v[152:155], v[218:221], v[90:93]
	v_mfma_f32_16x16x32_bf16 v[78:81], v[134:137], v[240:243], v[78:81]
	v_mfma_f32_16x16x32_bf16 v[74:77], v[152:155], v[240:243], v[74:77]
	v_mfma_f32_16x16x32_bf16 v[118:121], v[156:159], v[176:179], v[118:121]
	v_mfma_f32_16x16x32_bf16 v[114:117], v[168:171], v[176:179], v[114:117]
	v_mfma_f32_16x16x32_bf16 v[102:105], v[156:159], v[206:209], v[102:105]
	v_mfma_f32_16x16x32_bf16 v[98:101], v[168:171], v[206:209], v[98:101]
	v_mfma_f32_16x16x32_bf16 v[86:89], v[156:159], v[214:217], v[86:89]
	v_mfma_f32_16x16x32_bf16 v[82:85], v[168:171], v[214:217], v[82:85]
	v_mfma_f32_16x16x32_bf16 v[70:73], v[156:159], v[236:239], v[70:73]
	v_mfma_f32_16x16x32_bf16 v[66:69], v[168:171], v[236:239], v[66:69]
	v_mfma_f32_16x16x32_bf16 v[118:121], v[160:163], v[180:183], v[118:121]
	v_mfma_f32_16x16x32_bf16 v[114:117], v[172:175], v[180:183], v[114:117]
	v_mfma_f32_16x16x32_bf16 v[102:105], v[160:163], v[210:213], v[102:105]
	v_mfma_f32_16x16x32_bf16 v[98:101], v[172:175], v[210:213], v[98:101]
	v_mfma_f32_16x16x32_bf16 v[86:89], v[160:163], v[218:221], v[86:89]
	v_mfma_f32_16x16x32_bf16 v[82:85], v[172:175], v[218:221], v[82:85]
	v_mfma_f32_16x16x32_bf16 v[70:73], v[160:163], v[240:243], v[70:73]
	v_mfma_f32_16x16x32_bf16 v[66:69], v[172:175], v[240:243], v[66:69]
	s_barrier
; #define PG8_STAGE(bufoff, gbase, voff) do { _Pragma("unroll") for (int _i = 0; _i < 2; ++_i) \
;         __builtin_amdgcn_global_load_lds((const unsigned*)((const char*)(gbase) + (voff)[_i]), (PG8_LAS unsigned*)(lds + (bufoff) + ldsw + _i * 8192), 16, 0, 0); } while (0)
; #define PG8_LDA(dst, b, h) do { _Pragma("unroll") for (int m = 0; m < 4; ++m) _Pragma("unroll") for (int k = 0; k < 2; ++k) dst[m][k] = *(const PG8_LAS bf16x8*)(lds + PG8_SA(b, h) + aoff + m * 2048 + k * 1024); } while (0)
; #define PG8_LDB(dst, b, h) do { _Pragma("unroll") for (int n = 0; n < 2; ++n) _Pragma("unroll") for (int k = 0; k < 2; ++k) dst[n][k] = *(const PG8_LAS bf16x8*)(lds + PG8_SB(b, h) + boff + n * 2048 + k * 1024); } while (0)
; #define PG8_WAIT_V(n) asm volatile("s_waitcnt vmcnt(" #n ")" ::: "memory")
; template <class Epi, class Sched, bool ALIGN_EPI = false, bool SP2 = false>
; __device__ __forceinline__ void gemm_phase(PG8_LAS unsigned char* lds, const Gemm g, const Sched& S, const Epi& E) {
;     ...
;             const char* a1 = cA + (size_t)(t + 1) * kstep;
;             const char* a2 = last ? nA : cA + (size_t)(t + 2) * kstep; const char* b2 = last ? nB : cB + (size_t)(t + 2) * kstep;
;             const char* a3 = a2 + kstep; const char* b3 = b2 + kstep;
;             if (last && has_next) S.a_ready(nxt);
;             if constexpr (SP2) {
;             PG8_LDB(B0, 0, 0); PG8_LDB(B1, 0, 1); PG8_SCHED; PG8_LDA(At, 0, 0); PG8_STAGE(PG8_SA(1, 1), a1 + hstep, voffA);
;             PG8_WAIT_V(8); PG8_WAIT_L(0); PG8_BAR; PG8_MMA(0, 0, At, B0); PG8_MMA(0, 1, At, B1); PG8_BAR; PG8_SCHED;
;             PG8_LDA(At, 0, 1); PG8_STAGE(PG8_SB(0, 0), b2, voffB); PG8_STAGE(PG8_SB(0, 1), b2 + hstepB, voffB); PG8_STAGE(PG8_SA(0, 0), a2, voffA);
;             PG8_WAIT_V(8); PG8_WAIT_L(0); PG8_BAR; PG8_MMA(1, 0, At, B0); PG8_MMA(1, 1, At, B1); PG8_BAR; PG8_SCHED;
;             PG8_LDB(B0, 1, 0); PG8_LDB(B1, 1, 1); PG8_SCHED; PG8_LDA(At, 1, 0); PG8_STAGE(PG8_SA(0, 1), a2 + hstep, voffA);
;             PG8_WAIT_V(8); PG8_WAIT_L(0); PG8_BAR; PG8_MMA(0, 0, At, B0); PG8_MMA(0, 1, At, B1); PG8_BAR; PG8_SCHED;
;             PG8_LDA(At, 1, 1); PG8_STAGE(PG8_SB(1, 0), b3, voffB); PG8_STAGE(PG8_SB(1, 1), b3 + hstepB, voffB); PG8_STAGE(PG8_SA(1, 0), a3, voffA);
;             PG8_WAIT_V(8); PG8_WAIT_L(0); PG8_BAR; PG8_MMA(1, 0, At, B0); PG8_MMA(1, 1, At, B1); PG8_BAR; PG8_SCHED;
	s_add_i32 s10, s12, s67
	s_mov_b32 m0, s10
	ds_read_b128 v[176:179], v166 offset:49152
	ds_read_b128 v[180:183], v166 offset:50176
	ds_read_b128 v[206:209], v166 offset:51200
	ds_read_b128 v[210:213], v166 offset:52224
	ds_read_b128 v[214:217], v166 offset:53248
	ds_read_b128 v[218:221], v166 offset:54272
	ds_read_b128 v[236:239], v166 offset:55296
	ds_read_b128 v[240:243], v166 offset:56320
	s_add_u32 s100, s46, s60
	s_addc_u32 s101, s47, s61
	global_load_lds_dwordx4 v146, s[100:101]
	s_add_i32 m0, s10, 0x2000
	s_add_u32 s10, s46, 0x80080
	s_addc_u32 s11, s47, 0
	s_add_i32 s12, s13, s67
	global_load_lds_dwordx4 v142, s[100:101]
	s_mov_b32 m0, s12
	s_nop 0
	global_load_lds_dwordx4 v146, s[10:11]
	s_add_i32 m0, s12, 0x2000
	s_nop 0
	global_load_lds_dwordx4 v142, s[10:11]
	s_mov_b32 m0, s82
	s_add_u32 s100, vcc_lo, s60
	s_addc_u32 s101, vcc_hi, s61
	global_load_lds_dwordx4 v190, s[100:101]
	s_mov_b32 m0, s42
	s_nop 0
	global_load_lds_dwordx4 v144, s[100:101]
	s_waitcnt vmcnt(8)
	s_waitcnt lgkmcnt(0)
	s_barrier
	v_mfma_f32_16x16x32_bf16 v[62:65], v[130:133], v[176:179], v[62:65]
	v_mfma_f32_16x16x32_bf16 v[58:61], v[138:141], v[176:179], v[58:61]
	v_mfma_f32_16x16x32_bf16 v[46:49], v[130:133], v[206:209], v[46:49]
	v_mfma_f32_16x16x32_bf16 v[42:45], v[138:141], v[206:209], v[42:45]
	v_mfma_f32_16x16x32_bf16 v[30:33], v[130:133], v[214:217], v[30:33]
	v_mfma_f32_16x16x32_bf16 v[26:29], v[138:141], v[214:217], v[26:29]
	v_mfma_f32_16x16x32_bf16 v[14:17], v[130:133], v[236:239], v[14:17]
	v_mfma_f32_16x16x32_bf16 v[10:13], v[138:141], v[236:239], v[10:13]
	v_mfma_f32_16x16x32_bf16 v[62:65], v[134:137], v[180:183], v[62:65]
	v_mfma_f32_16x16x32_bf16 v[58:61], v[152:155], v[180:183], v[58:61]
	v_mfma_f32_16x16x32_bf16 v[46:49], v[134:137], v[210:213], v[46:49]
	v_mfma_f32_16x16x32_bf16 v[42:45], v[152:155], v[210:213], v[42:45]
	v_mfma_f32_16x16x32_bf16 v[30:33], v[134:137], v[218:221], v[30:33]
	v_mfma_f32_16x16x32_bf16 v[26:29], v[152:155], v[218:221], v[26:29]
	v_mfma_f32_16x16x32_bf16 v[14:17], v[134:137], v[240:243], v[14:17]
	v_mfma_f32_16x16x32_bf16 v[10:13], v[152:155], v[240:243], v[10:13]
	v_mfma_f32_16x16x32_bf16 v[54:57], v[156:159], v[176:179], v[54:57]
	v_mfma_f32_16x16x32_bf16 v[50:53], v[168:171], v[176:179], v[50:53]
	v_mfma_f32_16x16x32_bf16 v[38:41], v[156:159], v[206:209], v[38:41]
	v_mfma_f32_16x16x32_bf16 v[34:37], v[168:171], v[206:209], v[34:37]
	v_mfma_f32_16x16x32_bf16 v[22:25], v[156:159], v[214:217], v[22:25]
	v_mfma_f32_16x16x32_bf16 v[18:21], v[168:171], v[214:217], v[18:21]
	v_mfma_f32_16x16x32_bf16 v[6:9], v[156:159], v[236:239], v[6:9]
	v_mfma_f32_16x16x32_bf16 v[2:5], v[168:171], v[236:239], v[2:5]
	v_mfma_f32_16x16x32_bf16 v[54:57], v[160:163], v[180:183], v[54:57]
	v_mfma_f32_16x16x32_bf16 v[50:53], v[172:175], v[180:183], v[50:53]
	v_mfma_f32_16x16x32_bf16 v[38:41], v[160:163], v[210:213], v[38:41]
	v_mfma_f32_16x16x32_bf16 v[34:37], v[172:175], v[210:213], v[34:37]
	v_mfma_f32_16x16x32_bf16 v[22:25], v[160:163], v[218:221], v[22:25]
	v_mfma_f32_16x16x32_bf16 v[18:21], v[172:175], v[218:221], v[18:21]
	v_mfma_f32_16x16x32_bf16 v[6:9], v[160:163], v[240:243], v[6:9]
	v_mfma_f32_16x16x32_bf16 v[2:5], v[172:175], v[240:243], v[2:5]
	s_barrier
	s_add_i32 s9, s9, 2
	s_add_u32 s38, s38, 0x100
	s_addc_u32 s39, s39, 0
	s_add_u32 s7, s7, 0x100
	s_addc_u32 s8, s8, 0
	s_cmpk_gt_u32 s9, 0x7d
.LBB0_1071:
	s_add_u32 s10, s38, 0xffe00080
	s_addc_u32 s11, s39, -1
	s_add_i32 s12, 0, 0x10000
	s_cmpk_eq_i32 s9, 0x7c
	s_cselect_b32 vcc_hi, s97, s11
	s_cselect_b32 vcc_lo, s4, s10
	s_cselect_b32 s47, s5, s8
	s_cselect_b32 s46, s6, s7
	s_add_i32 s13, 0, 0x14000
	ds_read_b128 v[130:133], v186
	ds_read_b128 v[134:137], v186 offset:1024
	ds_read_b128 v[138:141], v186 offset:2048
	ds_read_b128 v[152:155], v186 offset:3072
	ds_read_b128 v[156:159], v187
	ds_read_b128 v[160:163], v187 offset:1024
	ds_read_b128 v[168:171], v187 offset:2048
	ds_read_b128 v[172:175], v187 offset:3072
	s_add_i32 m0, s74, 0xc000
	ds_read_b128 v[176:179], v166
	ds_read_b128 v[180:183], v166 offset:1024
	ds_read_b128 v[206:209], v166 offset:2048
	ds_read_b128 v[210:213], v166 offset:3072
	ds_read_b128 v[214:217], v166 offset:4096
	ds_read_b128 v[218:221], v166 offset:5120
	ds_read_b128 v[236:239], v166 offset:6144
	ds_read_b128 v[240:243], v166 offset:7168
	global_load_lds_dwordx4 v148, s[38:39]
	s_add_i32 m0, s74, 0xe000
	s_nop 0
	global_load_lds_dwordx4 v150, s[38:39]
	s_nop 0
	s_waitcnt vmcnt(8)
	s_waitcnt lgkmcnt(0)
	s_barrier
	v_mfma_f32_16x16x32_bf16 v[126:129], v[130:133], v[176:179], v[126:129]
	v_mfma_f32_16x16x32_bf16 v[122:125], v[138:141], v[176:179], v[122:125]
	v_mfma_f32_16x16x32_bf16 v[110:113], v[130:133], v[206:209], v[110:113]
	v_mfma_f32_16x16x32_bf16 v[106:109], v[138:141], v[206:209], v[106:109]
	v_mfma_f32_16x16x32_bf16 v[94:97], v[130:133], v[214:217], v[94:97]
	v_mfma_f32_16x16x32_bf16 v[90:93], v[138:141], v[214:217], v[90:93]
	v_mfma_f32_16x16x32_bf16 v[78:81], v[130:133], v[236:239], v[78:81]
	v_mfma_f32_16x16x32_bf16 v[74:77], v[138:141], v[236:239], v[74:77]
	v_mfma_f32_16x16x32_bf16 v[126:129], v[134:137], v[180:183], v[126:129]
	v_mfma_f32_16x16x32_bf16 v[122:125], v[152:155], v[180:183], v[122:125]
	v_mfma_f32_16x16x32_bf16 v[110:113], v[134:137], v[210:213], v[110:113]
	v_mfma_f32_16x16x32_bf16 v[106:109], v[152:155], v[210:213], v[106:109]
	v_mfma_f32_16x16x32_bf16 v[94:97], v[134:137], v[218:221], v[94:97]
	v_mfma_f32_16x16x32_bf16 v[90:93], v[152:155], v[218:221], v[90:93]
	v_mfma_f32_16x16x32_bf16 v[78:81], v[134:137], v[240:243], v[78:81]
	v_mfma_f32_16x16x32_bf16 v[74:77], v[152:155], v[240:243], v[74:77]
	v_mfma_f32_16x16x32_bf16 v[118:121], v[156:159], v[176:179], v[118:121]
	v_mfma_f32_16x16x32_bf16 v[114:117], v[168:171], v[176:179], v[114:117]
	v_mfma_f32_16x16x32_bf16 v[102:105], v[156:159], v[206:209], v[102:105]
	v_mfma_f32_16x16x32_bf16 v[98:101], v[168:171], v[206:209], v[98:101]
	v_mfma_f32_16x16x32_bf16 v[86:89], v[156:159], v[214:217], v[86:89]
	v_mfma_f32_16x16x32_bf16 v[82:85], v[168:171], v[214:217], v[82:85]
	v_mfma_f32_16x16x32_bf16 v[70:73], v[156:159], v[236:239], v[70:73]
	v_mfma_f32_16x16x32_bf16 v[66:69], v[168:171], v[236:239], v[66:69]
	v_mfma_f32_16x16x32_bf16 v[118:121], v[160:163], v[180:183], v[118:121]
	v_mfma_f32_16x16x32_bf16 v[114:117], v[172:175], v[180:183], v[114:117]
	v_mfma_f32_16x16x32_bf16 v[102:105], v[160:163], v[210:213], v[102:105]
	v_mfma_f32_16x16x32_bf16 v[98:101], v[172:175], v[210:213], v[98:101]
	v_mfma_f32_16x16x32_bf16 v[86:89], v[160:163], v[218:221], v[86:89]
	v_mfma_f32_16x16x32_bf16 v[82:85], v[172:175], v[218:221], v[82:85]
	v_mfma_f32_16x16x32_bf16 v[70:73], v[160:163], v[240:243], v[70:73]
	v_mfma_f32_16x16x32_bf16 v[66:69], v[172:175], v[240:243], v[66:69]
	s_barrier
; #define PG8_STAGE(bufoff, gbase, voff) do { _Pragma("unroll") for (int _i = 0; _i < 2; ++_i) \
;         __builtin_amdgcn_global_load_lds((const unsigned*)((const char*)(gbase) + (voff)[_i]), (PG8_LAS unsigned*)(lds + (bufoff) + ldsw + _i * 8192), 16, 0, 0); } while (0)
; #define PG8_LDA(dst, b, h) do { _Pragma("unroll") for (int m = 0; m < 4; ++m) _Pragma("unroll") for (int k = 0; k < 2; ++k) dst[m][k] = *(const PG8_LAS bf16x8*)(lds + PG8_SA(b, h) + aoff + m * 2048 + k * 1024); } while (0)
; #define PG8_LDB(dst, b, h) do { _Pragma("unroll") for (int n = 0; n < 2; ++n) _Pragma("unroll") for (int k = 0; k < 2; ++k) dst[n][k] = *(const PG8_LAS bf16x8*)(lds + PG8_SB(b, h) + boff + n * 2048 + k * 1024); } while (0)
; #define PG8_MMA(ai, bj, At, Bt) do { __builtin_amdgcn_s_setprio(1); _Pragma("unroll") for (int m = 0; m < 4; ++m) _Pragma("unroll") for (int n = 0; n < 2; ++n) _Pragma("unroll") for (int k = 0; k < 2; ++k) \
;         acc[ai][bj][m][n] = __builtin_amdgcn_mfma_f32_16x16x32_bf16(Bt[n][k], At[m][k], acc[ai][bj][m][n], 0, 0, 0); __builtin_amdgcn_s_setprio(0); } while (0)
; #define PG8_WAIT_V(n) asm volatile("s_waitcnt vmcnt(" #n ")" ::: "memory")
; #define PG8_WAIT_L(n) asm volatile("s_waitcnt lgkmcnt(" #n ")" ::: "memory")
; #define PG8_BAR __builtin_amdgcn_s_barrier()
; #define PG8_SCHED __builtin_amdgcn_sched_barrier(0)
; template <class Epi, class Sched, bool ALIGN_EPI = false, bool SP2 = false>
; __device__ __forceinline__ void gemm_phase(PG8_LAS unsigned char* lds, const Gemm g, const Sched& S, const Epi& E) {
;     ...
;             PG8_LDA(At, 0, 1); PG8_STAGE(PG8_SB(0, 0), b2, voffB); PG8_STAGE(PG8_SB(0, 1), b2 + hstepB, voffB); PG8_STAGE(PG8_SA(0, 0), a2, voffA);
;             PG8_WAIT_V(8); PG8_WAIT_L(0); PG8_BAR; PG8_MMA(1, 0, At, B0); PG8_MMA(1, 1, At, B1); PG8_BAR; PG8_SCHED;
;             PG8_LDB(B0, 1, 0); PG8_LDB(B1, 1, 1); PG8_SCHED; PG8_LDA(At, 1, 0); PG8_STAGE(PG8_SA(0, 1), a2 + hstep, voffA);
;             PG8_WAIT_V(8); PG8_WAIT_L(0); PG8_BAR; PG8_MMA(0, 0, At, B0); PG8_MMA(0, 1, At, B1); PG8_BAR; PG8_SCHED;
	s_add_i32 s10, s12, s67
	s_mov_b32 m0, s10
	ds_read_b128 v[176:179], v166 offset:16384
	ds_read_b128 v[180:183], v166 offset:17408
	ds_read_b128 v[206:209], v166 offset:18432
	ds_read_b128 v[210:213], v166 offset:19456
	ds_read_b128 v[214:217], v166 offset:20480
	ds_read_b128 v[218:221], v166 offset:21504
	ds_read_b128 v[236:239], v166 offset:22528
	ds_read_b128 v[240:243], v166 offset:23552
	global_load_lds_dwordx4 v146, s[46:47]
	s_add_i32 m0, s10, 0x2000
	s_add_u32 s10, s46, 0x80000
	s_addc_u32 s11, s47, 0
	s_add_i32 s12, s13, s67
	global_load_lds_dwordx4 v142, s[46:47]
	s_mov_b32 m0, s12
	s_nop 0
	global_load_lds_dwordx4 v146, s[10:11]
	s_add_i32 m0, s12, 0x2000
	s_nop 0
	global_load_lds_dwordx4 v142, s[10:11]
	s_mov_b32 m0, s74
	s_nop 0
	global_load_lds_dwordx4 v190, vcc
	s_mov_b32 m0, s75
	s_nop 0
	global_load_lds_dwordx4 v144, vcc
	s_nop 0
	s_waitcnt vmcnt(8)
	s_waitcnt lgkmcnt(0)
	s_barrier
	v_mfma_f32_16x16x32_bf16 v[62:65], v[130:133], v[176:179], v[62:65]
	v_mfma_f32_16x16x32_bf16 v[58:61], v[138:141], v[176:179], v[58:61]
	v_mfma_f32_16x16x32_bf16 v[46:49], v[130:133], v[206:209], v[46:49]
	v_mfma_f32_16x16x32_bf16 v[42:45], v[138:141], v[206:209], v[42:45]
	v_mfma_f32_16x16x32_bf16 v[30:33], v[130:133], v[214:217], v[30:33]
	v_mfma_f32_16x16x32_bf16 v[26:29], v[138:141], v[214:217], v[26:29]
	v_mfma_f32_16x16x32_bf16 v[14:17], v[130:133], v[236:239], v[14:17]
	v_mfma_f32_16x16x32_bf16 v[10:13], v[138:141], v[236:239], v[10:13]
	v_mfma_f32_16x16x32_bf16 v[62:65], v[134:137], v[180:183], v[62:65]
	v_mfma_f32_16x16x32_bf16 v[58:61], v[152:155], v[180:183], v[58:61]
	v_mfma_f32_16x16x32_bf16 v[46:49], v[134:137], v[210:213], v[46:49]
	v_mfma_f32_16x16x32_bf16 v[42:45], v[152:155], v[210:213], v[42:45]
	v_mfma_f32_16x16x32_bf16 v[30:33], v[134:137], v[218:221], v[30:33]
	v_mfma_f32_16x16x32_bf16 v[26:29], v[152:155], v[218:221], v[26:29]
	v_mfma_f32_16x16x32_bf16 v[14:17], v[134:137], v[240:243], v[14:17]
	v_mfma_f32_16x16x32_bf16 v[10:13], v[152:155], v[240:243], v[10:13]
	v_mfma_f32_16x16x32_bf16 v[54:57], v[156:159], v[176:179], v[54:57]
	v_mfma_f32_16x16x32_bf16 v[50:53], v[168:171], v[176:179], v[50:53]
	v_mfma_f32_16x16x32_bf16 v[38:41], v[156:159], v[206:209], v[38:41]
	v_mfma_f32_16x16x32_bf16 v[34:37], v[168:171], v[206:209], v[34:37]
	v_mfma_f32_16x16x32_bf16 v[22:25], v[156:159], v[214:217], v[22:25]
	v_mfma_f32_16x16x32_bf16 v[18:21], v[168:171], v[214:217], v[18:21]
	v_mfma_f32_16x16x32_bf16 v[6:9], v[156:159], v[236:239], v[6:9]
	v_mfma_f32_16x16x32_bf16 v[2:5], v[168:171], v[236:239], v[2:5]
	v_mfma_f32_16x16x32_bf16 v[54:57], v[160:163], v[180:183], v[54:57]
	v_mfma_f32_16x16x32_bf16 v[50:53], v[172:175], v[180:183], v[50:53]
	v_mfma_f32_16x16x32_bf16 v[38:41], v[160:163], v[210:213], v[38:41]
	v_mfma_f32_16x16x32_bf16 v[34:37], v[172:175], v[210:213], v[34:37]
	v_mfma_f32_16x16x32_bf16 v[22:25], v[160:163], v[218:221], v[22:25]
	v_mfma_f32_16x16x32_bf16 v[18:21], v[172:175], v[218:221], v[18:21]
	v_mfma_f32_16x16x32_bf16 v[6:9], v[160:163], v[240:243], v[6:9]
	v_mfma_f32_16x16x32_bf16 v[2:5], v[172:175], v[240:243], v[2:5]
	s_barrier
	s_add_i32 s12, 0, 0x18000
	s_add_i32 s13, 0, 0x1c000
	ds_read_b128 v[130:133], v198
	ds_read_b128 v[134:137], v198 offset:1024
	ds_read_b128 v[138:141], v198 offset:2048
	ds_read_b128 v[152:155], v198 offset:3072
	ds_read_b128 v[156:159], v199
	ds_read_b128 v[160:163], v199 offset:1024
	ds_read_b128 v[168:171], v199 offset:2048
	ds_read_b128 v[172:175], v199 offset:3072
	s_add_u32 s10, vcc_lo, 0x200000
	s_addc_u32 s11, vcc_hi, 0
	s_mov_b32 m0, s86
	ds_read_b128 v[176:179], v166 offset:32768
	ds_read_b128 v[180:183], v166 offset:33792
	ds_read_b128 v[206:209], v166 offset:34816
	ds_read_b128 v[210:213], v166 offset:35840
	ds_read_b128 v[214:217], v166 offset:36864
	ds_read_b128 v[218:221], v166 offset:37888
	ds_read_b128 v[236:239], v166 offset:38912
	ds_read_b128 v[240:243], v166 offset:39936
	global_load_lds_dwordx4 v190, s[10:11]
	s_mov_b32 m0, s87
	s_nop 0
	global_load_lds_dwordx4 v144, s[10:11]
	s_waitcnt vmcnt(8)
	s_waitcnt lgkmcnt(0)
	s_barrier
; #define PG8_STAGE(bufoff, gbase, voff) do { _Pragma("unroll") for (int _i = 0; _i < 2; ++_i) \
;         __builtin_amdgcn_global_load_lds((const unsigned*)((const char*)(gbase) + (voff)[_i]), (PG8_LAS unsigned*)(lds + (bufoff) + ldsw + _i * 8192), 16, 0, 0); } while (0)
; #define PG8_LDA(dst, b, h) do { _Pragma("unroll") for (int m = 0; m < 4; ++m) _Pragma("unroll") for (int k = 0; k < 2; ++k) dst[m][k] = *(const PG8_LAS bf16x8*)(lds + PG8_SA(b, h) + aoff + m * 2048 + k * 1024); } while (0)
; #define PG8_MMA(ai, bj, At, Bt) do { __builtin_amdgcn_s_setprio(1); _Pragma("unroll") for (int m = 0; m < 4; ++m) _Pragma("unroll") for (int n = 0; n < 2; ++n) _Pragma("unroll") for (int k = 0; k < 2; ++k) \
;         acc[ai][bj][m][n] = __builtin_amdgcn_mfma_f32_16x16x32_bf16(Bt[n][k], At[m][k], acc[ai][bj][m][n], 0, 0, 0); __builtin_amdgcn_s_setprio(0); } while (0)
; #define PG8_WAIT_V(n) asm volatile("s_waitcnt vmcnt(" #n ")" ::: "memory")
; #define PG8_WAIT_L(n) asm volatile("s_waitcnt lgkmcnt(" #n ")" ::: "memory")
; #define PG8_BAR __builtin_amdgcn_s_barrier()
; #define PG8_SCHED __builtin_amdgcn_sched_barrier(0)
; template <class Epi, class Sched, bool ALIGN_EPI = false, bool SP2 = false>
; __device__ __forceinline__ void gemm_phase(PG8_LAS unsigned char* lds, const Gemm g, const Sched& S, const Epi& E) {
;     ...
;             PG8_WAIT_V(8); PG8_WAIT_L(0); PG8_BAR; PG8_MMA(0, 0, At, B0); PG8_MMA(0, 1, At, B1); PG8_BAR; PG8_SCHED;
;             PG8_LDA(At, 1, 1); PG8_STAGE(PG8_SB(1, 0), b3, voffB); PG8_STAGE(PG8_SB(1, 1), b3 + hstepB, voffB); PG8_STAGE(PG8_SA(1, 0), a3, voffA);
;             PG8_WAIT_V(8); PG8_WAIT_L(0); PG8_BAR; PG8_MMA(1, 0, At, B0); PG8_MMA(1, 1, At, B1); PG8_BAR; PG8_SCHED;
	v_mfma_f32_16x16x32_bf16 v[126:129], v[130:133], v[176:179], v[126:129]
	v_mfma_f32_16x16x32_bf16 v[122:125], v[138:141], v[176:179], v[122:125]
	v_mfma_f32_16x16x32_bf16 v[110:113], v[130:133], v[206:209], v[110:113]
	v_mfma_f32_16x16x32_bf16 v[106:109], v[138:141], v[206:209], v[106:109]
	v_mfma_f32_16x16x32_bf16 v[94:97], v[130:133], v[214:217], v[94:97]
	v_mfma_f32_16x16x32_bf16 v[90:93], v[138:141], v[214:217], v[90:93]
	v_mfma_f32_16x16x32_bf16 v[78:81], v[130:133], v[236:239], v[78:81]
	v_mfma_f32_16x16x32_bf16 v[74:77], v[138:141], v[236:239], v[74:77]
	v_mfma_f32_16x16x32_bf16 v[126:129], v[134:137], v[180:183], v[126:129]
	v_mfma_f32_16x16x32_bf16 v[122:125], v[152:155], v[180:183], v[122:125]
	v_mfma_f32_16x16x32_bf16 v[110:113], v[134:137], v[210:213], v[110:113]
	v_mfma_f32_16x16x32_bf16 v[106:109], v[152:155], v[210:213], v[106:109]
	v_mfma_f32_16x16x32_bf16 v[94:97], v[134:137], v[218:221], v[94:97]
	v_mfma_f32_16x16x32_bf16 v[90:93], v[152:155], v[218:221], v[90:93]
	v_mfma_f32_16x16x32_bf16 v[78:81], v[134:137], v[240:243], v[78:81]
	v_mfma_f32_16x16x32_bf16 v[74:77], v[152:155], v[240:243], v[74:77]
	v_mfma_f32_16x16x32_bf16 v[118:121], v[156:159], v[176:179], v[118:121]
	v_mfma_f32_16x16x32_bf16 v[114:117], v[168:171], v[176:179], v[114:117]
	v_mfma_f32_16x16x32_bf16 v[102:105], v[156:159], v[206:209], v[102:105]
	v_mfma_f32_16x16x32_bf16 v[98:101], v[168:171], v[206:209], v[98:101]
	v_mfma_f32_16x16x32_bf16 v[86:89], v[156:159], v[214:217], v[86:89]
	v_mfma_f32_16x16x32_bf16 v[82:85], v[168:171], v[214:217], v[82:85]
	v_mfma_f32_16x16x32_bf16 v[70:73], v[156:159], v[236:239], v[70:73]
	v_mfma_f32_16x16x32_bf16 v[66:69], v[168:171], v[236:239], v[66:69]
	v_mfma_f32_16x16x32_bf16 v[118:121], v[160:163], v[180:183], v[118:121]
	v_mfma_f32_16x16x32_bf16 v[114:117], v[172:175], v[180:183], v[114:117]
	v_mfma_f32_16x16x32_bf16 v[102:105], v[160:163], v[210:213], v[102:105]
	v_mfma_f32_16x16x32_bf16 v[98:101], v[172:175], v[210:213], v[98:101]
	v_mfma_f32_16x16x32_bf16 v[86:89], v[160:163], v[218:221], v[86:89]
	v_mfma_f32_16x16x32_bf16 v[82:85], v[172:175], v[218:221], v[82:85]
	v_mfma_f32_16x16x32_bf16 v[70:73], v[160:163], v[240:243], v[70:73]
	v_mfma_f32_16x16x32_bf16 v[66:69], v[172:175], v[240:243], v[66:69]
	s_barrier
	s_add_i32 s10, s12, s67
	s_mov_b32 m0, s10
	ds_read_b128 v[176:179], v166 offset:49152
	ds_read_b128 v[180:183], v166 offset:50176
	ds_read_b128 v[206:209], v166 offset:51200
	ds_read_b128 v[210:213], v166 offset:52224
	ds_read_b128 v[214:217], v166 offset:53248
	ds_read_b128 v[218:221], v166 offset:54272
	ds_read_b128 v[236:239], v166 offset:55296
	ds_read_b128 v[240:243], v166 offset:56320
	s_add_u32 s100, s46, s60
	s_addc_u32 s101, s47, s61
	global_load_lds_dwordx4 v146, s[100:101]
	s_add_i32 m0, s10, 0x2000
	s_add_u32 s10, s46, 0x80080
	s_addc_u32 s11, s47, 0
	s_add_i32 s12, s13, s67
	global_load_lds_dwordx4 v142, s[100:101]
	s_mov_b32 m0, s12
	s_nop 0
	global_load_lds_dwordx4 v146, s[10:11]
	s_add_i32 m0, s12, 0x2000
	s_nop 0
	global_load_lds_dwordx4 v142, s[10:11]
	s_mov_b32 m0, s82
	s_add_u32 s100, vcc_lo, s60
	s_addc_u32 s101, vcc_hi, s61
	global_load_lds_dwordx4 v190, s[100:101]
	s_mov_b32 m0, s42
	s_nop 0
	global_load_lds_dwordx4 v144, s[100:101]
	s_waitcnt vmcnt(8)
	s_waitcnt lgkmcnt(0)
	s_barrier
	v_mfma_f32_16x16x32_bf16 v[62:65], v[130:133], v[176:179], v[62:65]
	v_mfma_f32_16x16x32_bf16 v[58:61], v[138:141], v[176:179], v[58:61]
	v_mfma_f32_16x16x32_bf16 v[46:49], v[130:133], v[206:209], v[46:49]
	v_mfma_f32_16x16x32_bf16 v[42:45], v[138:141], v[206:209], v[42:45]
	v_mfma_f32_16x16x32_bf16 v[30:33], v[130:133], v[214:217], v[30:33]
	v_mfma_f32_16x16x32_bf16 v[26:29], v[138:141], v[214:217], v[26:29]
	v_mfma_f32_16x16x32_bf16 v[14:17], v[130:133], v[236:239], v[14:17]
	v_mfma_f32_16x16x32_bf16 v[10:13], v[138:141], v[236:239], v[10:13]
	v_mfma_f32_16x16x32_bf16 v[62:65], v[134:137], v[180:183], v[62:65]
	v_mfma_f32_16x16x32_bf16 v[58:61], v[152:155], v[180:183], v[58:61]
	v_mfma_f32_16x16x32_bf16 v[46:49], v[134:137], v[210:213], v[46:49]
	v_mfma_f32_16x16x32_bf16 v[42:45], v[152:155], v[210:213], v[42:45]
	v_mfma_f32_16x16x32_bf16 v[30:33], v[134:137], v[218:221], v[30:33]
	v_mfma_f32_16x16x32_bf16 v[26:29], v[152:155], v[218:221], v[26:29]
	v_mfma_f32_16x16x32_bf16 v[14:17], v[134:137], v[240:243], v[14:17]
	v_mfma_f32_16x16x32_bf16 v[10:13], v[152:155], v[240:243], v[10:13]
	v_mfma_f32_16x16x32_bf16 v[54:57], v[156:159], v[176:179], v[54:57]
	v_mfma_f32_16x16x32_bf16 v[50:53], v[168:171], v[176:179], v[50:53]
	v_mfma_f32_16x16x32_bf16 v[38:41], v[156:159], v[206:209], v[38:41]
	v_mfma_f32_16x16x32_bf16 v[34:37], v[168:171], v[206:209], v[34:37]
	v_mfma_f32_16x16x32_bf16 v[22:25], v[156:159], v[214:217], v[22:25]
	v_mfma_f32_16x16x32_bf16 v[18:21], v[168:171], v[214:217], v[18:21]
	v_mfma_f32_16x16x32_bf16 v[6:9], v[156:159], v[236:239], v[6:9]
	v_mfma_f32_16x16x32_bf16 v[2:5], v[168:171], v[236:239], v[2:5]
	v_mfma_f32_16x16x32_bf16 v[54:57], v[160:163], v[180:183], v[54:57]
	v_mfma_f32_16x16x32_bf16 v[50:53], v[172:175], v[180:183], v[50:53]
	v_mfma_f32_16x16x32_bf16 v[38:41], v[160:163], v[210:213], v[38:41]
	v_mfma_f32_16x16x32_bf16 v[34:37], v[172:175], v[210:213], v[34:37]
	v_mfma_f32_16x16x32_bf16 v[22:25], v[160:163], v[218:221], v[22:25]
	v_mfma_f32_16x16x32_bf16 v[18:21], v[172:175], v[218:221], v[18:21]
	v_mfma_f32_16x16x32_bf16 v[6:9], v[160:163], v[240:243], v[6:9]
	v_mfma_f32_16x16x32_bf16 v[2:5], v[172:175], v[240:243], v[2:5]
	s_barrier
	s_add_i32 s9, s9, 2
	s_add_u32 s38, s38, 0x100
	s_addc_u32 s39, s39, 0
	s_add_u32 s7, s7, 0x100
	s_addc_u32 s8, s8, 0
	s_cmpk_gt_u32 s9, 0x7d
	s_cbranch_scc0 .LBB0_1071
	s_and_b64 vcc, exec, s[72:73]
	s_cbranch_vccz .LBB0_1074
	s_barrier

; #define PG8_STAGE(bufoff, gbase, voff) do { _Pragma("unroll") for (int _i = 0; _i < 2; ++_i) \
;         __builtin_amdgcn_global_load_lds((const unsigned*)((const char*)(gbase) + (voff)[_i]), (PG8_LAS unsigned*)(lds + (bufoff) + ldsw + _i * 8192), 16, 0, 0); } while (0)
; #define PG8_LDA(dst, b, h) do { _Pragma("unroll") for (int m = 0; m < 4; ++m) _Pragma("unroll") for (int k = 0; k < 2; ++k) dst[m][k] = *(const PG8_LAS bf16x8*)(lds + PG8_SA(b, h) + aoff + m * 2048 + k * 1024); } while (0)
; #define PG8_LDB(dst, b, h) do { _Pragma("unroll") for (int n = 0; n < 2; ++n) _Pragma("unroll") for (int k = 0; k < 2; ++k) dst[n][k] = *(const PG8_LAS bf16x8*)(lds + PG8_SB(b, h) + boff + n * 2048 + k * 1024); } while (0)
; #define PG8_WAIT_V(n) asm volatile("s_waitcnt vmcnt(" #n ")" ::: "memory")
; #define PG8_WAIT_L(n) asm volatile("s_waitcnt lgkmcnt(" #n ")" ::: "memory")
; #define PG8_BAR __builtin_amdgcn_s_barrier()
; #define PG8_SCHED __builtin_amdgcn_sched_barrier(0)
; template <class Epi, class Sched, bool ALIGN_EPI = false, bool SP2 = false>
; __device__ __forceinline__ void gemm_phase(PG8_LAS unsigned char* lds, const Gemm g, const Sched& S, const Epi& E) {
;     ...
;         const bool has_next = S.next(ui + 1, nxt);
;         const char* nA = has_next ? (const char*)g.A + (size_t)nxt.pm * tstep : cA; const char* nB = has_next ? (const char*)g.Bt + (size_t)nxt.pn * tstep : cB;
;         for (int t = 0; t < nt; t += 2) {
;             const bool last = (t == nt - 2);
;             const char* a1 = cA + (size_t)(t + 1) * kstep;
;             const char* a2 = last ? nA : cA + (size_t)(t + 2) * kstep; const char* b2 = last ? nB : cB + (size_t)(t + 2) * kstep;
;             const char* a3 = a2 + kstep; const char* b3 = b2 + kstep;
;             if (last && has_next) S.a_ready(nxt);
;             if constexpr (SP2) {
;             PG8_LDB(B0, 0, 0); PG8_LDB(B1, 0, 1); PG8_SCHED; PG8_LDA(At, 0, 0); PG8_STAGE(PG8_SA(1, 1), a1 + hstep, voffA);
;             PG8_WAIT_V(8); PG8_WAIT_L(0); PG8_BAR; PG8_MMA(0, 0, At, B0); PG8_MMA(0, 1, At, B1); PG8_BAR; PG8_SCHED;
;             PG8_LDA(At, 0, 1); PG8_STAGE(PG8_SB(0, 0), b2, voffB); PG8_STAGE(PG8_SB(0, 1), b2 + hstepB, voffB); PG8_STAGE(PG8_SA(0, 0), a2, voffA);
;             PG8_WAIT_V(8); PG8_WAIT_L(0); PG8_BAR; PG8_MMA(1, 0, At, B0); PG8_MMA(1, 1, At, B1); PG8_BAR; PG8_SCHED;
.LBB0_1232:
	s_add_u32 s36, s80, 0x100
	s_addc_u32 s37, s81, 0
	s_ashr_i32 s73, s72, 31
	s_lshl_b64 s[4:5], s[72:73], 20
	s_add_u32 s78, s0, s4
	s_addc_u32 s79, s1, s5
	s_and_b64 s[4:5], s[46:47], exec
	s_cselect_b32 s4, s79, s69
	s_cselect_b32 s5, s78, s68
	s_ashr_i32 s71, s70, 31
	s_lshl_b64 s[6:7], s[70:71], 20
	s_add_u32 s76, s34, s6
	s_addc_u32 s77, s35, s7
	s_and_b64 s[6:7], s[46:47], exec
	s_cselect_b32 s6, s77, s81
	s_cselect_b32 s7, s76, s80
	s_add_u32 s8, s68, 0x80080
	s_addc_u32 s9, s69, 0
	v_lshl_add_u64 v[140:141], s[8:9], 0, v[136:137]
	v_lshl_add_u64 v[142:143], s[8:9], 0, v[138:139]
	s_mov_b32 s8, -2
	s_mov_b64 s[80:81], 0
	v_add_u32_e32 v186, 0x10000, v145
	v_add_u32_e32 v187, 0x14000, v145
	v_add_u32_e32 v198, 0x18000, v145
	v_add_u32_e32 v199, 0x1c000, v145
	s_add_u32 s9, s68, s80
	s_addc_u32 s10, s69, s81
	s_add_u32 s9, s9, 0x100
	s_addc_u32 s10, s10, 0
	s_add_u32 s100, s9, 0x7ff80
	s_addc_u32 s101, s10, 0
	s_add_u32 s11, s36, s80
	s_addc_u32 s12, s37, s81
	s_add_i32 s13, 0, 0x10000
	s_cmpk_eq_i32 s80, 0xf00
	s_cselect_b32 s93, s4, s10
	s_cselect_b32 s92, s5, s9
	s_cselect_b32 s85, s6, s12
	s_cselect_b32 s84, s7, s11
	s_add_i32 s9, 0, 0x14000
	ds_read_b128 v[152:155], v186
	ds_read_b128 v[156:159], v186 offset:1024
	ds_read_b128 v[160:163], v186 offset:2048
	ds_read_b128 v[164:167], v186 offset:3072
	ds_read_b128 v[168:171], v187
	ds_read_b128 v[172:175], v187 offset:1024
	ds_read_b128 v[176:179], v187 offset:2048
	ds_read_b128 v[180:183], v187 offset:3072
	s_add_i32 m0, s51, 0xc000
	ds_read_b128 v[206:209], v151
	ds_read_b128 v[210:213], v151 offset:1024
	ds_read_b128 v[214:217], v151 offset:2048
	ds_read_b128 v[218:221], v151 offset:3072
	ds_read_b128 v[236:239], v151 offset:4096
	ds_read_b128 v[240:243], v151 offset:5120
	ds_read_b128 v[244:247], v151 offset:6144
	ds_read_b128 v[194:197], v151 offset:7168
	global_load_lds_dwordx4 v136, s[100:101]
	s_add_i32 m0, s51, 0xe000
	s_nop 0
	global_load_lds_dwordx4 v138, s[100:101]
	s_waitcnt vmcnt(8)
	s_waitcnt lgkmcnt(0)
	s_barrier
	v_mfma_f32_16x16x32_bf16 v[126:129], v[152:155], v[206:209], 0
	v_mfma_f32_16x16x32_bf16 v[122:125], v[160:163], v[206:209], 0
	v_mfma_f32_16x16x32_bf16 v[118:121], v[152:155], v[214:217], 0
	v_mfma_f32_16x16x32_bf16 v[114:117], v[160:163], v[214:217], 0
	v_mfma_f32_16x16x32_bf16 v[110:113], v[152:155], v[236:239], 0
	v_mfma_f32_16x16x32_bf16 v[106:109], v[160:163], v[236:239], 0
	v_mfma_f32_16x16x32_bf16 v[102:105], v[152:155], v[244:247], 0
	v_mfma_f32_16x16x32_bf16 v[98:101], v[160:163], v[244:247], 0
	v_mfma_f32_16x16x32_bf16 v[126:129], v[156:159], v[210:213], v[126:129]
	v_mfma_f32_16x16x32_bf16 v[122:125], v[164:167], v[210:213], v[122:125]
	v_mfma_f32_16x16x32_bf16 v[118:121], v[156:159], v[218:221], v[118:121]
	v_mfma_f32_16x16x32_bf16 v[114:117], v[164:167], v[218:221], v[114:117]
	v_mfma_f32_16x16x32_bf16 v[110:113], v[156:159], v[240:243], v[110:113]
	v_mfma_f32_16x16x32_bf16 v[106:109], v[164:167], v[240:243], v[106:109]
	v_mfma_f32_16x16x32_bf16 v[102:105], v[156:159], v[194:197], v[102:105]
	v_mfma_f32_16x16x32_bf16 v[98:101], v[164:167], v[194:197], v[98:101]
	v_mfma_f32_16x16x32_bf16 v[94:97], v[168:171], v[206:209], 0
	v_mfma_f32_16x16x32_bf16 v[90:93], v[176:179], v[206:209], 0
	v_mfma_f32_16x16x32_bf16 v[86:89], v[168:171], v[214:217], 0
	v_mfma_f32_16x16x32_bf16 v[82:85], v[176:179], v[214:217], 0
	v_mfma_f32_16x16x32_bf16 v[78:81], v[168:171], v[236:239], 0
	v_mfma_f32_16x16x32_bf16 v[74:77], v[176:179], v[236:239], 0
	v_mfma_f32_16x16x32_bf16 v[70:73], v[168:171], v[244:247], 0
	v_mfma_f32_16x16x32_bf16 v[66:69], v[176:179], v[244:247], 0
	v_mfma_f32_16x16x32_bf16 v[94:97], v[172:175], v[210:213], v[94:97]
	v_mfma_f32_16x16x32_bf16 v[90:93], v[180:183], v[210:213], v[90:93]
	v_mfma_f32_16x16x32_bf16 v[86:89], v[172:175], v[218:221], v[86:89]
	v_mfma_f32_16x16x32_bf16 v[82:85], v[180:183], v[218:221], v[82:85]
	v_mfma_f32_16x16x32_bf16 v[78:81], v[172:175], v[240:243], v[78:81]
	v_mfma_f32_16x16x32_bf16 v[74:77], v[180:183], v[240:243], v[74:77]
	v_mfma_f32_16x16x32_bf16 v[70:73], v[172:175], v[194:197], v[70:73]
	v_mfma_f32_16x16x32_bf16 v[66:69], v[180:183], v[194:197], v[66:69]
	s_barrier
	s_add_i32 s10, s13, s42
	s_mov_b32 m0, s10
	ds_read_b128 v[194:197], v151 offset:16384
	ds_read_b128 v[206:209], v151 offset:17408
	ds_read_b128 v[210:213], v151 offset:18432
	ds_read_b128 v[214:217], v151 offset:19456
	ds_read_b128 v[218:221], v151 offset:20480
	ds_read_b128 v[236:239], v151 offset:21504
	ds_read_b128 v[240:243], v151 offset:22528
	ds_read_b128 v[244:247], v151 offset:23552
	global_load_lds_dwordx4 v130, s[84:85]
	s_add_i32 m0, s10, 0x2000
	s_add_u32 s10, s84, 0x20000
	s_addc_u32 s11, s85, 0
	s_add_i32 s9, s9, s42
	global_load_lds_dwordx4 v134, s[84:85]
	s_mov_b32 m0, s9
	s_nop 0
	global_load_lds_dwordx4 v130, s[10:11]
	s_add_i32 m0, s9, 0x2000
	s_nop 0
	global_load_lds_dwordx4 v134, s[10:11]
	s_mov_b32 m0, s51
	s_nop 0
	global_load_lds_dwordx4 v190, s[92:93]
	s_mov_b32 m0, s67
	s_nop 0
	global_load_lds_dwordx4 v132, s[92:93]
	s_nop 0
	s_waitcnt vmcnt(8)
	s_waitcnt lgkmcnt(0)
	s_barrier
; #define PG8_STAGE(bufoff, gbase, voff) do { _Pragma("unroll") for (int _i = 0; _i < 2; ++_i) \
;         __builtin_amdgcn_global_load_lds((const unsigned*)((const char*)(gbase) + (voff)[_i]), (PG8_LAS unsigned*)(lds + (bufoff) + ldsw + _i * 8192), 16, 0, 0); } while (0)
; #define PG8_LDA(dst, b, h) do { _Pragma("unroll") for (int m = 0; m < 4; ++m) _Pragma("unroll") for (int k = 0; k < 2; ++k) dst[m][k] = *(const PG8_LAS bf16x8*)(lds + PG8_SA(b, h) + aoff + m * 2048 + k * 1024); } while (0)
; #define PG8_LDB(dst, b, h) do { _Pragma("unroll") for (int n = 0; n < 2; ++n) _Pragma("unroll") for (int k = 0; k < 2; ++k) dst[n][k] = *(const PG8_LAS bf16x8*)(lds + PG8_SB(b, h) + boff + n * 2048 + k * 1024); } while (0)
; #define PG8_MMA(ai, bj, At, Bt) do { __builtin_amdgcn_s_setprio(1); _Pragma("unroll") for (int m = 0; m < 4; ++m) _Pragma("unroll") for (int n = 0; n < 2; ++n) _Pragma("unroll") for (int k = 0; k < 2; ++k) \
;         acc[ai][bj][m][n] = __builtin_amdgcn_mfma_f32_16x16x32_bf16(Bt[n][k], At[m][k], acc[ai][bj][m][n], 0, 0, 0); __builtin_amdgcn_s_setprio(0); } while (0)
; #define PG8_WAIT_V(n) asm volatile("s_waitcnt vmcnt(" #n ")" ::: "memory")
; #define PG8_WAIT_L(n) asm volatile("s_waitcnt lgkmcnt(" #n ")" ::: "memory")
; #define PG8_BAR __builtin_amdgcn_s_barrier()
; #define PG8_SCHED __builtin_amdgcn_sched_barrier(0)
; template <class Epi, class Sched, bool ALIGN_EPI = false, bool SP2 = false>
; __device__ __forceinline__ void gemm_phase(PG8_LAS unsigned char* lds, const Gemm g, const Sched& S, const Epi& E) {
;     ...
;             PG8_WAIT_V(8); PG8_WAIT_L(0); PG8_BAR; PG8_MMA(1, 0, At, B0); PG8_MMA(1, 1, At, B1); PG8_BAR; PG8_SCHED;
;             PG8_LDB(B0, 1, 0); PG8_LDB(B1, 1, 1); PG8_SCHED; PG8_LDA(At, 1, 0); PG8_STAGE(PG8_SA(0, 1), a2 + hstep, voffA);
;             PG8_WAIT_V(8); PG8_WAIT_L(0); PG8_BAR; PG8_MMA(0, 0, At, B0); PG8_MMA(0, 1, At, B1); PG8_BAR; PG8_SCHED;
	v_mfma_f32_16x16x32_bf16 v[62:65], v[152:155], v[194:197], 0
	v_mfma_f32_16x16x32_bf16 v[58:61], v[160:163], v[194:197], 0
	v_mfma_f32_16x16x32_bf16 v[54:57], v[152:155], v[210:213], 0
	v_mfma_f32_16x16x32_bf16 v[50:53], v[160:163], v[210:213], 0
	v_mfma_f32_16x16x32_bf16 v[46:49], v[152:155], v[218:221], 0
	v_mfma_f32_16x16x32_bf16 v[42:45], v[160:163], v[218:221], 0
	v_mfma_f32_16x16x32_bf16 v[38:41], v[152:155], v[240:243], 0
	v_mfma_f32_16x16x32_bf16 v[34:37], v[160:163], v[240:243], 0
	v_mfma_f32_16x16x32_bf16 v[62:65], v[156:159], v[206:209], v[62:65]
	v_mfma_f32_16x16x32_bf16 v[58:61], v[164:167], v[206:209], v[58:61]
	v_mfma_f32_16x16x32_bf16 v[54:57], v[156:159], v[214:217], v[54:57]
	v_mfma_f32_16x16x32_bf16 v[50:53], v[164:167], v[214:217], v[50:53]
	v_mfma_f32_16x16x32_bf16 v[46:49], v[156:159], v[236:239], v[46:49]
	v_mfma_f32_16x16x32_bf16 v[42:45], v[164:167], v[236:239], v[42:45]
	v_mfma_f32_16x16x32_bf16 v[38:41], v[156:159], v[244:247], v[38:41]
	v_mfma_f32_16x16x32_bf16 v[34:37], v[164:167], v[244:247], v[34:37]
	v_mfma_f32_16x16x32_bf16 v[30:33], v[168:171], v[194:197], 0
	v_mfma_f32_16x16x32_bf16 v[26:29], v[176:179], v[194:197], 0
	v_mfma_f32_16x16x32_bf16 v[22:25], v[168:171], v[210:213], 0
	v_mfma_f32_16x16x32_bf16 v[18:21], v[176:179], v[210:213], 0
	v_mfma_f32_16x16x32_bf16 v[14:17], v[168:171], v[218:221], 0
	v_mfma_f32_16x16x32_bf16 v[10:13], v[176:179], v[218:221], 0
	v_mfma_f32_16x16x32_bf16 v[6:9], v[168:171], v[240:243], 0
	v_mfma_f32_16x16x32_bf16 v[2:5], v[176:179], v[240:243], 0
	v_mfma_f32_16x16x32_bf16 v[30:33], v[172:175], v[206:209], v[30:33]
	v_mfma_f32_16x16x32_bf16 v[26:29], v[180:183], v[206:209], v[26:29]
	v_mfma_f32_16x16x32_bf16 v[22:25], v[172:175], v[214:217], v[22:25]
	v_mfma_f32_16x16x32_bf16 v[18:21], v[180:183], v[214:217], v[18:21]
	v_mfma_f32_16x16x32_bf16 v[14:17], v[172:175], v[236:239], v[14:17]
	v_mfma_f32_16x16x32_bf16 v[10:13], v[180:183], v[236:239], v[10:13]
	v_mfma_f32_16x16x32_bf16 v[6:9], v[172:175], v[244:247], v[6:9]
	v_mfma_f32_16x16x32_bf16 v[2:5], v[180:183], v[244:247], v[2:5]
	s_barrier
	s_add_i32 s9, 0, 0x18000
	s_add_i32 s12, 0, 0x1c000
	ds_read_b128 v[152:155], v198
	ds_read_b128 v[156:159], v198 offset:1024
	ds_read_b128 v[160:163], v198 offset:2048
	ds_read_b128 v[164:167], v198 offset:3072
	ds_read_b128 v[168:171], v199
	ds_read_b128 v[172:175], v199 offset:1024
	ds_read_b128 v[176:179], v199 offset:2048
	ds_read_b128 v[180:183], v199 offset:3072
	s_add_u32 s10, s92, 0x80000
	s_addc_u32 s11, s93, 0
	s_mov_b32 m0, s74
	ds_read_b128 v[194:197], v151 offset:32768
	ds_read_b128 v[206:209], v151 offset:33792
	ds_read_b128 v[210:213], v151 offset:34816
	ds_read_b128 v[214:217], v151 offset:35840
	ds_read_b128 v[218:221], v151 offset:36864
	ds_read_b128 v[236:239], v151 offset:37888
	ds_read_b128 v[240:243], v151 offset:38912
	ds_read_b128 v[244:247], v151 offset:39936
	global_load_lds_dwordx4 v190, s[10:11]
	s_mov_b32 m0, s75
	s_nop 0
	global_load_lds_dwordx4 v132, s[10:11]
	s_waitcnt vmcnt(8)
	s_waitcnt lgkmcnt(0)
	s_barrier
	v_mfma_f32_16x16x32_bf16 v[126:129], v[152:155], v[194:197], v[126:129]
	v_mfma_f32_16x16x32_bf16 v[122:125], v[160:163], v[194:197], v[122:125]
	v_mfma_f32_16x16x32_bf16 v[118:121], v[152:155], v[210:213], v[118:121]
	v_mfma_f32_16x16x32_bf16 v[114:117], v[160:163], v[210:213], v[114:117]
	v_mfma_f32_16x16x32_bf16 v[110:113], v[152:155], v[218:221], v[110:113]
	v_mfma_f32_16x16x32_bf16 v[106:109], v[160:163], v[218:221], v[106:109]
	v_mfma_f32_16x16x32_bf16 v[102:105], v[152:155], v[240:243], v[102:105]
	v_mfma_f32_16x16x32_bf16 v[98:101], v[160:163], v[240:243], v[98:101]
	v_mfma_f32_16x16x32_bf16 v[126:129], v[156:159], v[206:209], v[126:129]
	v_mfma_f32_16x16x32_bf16 v[122:125], v[164:167], v[206:209], v[122:125]
	v_mfma_f32_16x16x32_bf16 v[118:121], v[156:159], v[214:217], v[118:121]
	v_mfma_f32_16x16x32_bf16 v[114:117], v[164:167], v[214:217], v[114:117]
	v_mfma_f32_16x16x32_bf16 v[110:113], v[156:159], v[236:239], v[110:113]
	v_mfma_f32_16x16x32_bf16 v[106:109], v[164:167], v[236:239], v[106:109]
	v_mfma_f32_16x16x32_bf16 v[102:105], v[156:159], v[244:247], v[102:105]
	v_mfma_f32_16x16x32_bf16 v[98:101], v[164:167], v[244:247], v[98:101]
	v_mfma_f32_16x16x32_bf16 v[94:97], v[168:171], v[194:197], v[94:97]
	v_mfma_f32_16x16x32_bf16 v[90:93], v[176:179], v[194:197], v[90:93]
	v_mfma_f32_16x16x32_bf16 v[86:89], v[168:171], v[210:213], v[86:89]
	v_mfma_f32_16x16x32_bf16 v[82:85], v[176:179], v[210:213], v[82:85]
	v_mfma_f32_16x16x32_bf16 v[78:81], v[168:171], v[218:221], v[78:81]
	v_mfma_f32_16x16x32_bf16 v[74:77], v[176:179], v[218:221], v[74:77]
	v_mfma_f32_16x16x32_bf16 v[70:73], v[168:171], v[240:243], v[70:73]
	v_mfma_f32_16x16x32_bf16 v[66:69], v[176:179], v[240:243], v[66:69]
	v_mfma_f32_16x16x32_bf16 v[94:97], v[172:175], v[206:209], v[94:97]
	v_mfma_f32_16x16x32_bf16 v[90:93], v[180:183], v[206:209], v[90:93]
	v_mfma_f32_16x16x32_bf16 v[86:89], v[172:175], v[214:217], v[86:89]
	v_mfma_f32_16x16x32_bf16 v[82:85], v[180:183], v[214:217], v[82:85]
	v_mfma_f32_16x16x32_bf16 v[78:81], v[172:175], v[236:239], v[78:81]
	v_mfma_f32_16x16x32_bf16 v[74:77], v[180:183], v[236:239], v[74:77]
	v_mfma_f32_16x16x32_bf16 v[70:73], v[172:175], v[244:247], v[70:73]
	v_mfma_f32_16x16x32_bf16 v[66:69], v[180:183], v[244:247], v[66:69]
	s_barrier
; #define PG8_STAGE(bufoff, gbase, voff) do { _Pragma("unroll") for (int _i = 0; _i < 2; ++_i) \
;         __builtin_amdgcn_global_load_lds((const unsigned*)((const char*)(gbase) + (voff)[_i]), (PG8_LAS unsigned*)(lds + (bufoff) + ldsw + _i * 8192), 16, 0, 0); } while (0)
; #define PG8_LDA(dst, b, h) do { _Pragma("unroll") for (int m = 0; m < 4; ++m) _Pragma("unroll") for (int k = 0; k < 2; ++k) dst[m][k] = *(const PG8_LAS bf16x8*)(lds + PG8_SA(b, h) + aoff + m * 2048 + k * 1024); } while (0)
; #define PG8_LDB(dst, b, h) do { _Pragma("unroll") for (int n = 0; n < 2; ++n) _Pragma("unroll") for (int k = 0; k < 2; ++k) dst[n][k] = *(const PG8_LAS bf16x8*)(lds + PG8_SB(b, h) + boff + n * 2048 + k * 1024); } while (0)
; #define PG8_WAIT_V(n) asm volatile("s_waitcnt vmcnt(" #n ")" ::: "memory")
; template <class Epi, class Sched, bool ALIGN_EPI = false, bool SP2 = false>
; __device__ __forceinline__ void gemm_phase(PG8_LAS unsigned char* lds, const Gemm g, const Sched& S, const Epi& E) {
;     ...
;             const char* a1 = cA + (size_t)(t + 1) * kstep;
;             const char* a2 = last ? nA : cA + (size_t)(t + 2) * kstep; const char* b2 = last ? nB : cB + (size_t)(t + 2) * kstep;
;             const char* a3 = a2 + kstep; const char* b3 = b2 + kstep;
;             if (last && has_next) S.a_ready(nxt);
;             if constexpr (SP2) {
;             PG8_LDB(B0, 0, 0); PG8_LDB(B1, 0, 1); PG8_SCHED; PG8_LDA(At, 0, 0); PG8_STAGE(PG8_SA(1, 1), a1 + hstep, voffA);
;             PG8_WAIT_V(8); PG8_WAIT_L(0); PG8_BAR; PG8_MMA(0, 0, At, B0); PG8_MMA(0, 1, At, B1); PG8_BAR; PG8_SCHED;
;             PG8_LDA(At, 0, 1); PG8_STAGE(PG8_SB(0, 0), b2, voffB); PG8_STAGE(PG8_SB(0, 1), b2 + hstepB, voffB); PG8_STAGE(PG8_SA(0, 0), a2, voffA);
;             PG8_WAIT_V(8); PG8_WAIT_L(0); PG8_BAR; PG8_MMA(1, 0, At, B0); PG8_MMA(1, 1, At, B1); PG8_BAR; PG8_SCHED;
;             PG8_LDB(B0, 1, 0); PG8_LDB(B1, 1, 1); PG8_SCHED; PG8_LDA(At, 1, 0); PG8_STAGE(PG8_SA(0, 1), a2 + hstep, voffA);
;             PG8_WAIT_V(8); PG8_WAIT_L(0); PG8_BAR; PG8_MMA(0, 0, At, B0); PG8_MMA(0, 1, At, B1); PG8_BAR; PG8_SCHED;
;             PG8_LDA(At, 1, 1); PG8_STAGE(PG8_SB(1, 0), b3, voffB); PG8_STAGE(PG8_SB(1, 1), b3 + hstepB, voffB); PG8_STAGE(PG8_SA(1, 0), a3, voffA);
;             PG8_WAIT_V(8); PG8_WAIT_L(0); PG8_BAR; PG8_MMA(1, 0, At, B0); PG8_MMA(1, 1, At, B1); PG8_BAR; PG8_SCHED;
	s_add_i32 s9, s9, s42
	s_mov_b32 m0, s9
	ds_read_b128 v[194:197], v151 offset:49152
	ds_read_b128 v[206:209], v151 offset:50176
	ds_read_b128 v[210:213], v151 offset:51200
	ds_read_b128 v[214:217], v151 offset:52224
	ds_read_b128 v[218:221], v151 offset:53248
	ds_read_b128 v[236:239], v151 offset:54272
	ds_read_b128 v[240:243], v151 offset:55296
	ds_read_b128 v[244:247], v151 offset:56320
	s_add_u32 s100, s84, s60
	s_addc_u32 s101, s85, s61
	global_load_lds_dwordx4 v130, s[100:101]
	s_add_i32 m0, s9, 0x2000
	s_add_u32 s10, s84, 0x20080
	s_addc_u32 s11, s85, 0
	s_add_i32 s9, s12, s42
	global_load_lds_dwordx4 v134, s[100:101]
	s_mov_b32 m0, s9
	s_nop 0
	global_load_lds_dwordx4 v130, s[10:11]
	s_add_i32 m0, s9, 0x2000
	s_nop 0
	global_load_lds_dwordx4 v134, s[10:11]
	s_mov_b32 m0, s82
	s_add_u32 s100, s92, s60
	s_addc_u32 s101, s93, s61
	global_load_lds_dwordx4 v190, s[100:101]
	s_mov_b32 m0, s86
	s_nop 0
	global_load_lds_dwordx4 v132, s[100:101]
	s_waitcnt vmcnt(8)
	s_waitcnt lgkmcnt(0)
	s_barrier
	v_mfma_f32_16x16x32_bf16 v[62:65], v[152:155], v[194:197], v[62:65]
	v_mfma_f32_16x16x32_bf16 v[58:61], v[160:163], v[194:197], v[58:61]
	v_mfma_f32_16x16x32_bf16 v[54:57], v[152:155], v[210:213], v[54:57]
	v_mfma_f32_16x16x32_bf16 v[50:53], v[160:163], v[210:213], v[50:53]
	v_mfma_f32_16x16x32_bf16 v[46:49], v[152:155], v[218:221], v[46:49]
	v_mfma_f32_16x16x32_bf16 v[42:45], v[160:163], v[218:221], v[42:45]
	v_mfma_f32_16x16x32_bf16 v[38:41], v[152:155], v[240:243], v[38:41]
	v_mfma_f32_16x16x32_bf16 v[34:37], v[160:163], v[240:243], v[34:37]
	v_mfma_f32_16x16x32_bf16 v[62:65], v[156:159], v[206:209], v[62:65]
	v_mfma_f32_16x16x32_bf16 v[58:61], v[164:167], v[206:209], v[58:61]
	v_mfma_f32_16x16x32_bf16 v[54:57], v[156:159], v[214:217], v[54:57]
	v_mfma_f32_16x16x32_bf16 v[50:53], v[164:167], v[214:217], v[50:53]
	v_mfma_f32_16x16x32_bf16 v[46:49], v[156:159], v[236:239], v[46:49]
	v_mfma_f32_16x16x32_bf16 v[42:45], v[164:167], v[236:239], v[42:45]
	v_mfma_f32_16x16x32_bf16 v[38:41], v[156:159], v[244:247], v[38:41]
	v_mfma_f32_16x16x32_bf16 v[34:37], v[164:167], v[244:247], v[34:37]
	v_mfma_f32_16x16x32_bf16 v[30:33], v[168:171], v[194:197], v[30:33]
	v_mfma_f32_16x16x32_bf16 v[26:29], v[176:179], v[194:197], v[26:29]
	v_mfma_f32_16x16x32_bf16 v[22:25], v[168:171], v[210:213], v[22:25]
	v_mfma_f32_16x16x32_bf16 v[18:21], v[176:179], v[210:213], v[18:21]
	v_mfma_f32_16x16x32_bf16 v[14:17], v[168:171], v[218:221], v[14:17]
	v_mfma_f32_16x16x32_bf16 v[10:13], v[176:179], v[218:221], v[10:13]
	v_mfma_f32_16x16x32_bf16 v[6:9], v[168:171], v[240:243], v[6:9]
	v_mfma_f32_16x16x32_bf16 v[2:5], v[176:179], v[240:243], v[2:5]
	v_mfma_f32_16x16x32_bf16 v[30:33], v[172:175], v[206:209], v[30:33]
	v_mfma_f32_16x16x32_bf16 v[26:29], v[180:183], v[206:209], v[26:29]
	v_mfma_f32_16x16x32_bf16 v[22:25], v[172:175], v[214:217], v[22:25]
	v_mfma_f32_16x16x32_bf16 v[18:21], v[180:183], v[214:217], v[18:21]
	v_mfma_f32_16x16x32_bf16 v[14:17], v[172:175], v[236:239], v[14:17]
	v_mfma_f32_16x16x32_bf16 v[10:13], v[180:183], v[236:239], v[10:13]
	v_mfma_f32_16x16x32_bf16 v[6:9], v[172:175], v[244:247], v[6:9]
	v_mfma_f32_16x16x32_bf16 v[2:5], v[180:183], v[244:247], v[2:5]
	s_barrier
	s_add_i32 s8, s8, 2
	s_add_u32 s80, s80, 0x100
	s_addc_u32 s81, s81, 0
	s_cmp_gt_u32 s8, 29
.LBB0_1233:
	s_add_u32 s9, s68, s80
	s_addc_u32 s10, s69, s81
	s_add_u32 s9, s9, 0x100
	s_addc_u32 s10, s10, 0
	s_add_u32 s100, s9, 0x7ff80
	s_addc_u32 s101, s10, 0
	s_add_u32 s11, s36, s80
	s_addc_u32 s12, s37, s81
	s_add_i32 s13, 0, 0x10000
	s_cmpk_eq_i32 s80, 0xf00
	s_cselect_b32 s93, s4, s10
	s_cselect_b32 s92, s5, s9
	s_cselect_b32 s85, s6, s12
	s_cselect_b32 s84, s7, s11
	s_add_i32 s9, 0, 0x14000
	ds_read_b128 v[152:155], v186
	ds_read_b128 v[156:159], v186 offset:1024
	ds_read_b128 v[160:163], v186 offset:2048
	ds_read_b128 v[164:167], v186 offset:3072
	ds_read_b128 v[168:171], v187
	ds_read_b128 v[172:175], v187 offset:1024
	ds_read_b128 v[176:179], v187 offset:2048
	ds_read_b128 v[180:183], v187 offset:3072
	s_add_i32 m0, s51, 0xc000
	ds_read_b128 v[206:209], v151
	ds_read_b128 v[210:213], v151 offset:1024
	ds_read_b128 v[214:217], v151 offset:2048
	ds_read_b128 v[218:221], v151 offset:3072
	ds_read_b128 v[236:239], v151 offset:4096
	ds_read_b128 v[240:243], v151 offset:5120
	ds_read_b128 v[244:247], v151 offset:6144
	ds_read_b128 v[194:197], v151 offset:7168
	global_load_lds_dwordx4 v136, s[100:101]
	s_add_i32 m0, s51, 0xe000
	s_nop 0
	global_load_lds_dwordx4 v138, s[100:101]
	s_nop 0
	s_waitcnt vmcnt(8)
	s_waitcnt lgkmcnt(0)
	s_barrier
; #define PG8_STAGE(bufoff, gbase, voff) do { _Pragma("unroll") for (int _i = 0; _i < 2; ++_i) \
;         __builtin_amdgcn_global_load_lds((const unsigned*)((const char*)(gbase) + (voff)[_i]), (PG8_LAS unsigned*)(lds + (bufoff) + ldsw + _i * 8192), 16, 0, 0); } while (0)
; #define PG8_LDA(dst, b, h) do { _Pragma("unroll") for (int m = 0; m < 4; ++m) _Pragma("unroll") for (int k = 0; k < 2; ++k) dst[m][k] = *(const PG8_LAS bf16x8*)(lds + PG8_SA(b, h) + aoff + m * 2048 + k * 1024); } while (0)
; #define PG8_MMA(ai, bj, At, Bt) do { __builtin_amdgcn_s_setprio(1); _Pragma("unroll") for (int m = 0; m < 4; ++m) _Pragma("unroll") for (int n = 0; n < 2; ++n) _Pragma("unroll") for (int k = 0; k < 2; ++k) \
;         acc[ai][bj][m][n] = __builtin_amdgcn_mfma_f32_16x16x32_bf16(Bt[n][k], At[m][k], acc[ai][bj][m][n], 0, 0, 0); __builtin_amdgcn_s_setprio(0); } while (0)
; #define PG8_WAIT_V(n) asm volatile("s_waitcnt vmcnt(" #n ")" ::: "memory")
; #define PG8_WAIT_L(n) asm volatile("s_waitcnt lgkmcnt(" #n ")" ::: "memory")
; #define PG8_BAR __builtin_amdgcn_s_barrier()
; #define PG8_SCHED __builtin_amdgcn_sched_barrier(0)
; template <class Epi, class Sched, bool ALIGN_EPI = false, bool SP2 = false>
; __device__ __forceinline__ void gemm_phase(PG8_LAS unsigned char* lds, const Gemm g, const Sched& S, const Epi& E) {
;     ...
;             PG8_WAIT_V(8); PG8_WAIT_L(0); PG8_BAR; PG8_MMA(0, 0, At, B0); PG8_MMA(0, 1, At, B1); PG8_BAR; PG8_SCHED;
;             PG8_LDA(At, 0, 1); PG8_STAGE(PG8_SB(0, 0), b2, voffB); PG8_STAGE(PG8_SB(0, 1), b2 + hstepB, voffB); PG8_STAGE(PG8_SA(0, 0), a2, voffA);
;             PG8_WAIT_V(8); PG8_WAIT_L(0); PG8_BAR; PG8_MMA(1, 0, At, B0); PG8_MMA(1, 1, At, B1); PG8_BAR; PG8_SCHED;
	v_mfma_f32_16x16x32_bf16 v[126:129], v[152:155], v[206:209], v[126:129]
	v_mfma_f32_16x16x32_bf16 v[122:125], v[160:163], v[206:209], v[122:125]
	v_mfma_f32_16x16x32_bf16 v[118:121], v[152:155], v[214:217], v[118:121]
	v_mfma_f32_16x16x32_bf16 v[114:117], v[160:163], v[214:217], v[114:117]
	v_mfma_f32_16x16x32_bf16 v[110:113], v[152:155], v[236:239], v[110:113]
	v_mfma_f32_16x16x32_bf16 v[106:109], v[160:163], v[236:239], v[106:109]
	v_mfma_f32_16x16x32_bf16 v[102:105], v[152:155], v[244:247], v[102:105]
	v_mfma_f32_16x16x32_bf16 v[98:101], v[160:163], v[244:247], v[98:101]
	v_mfma_f32_16x16x32_bf16 v[126:129], v[156:159], v[210:213], v[126:129]
	v_mfma_f32_16x16x32_bf16 v[122:125], v[164:167], v[210:213], v[122:125]
	v_mfma_f32_16x16x32_bf16 v[118:121], v[156:159], v[218:221], v[118:121]
	v_mfma_f32_16x16x32_bf16 v[114:117], v[164:167], v[218:221], v[114:117]
	v_mfma_f32_16x16x32_bf16 v[110:113], v[156:159], v[240:243], v[110:113]
	v_mfma_f32_16x16x32_bf16 v[106:109], v[164:167], v[240:243], v[106:109]
	v_mfma_f32_16x16x32_bf16 v[102:105], v[156:159], v[194:197], v[102:105]
	v_mfma_f32_16x16x32_bf16 v[98:101], v[164:167], v[194:197], v[98:101]
	v_mfma_f32_16x16x32_bf16 v[94:97], v[168:171], v[206:209], v[94:97]
	v_mfma_f32_16x16x32_bf16 v[90:93], v[176:179], v[206:209], v[90:93]
	v_mfma_f32_16x16x32_bf16 v[86:89], v[168:171], v[214:217], v[86:89]
	v_mfma_f32_16x16x32_bf16 v[82:85], v[176:179], v[214:217], v[82:85]
	v_mfma_f32_16x16x32_bf16 v[78:81], v[168:171], v[236:239], v[78:81]
	v_mfma_f32_16x16x32_bf16 v[74:77], v[176:179], v[236:239], v[74:77]
	v_mfma_f32_16x16x32_bf16 v[70:73], v[168:171], v[244:247], v[70:73]
	v_mfma_f32_16x16x32_bf16 v[66:69], v[176:179], v[244:247], v[66:69]
	v_mfma_f32_16x16x32_bf16 v[94:97], v[172:175], v[210:213], v[94:97]
	v_mfma_f32_16x16x32_bf16 v[90:93], v[180:183], v[210:213], v[90:93]
	v_mfma_f32_16x16x32_bf16 v[86:89], v[172:175], v[218:221], v[86:89]
	v_mfma_f32_16x16x32_bf16 v[82:85], v[180:183], v[218:221], v[82:85]
	v_mfma_f32_16x16x32_bf16 v[78:81], v[172:175], v[240:243], v[78:81]
	v_mfma_f32_16x16x32_bf16 v[74:77], v[180:183], v[240:243], v[74:77]
	v_mfma_f32_16x16x32_bf16 v[70:73], v[172:175], v[194:197], v[70:73]
	v_mfma_f32_16x16x32_bf16 v[66:69], v[180:183], v[194:197], v[66:69]
	s_barrier
	s_add_i32 s10, s13, s42
	s_mov_b32 m0, s10
	ds_read_b128 v[194:197], v151 offset:16384
	ds_read_b128 v[206:209], v151 offset:17408
	ds_read_b128 v[210:213], v151 offset:18432
	ds_read_b128 v[214:217], v151 offset:19456
	ds_read_b128 v[218:221], v151 offset:20480
	ds_read_b128 v[236:239], v151 offset:21504
	ds_read_b128 v[240:243], v151 offset:22528
	ds_read_b128 v[244:247], v151 offset:23552
	global_load_lds_dwordx4 v130, s[84:85]
	s_add_i32 m0, s10, 0x2000
	s_add_u32 s10, s84, 0x20000
	s_addc_u32 s11, s85, 0
	s_add_i32 s9, s9, s42
	global_load_lds_dwordx4 v134, s[84:85]
	s_mov_b32 m0, s9
	s_nop 0
	global_load_lds_dwordx4 v130, s[10:11]
	s_add_i32 m0, s9, 0x2000
	s_nop 0
	global_load_lds_dwordx4 v134, s[10:11]
	s_mov_b32 m0, s51
	s_nop 0
	global_load_lds_dwordx4 v190, s[92:93]
	s_mov_b32 m0, s67
	s_nop 0
	global_load_lds_dwordx4 v132, s[92:93]
	s_nop 0
	s_waitcnt vmcnt(8)
	s_waitcnt lgkmcnt(0)
	s_barrier
	v_mfma_f32_16x16x32_bf16 v[62:65], v[152:155], v[194:197], v[62:65]
	v_mfma_f32_16x16x32_bf16 v[58:61], v[160:163], v[194:197], v[58:61]
	v_mfma_f32_16x16x32_bf16 v[54:57], v[152:155], v[210:213], v[54:57]
	v_mfma_f32_16x16x32_bf16 v[50:53], v[160:163], v[210:213], v[50:53]
	v_mfma_f32_16x16x32_bf16 v[46:49], v[152:155], v[218:221], v[46:49]
	v_mfma_f32_16x16x32_bf16 v[42:45], v[160:163], v[218:221], v[42:45]
	v_mfma_f32_16x16x32_bf16 v[38:41], v[152:155], v[240:243], v[38:41]
	v_mfma_f32_16x16x32_bf16 v[34:37], v[160:163], v[240:243], v[34:37]
	v_mfma_f32_16x16x32_bf16 v[62:65], v[156:159], v[206:209], v[62:65]
	v_mfma_f32_16x16x32_bf16 v[58:61], v[164:167], v[206:209], v[58:61]
	v_mfma_f32_16x16x32_bf16 v[54:57], v[156:159], v[214:217], v[54:57]
	v_mfma_f32_16x16x32_bf16 v[50:53], v[164:167], v[214:217], v[50:53]
	v_mfma_f32_16x16x32_bf16 v[46:49], v[156:159], v[236:239], v[46:49]
	v_mfma_f32_16x16x32_bf16 v[42:45], v[164:167], v[236:239], v[42:45]
	v_mfma_f32_16x16x32_bf16 v[38:41], v[156:159], v[244:247], v[38:41]
	v_mfma_f32_16x16x32_bf16 v[34:37], v[164:167], v[244:247], v[34:37]
	v_mfma_f32_16x16x32_bf16 v[30:33], v[168:171], v[194:197], v[30:33]
	v_mfma_f32_16x16x32_bf16 v[26:29], v[176:179], v[194:197], v[26:29]
	v_mfma_f32_16x16x32_bf16 v[22:25], v[168:171], v[210:213], v[22:25]
	v_mfma_f32_16x16x32_bf16 v[18:21], v[176:179], v[210:213], v[18:21]
	v_mfma_f32_16x16x32_bf16 v[14:17], v[168:171], v[218:221], v[14:17]
	v_mfma_f32_16x16x32_bf16 v[10:13], v[176:179], v[218:221], v[10:13]
	v_mfma_f32_16x16x32_bf16 v[6:9], v[168:171], v[240:243], v[6:9]
	v_mfma_f32_16x16x32_bf16 v[2:5], v[176:179], v[240:243], v[2:5]
	v_mfma_f32_16x16x32_bf16 v[30:33], v[172:175], v[206:209], v[30:33]
	v_mfma_f32_16x16x32_bf16 v[26:29], v[180:183], v[206:209], v[26:29]
	v_mfma_f32_16x16x32_bf16 v[22:25], v[172:175], v[214:217], v[22:25]
	v_mfma_f32_16x16x32_bf16 v[18:21], v[180:183], v[214:217], v[18:21]
	v_mfma_f32_16x16x32_bf16 v[14:17], v[172:175], v[236:239], v[14:17]
	v_mfma_f32_16x16x32_bf16 v[10:13], v[180:183], v[236:239], v[10:13]
	v_mfma_f32_16x16x32_bf16 v[6:9], v[172:175], v[244:247], v[6:9]
	v_mfma_f32_16x16x32_bf16 v[2:5], v[180:183], v[244:247], v[2:5]
	s_barrier
; #define PG8_STAGE(bufoff, gbase, voff) do { _Pragma("unroll") for (int _i = 0; _i < 2; ++_i) \
;         __builtin_amdgcn_global_load_lds((const unsigned*)((const char*)(gbase) + (voff)[_i]), (PG8_LAS unsigned*)(lds + (bufoff) + ldsw + _i * 8192), 16, 0, 0); } while (0)
; #define PG8_LDA(dst, b, h) do { _Pragma("unroll") for (int m = 0; m < 4; ++m) _Pragma("unroll") for (int k = 0; k < 2; ++k) dst[m][k] = *(const PG8_LAS bf16x8*)(lds + PG8_SA(b, h) + aoff + m * 2048 + k * 1024); } while (0)
; #define PG8_LDB(dst, b, h) do { _Pragma("unroll") for (int n = 0; n < 2; ++n) _Pragma("unroll") for (int k = 0; k < 2; ++k) dst[n][k] = *(const PG8_LAS bf16x8*)(lds + PG8_SB(b, h) + boff + n * 2048 + k * 1024); } while (0)
; #define PG8_MMA(ai, bj, At, Bt) do { __builtin_amdgcn_s_setprio(1); _Pragma("unroll") for (int m = 0; m < 4; ++m) _Pragma("unroll") for (int n = 0; n < 2; ++n) _Pragma("unroll") for (int k = 0; k < 2; ++k) \
;         acc[ai][bj][m][n] = __builtin_amdgcn_mfma_f32_16x16x32_bf16(Bt[n][k], At[m][k], acc[ai][bj][m][n], 0, 0, 0); __builtin_amdgcn_s_setprio(0); } while (0)
; #define PG8_WAIT_V(n) asm volatile("s_waitcnt vmcnt(" #n ")" ::: "memory")
; #define PG8_WAIT_L(n) asm volatile("s_waitcnt lgkmcnt(" #n ")" ::: "memory")
; #define PG8_BAR __builtin_amdgcn_s_barrier()
; #define PG8_SCHED __builtin_amdgcn_sched_barrier(0)
; template <class Epi, class Sched, bool ALIGN_EPI = false, bool SP2 = false>
; __device__ __forceinline__ void gemm_phase(PG8_LAS unsigned char* lds, const Gemm g, const Sched& S, const Epi& E) {
;     ...
;             PG8_LDB(B0, 1, 0); PG8_LDB(B1, 1, 1); PG8_SCHED; PG8_LDA(At, 1, 0); PG8_STAGE(PG8_SA(0, 1), a2 + hstep, voffA);
;             PG8_WAIT_V(8); PG8_WAIT_L(0); PG8_BAR; PG8_MMA(0, 0, At, B0); PG8_MMA(0, 1, At, B1); PG8_BAR; PG8_SCHED;
;             PG8_LDA(At, 1, 1); PG8_STAGE(PG8_SB(1, 0), b3, voffB); PG8_STAGE(PG8_SB(1, 1), b3 + hstepB, voffB); PG8_STAGE(PG8_SA(1, 0), a3, voffA);
;             PG8_WAIT_V(8); PG8_WAIT_L(0); PG8_BAR; PG8_MMA(1, 0, At, B0); PG8_MMA(1, 1, At, B1); PG8_BAR; PG8_SCHED;
	s_add_i32 s9, 0, 0x18000
	s_add_i32 s12, 0, 0x1c000
	ds_read_b128 v[152:155], v198
	ds_read_b128 v[156:159], v198 offset:1024
	ds_read_b128 v[160:163], v198 offset:2048
	ds_read_b128 v[164:167], v198 offset:3072
	ds_read_b128 v[168:171], v199
	ds_read_b128 v[172:175], v199 offset:1024
	ds_read_b128 v[176:179], v199 offset:2048
	ds_read_b128 v[180:183], v199 offset:3072
	s_add_u32 s10, s92, 0x80000
	s_addc_u32 s11, s93, 0
	s_mov_b32 m0, s74
	ds_read_b128 v[194:197], v151 offset:32768
	ds_read_b128 v[206:209], v151 offset:33792
	ds_read_b128 v[210:213], v151 offset:34816
	ds_read_b128 v[214:217], v151 offset:35840
	ds_read_b128 v[218:221], v151 offset:36864
	ds_read_b128 v[236:239], v151 offset:37888
	ds_read_b128 v[240:243], v151 offset:38912
	ds_read_b128 v[244:247], v151 offset:39936
	global_load_lds_dwordx4 v190, s[10:11]
	s_mov_b32 m0, s75
	s_nop 0
	global_load_lds_dwordx4 v132, s[10:11]
	s_waitcnt vmcnt(8)
	s_waitcnt lgkmcnt(0)
	s_barrier
	v_mfma_f32_16x16x32_bf16 v[126:129], v[152:155], v[194:197], v[126:129]
	v_mfma_f32_16x16x32_bf16 v[122:125], v[160:163], v[194:197], v[122:125]
	v_mfma_f32_16x16x32_bf16 v[118:121], v[152:155], v[210:213], v[118:121]
	v_mfma_f32_16x16x32_bf16 v[114:117], v[160:163], v[210:213], v[114:117]
	v_mfma_f32_16x16x32_bf16 v[110:113], v[152:155], v[218:221], v[110:113]
	v_mfma_f32_16x16x32_bf16 v[106:109], v[160:163], v[218:221], v[106:109]
	v_mfma_f32_16x16x32_bf16 v[102:105], v[152:155], v[240:243], v[102:105]
	v_mfma_f32_16x16x32_bf16 v[98:101], v[160:163], v[240:243], v[98:101]
	v_mfma_f32_16x16x32_bf16 v[126:129], v[156:159], v[206:209], v[126:129]
	v_mfma_f32_16x16x32_bf16 v[122:125], v[164:167], v[206:209], v[122:125]
	v_mfma_f32_16x16x32_bf16 v[118:121], v[156:159], v[214:217], v[118:121]
	v_mfma_f32_16x16x32_bf16 v[114:117], v[164:167], v[214:217], v[114:117]
	v_mfma_f32_16x16x32_bf16 v[110:113], v[156:159], v[236:239], v[110:113]
	v_mfma_f32_16x16x32_bf16 v[106:109], v[164:167], v[236:239], v[106:109]
	v_mfma_f32_16x16x32_bf16 v[102:105], v[156:159], v[244:247], v[102:105]
	v_mfma_f32_16x16x32_bf16 v[98:101], v[164:167], v[244:247], v[98:101]
	v_mfma_f32_16x16x32_bf16 v[94:97], v[168:171], v[194:197], v[94:97]
	v_mfma_f32_16x16x32_bf16 v[90:93], v[176:179], v[194:197], v[90:93]
	v_mfma_f32_16x16x32_bf16 v[86:89], v[168:171], v[210:213], v[86:89]
	v_mfma_f32_16x16x32_bf16 v[82:85], v[176:179], v[210:213], v[82:85]
	v_mfma_f32_16x16x32_bf16 v[78:81], v[168:171], v[218:221], v[78:81]
	v_mfma_f32_16x16x32_bf16 v[74:77], v[176:179], v[218:221], v[74:77]
	v_mfma_f32_16x16x32_bf16 v[70:73], v[168:171], v[240:243], v[70:73]
	v_mfma_f32_16x16x32_bf16 v[66:69], v[176:179], v[240:243], v[66:69]
	v_mfma_f32_16x16x32_bf16 v[94:97], v[172:175], v[206:209], v[94:97]
	v_mfma_f32_16x16x32_bf16 v[90:93], v[180:183], v[206:209], v[90:93]
	v_mfma_f32_16x16x32_bf16 v[86:89], v[172:175], v[214:217], v[86:89]
	v_mfma_f32_16x16x32_bf16 v[82:85], v[180:183], v[214:217], v[82:85]
	v_mfma_f32_16x16x32_bf16 v[78:81], v[172:175], v[236:239], v[78:81]
	v_mfma_f32_16x16x32_bf16 v[74:77], v[180:183], v[236:239], v[74:77]
	v_mfma_f32_16x16x32_bf16 v[70:73], v[172:175], v[244:247], v[70:73]
	v_mfma_f32_16x16x32_bf16 v[66:69], v[180:183], v[244:247], v[66:69]
	s_barrier
	s_add_i32 s9, s9, s42
	s_mov_b32 m0, s9
	ds_read_b128 v[194:197], v151 offset:49152
	ds_read_b128 v[206:209], v151 offset:50176
	ds_read_b128 v[210:213], v151 offset:51200
	ds_read_b128 v[214:217], v151 offset:52224
	ds_read_b128 v[218:221], v151 offset:53248
	ds_read_b128 v[236:239], v151 offset:54272
	ds_read_b128 v[240:243], v151 offset:55296
	ds_read_b128 v[244:247], v151 offset:56320
	s_add_u32 s100, s84, s60
	s_addc_u32 s101, s85, s61
	global_load_lds_dwordx4 v130, s[100:101]
	s_add_i32 m0, s9, 0x2000
	s_add_u32 s10, s84, 0x20080
	s_addc_u32 s11, s85, 0
	s_add_i32 s9, s12, s42
	global_load_lds_dwordx4 v134, s[100:101]
	s_mov_b32 m0, s9
	s_nop 0
	global_load_lds_dwordx4 v130, s[10:11]
	s_add_i32 m0, s9, 0x2000
	s_nop 0
	global_load_lds_dwordx4 v134, s[10:11]
	s_mov_b32 m0, s82
	s_add_u32 s100, s92, s60
	s_addc_u32 s101, s93, s61
	global_load_lds_dwordx4 v190, s[100:101]
	s_mov_b32 m0, s86
	s_nop 0
	global_load_lds_dwordx4 v132, s[100:101]
	s_waitcnt vmcnt(8)
	s_waitcnt lgkmcnt(0)
	s_barrier
	v_mfma_f32_16x16x32_bf16 v[62:65], v[152:155], v[194:197], v[62:65]
	v_mfma_f32_16x16x32_bf16 v[58:61], v[160:163], v[194:197], v[58:61]
	v_mfma_f32_16x16x32_bf16 v[54:57], v[152:155], v[210:213], v[54:57]
	v_mfma_f32_16x16x32_bf16 v[50:53], v[160:163], v[210:213], v[50:53]
	v_mfma_f32_16x16x32_bf16 v[46:49], v[152:155], v[218:221], v[46:49]
	v_mfma_f32_16x16x32_bf16 v[42:45], v[160:163], v[218:221], v[42:45]
	v_mfma_f32_16x16x32_bf16 v[38:41], v[152:155], v[240:243], v[38:41]
	v_mfma_f32_16x16x32_bf16 v[34:37], v[160:163], v[240:243], v[34:37]
	v_mfma_f32_16x16x32_bf16 v[62:65], v[156:159], v[206:209], v[62:65]
	v_mfma_f32_16x16x32_bf16 v[58:61], v[164:167], v[206:209], v[58:61]
	v_mfma_f32_16x16x32_bf16 v[54:57], v[156:159], v[214:217], v[54:57]
	v_mfma_f32_16x16x32_bf16 v[50:53], v[164:167], v[214:217], v[50:53]
	v_mfma_f32_16x16x32_bf16 v[46:49], v[156:159], v[236:239], v[46:49]
	v_mfma_f32_16x16x32_bf16 v[42:45], v[164:167], v[236:239], v[42:45]
	v_mfma_f32_16x16x32_bf16 v[38:41], v[156:159], v[244:247], v[38:41]
	v_mfma_f32_16x16x32_bf16 v[34:37], v[164:167], v[244:247], v[34:37]
	v_mfma_f32_16x16x32_bf16 v[30:33], v[168:171], v[194:197], v[30:33]
	v_mfma_f32_16x16x32_bf16 v[26:29], v[176:179], v[194:197], v[26:29]
	v_mfma_f32_16x16x32_bf16 v[22:25], v[168:171], v[210:213], v[22:25]
	v_mfma_f32_16x16x32_bf16 v[18:21], v[176:179], v[210:213], v[18:21]
	v_mfma_f32_16x16x32_bf16 v[14:17], v[168:171], v[218:221], v[14:17]
	v_mfma_f32_16x16x32_bf16 v[10:13], v[176:179], v[218:221], v[10:13]
	v_mfma_f32_16x16x32_bf16 v[6:9], v[168:171], v[240:243], v[6:9]
	v_mfma_f32_16x16x32_bf16 v[2:5], v[176:179], v[240:243], v[2:5]
	v_mfma_f32_16x16x32_bf16 v[30:33], v[172:175], v[206:209], v[30:33]
	v_mfma_f32_16x16x32_bf16 v[26:29], v[180:183], v[206:209], v[26:29]
	v_mfma_f32_16x16x32_bf16 v[22:25], v[172:175], v[214:217], v[22:25]
	v_mfma_f32_16x16x32_bf16 v[18:21], v[180:183], v[214:217], v[18:21]
	v_mfma_f32_16x16x32_bf16 v[14:17], v[172:175], v[236:239], v[14:17]
	v_mfma_f32_16x16x32_bf16 v[10:13], v[180:183], v[236:239], v[10:13]
	v_mfma_f32_16x16x32_bf16 v[6:9], v[172:175], v[244:247], v[6:9]
	v_mfma_f32_16x16x32_bf16 v[2:5], v[180:183], v[244:247], v[2:5]
	s_barrier
	s_add_i32 s8, s8, 2
	s_add_u32 s80, s80, 0x100
	s_addc_u32 s81, s81, 0
	s_cmp_gt_u32 s8, 29
	s_cbranch_scc0 .LBB0_1233
	s_and_b64 vcc, exec, s[62:63]
	s_cbranch_vccz .LBB0_1236
	s_barrier
